# GEMM K-loops: removed per-segment s_setprio flips and redundant post-barrier lgkmcnt waits (on top of peeled C=0 first iteration, saddr LDS-DMA, GQA loop rewrite)
# speedup vs baseline: 1.0195x; 1.0079x over previous
.LBB0_212:
	s_ashr_i32 s11, s10, 31
	s_lshl_b64 s[12:13], s[10:11], 19
	v_readlane_b32 s14, v252, 27
	v_readlane_b32 s15, v252, 28
	s_add_u32 s28, s14, s12
	s_addc_u32 s29, s15, s13
	s_and_b64 s[12:13], s[42:43], exec
	s_cselect_b32 s3, s29, s17
	s_cselect_b32 s11, s28, s16
	s_ashr_i32 s9, s8, 31
	s_lshl_b64 s[12:13], s[8:9], 19
	s_add_u32 s36, s20, s12
	s_addc_u32 s37, s22, s13
	s_and_b64 s[12:13], s[42:43], exec
	s_cselect_b32 s9, s37, s41
	s_cselect_b32 s12, s36, s40
	s_add_u32 s16, s16, 0x40080
	s_addc_u32 s17, s17, 0
	s_add_u32 s13, s40, 0x100
	s_addc_u32 s14, s41, 0
	s_mov_b32 s15, -2
	s_add_u32 s18, s16, 0xfffc0080
	s_addc_u32 s19, s17, -1
	s_add_i32 s21, 0, 0x10000
	s_cmp_eq_u32 s15, 12
	s_cselect_b32 s45, s3, s19
	s_cselect_b32 s44, s11, s18
	v_add_u32_e32 v152, s21, v155
	s_cselect_b32 s41, s9, s14
	s_cselect_b32 s40, s12, s13
	s_add_i32 s24, 0, 0x14000
	ds_read_b128 v[182:185], v152
	ds_read_b128 v[186:189], v152 offset:1024
	ds_read_b128 v[190:193], v152 offset:2048
	ds_read_b128 v[194:197], v152 offset:3072
	v_add_u32_e32 v152, s24, v155
	ds_read_b128 v[198:201], v152
	ds_read_b128 v[202:205], v152 offset:1024
	ds_read_b128 v[206:209], v152 offset:2048
	ds_read_b128 v[210:213], v152 offset:3072
	s_add_i32 m0, s26, 0xc000
	ds_read_b128 v[214:217], v157
	ds_read_b128 v[218:221], v157 offset:1024
	ds_read_b128 v[222:225], v157 offset:2048
	ds_read_b128 v[226:229], v157 offset:3072
	ds_read_b128 v[230:233], v157 offset:4096
	ds_read_b128 v[234:237], v157 offset:5120
	ds_read_b128 v[238:241], v157 offset:6144
	ds_read_b128 v[242:245], v157 offset:7168
	global_load_lds_dwordx4 v148, s[16:17]
	s_add_i32 m0, s26, 0xe000
	s_nop 0
	global_load_lds_dwordx4 v150, s[16:17]
	s_waitcnt vmcnt(8)
	s_waitcnt lgkmcnt(0)
	s_barrier
	v_mfma_f32_16x16x32_bf16 v[124:127], v[182:185], v[214:217], 0
	v_mfma_f32_16x16x32_bf16 v[120:123], v[190:193], v[214:217], 0
	v_mfma_f32_16x16x32_bf16 v[108:111], v[182:185], v[222:225], 0
	v_mfma_f32_16x16x32_bf16 v[104:107], v[190:193], v[222:225], 0
	v_mfma_f32_16x16x32_bf16 v[92:95], v[182:185], v[230:233], 0
	v_mfma_f32_16x16x32_bf16 v[88:91], v[190:193], v[230:233], 0
	v_mfma_f32_16x16x32_bf16 v[76:79], v[182:185], v[238:241], 0
	v_mfma_f32_16x16x32_bf16 v[72:75], v[190:193], v[238:241], 0
	v_mfma_f32_16x16x32_bf16 v[124:127], v[186:189], v[218:221], v[124:127]
	v_mfma_f32_16x16x32_bf16 v[120:123], v[194:197], v[218:221], v[120:123]
	v_mfma_f32_16x16x32_bf16 v[108:111], v[186:189], v[226:229], v[108:111]
	v_mfma_f32_16x16x32_bf16 v[104:107], v[194:197], v[226:229], v[104:107]
	v_mfma_f32_16x16x32_bf16 v[92:95], v[186:189], v[234:237], v[92:95]
	v_mfma_f32_16x16x32_bf16 v[88:91], v[194:197], v[234:237], v[88:91]
	v_mfma_f32_16x16x32_bf16 v[76:79], v[186:189], v[242:245], v[76:79]
	v_mfma_f32_16x16x32_bf16 v[72:75], v[194:197], v[242:245], v[72:75]
	v_mfma_f32_16x16x32_bf16 v[116:119], v[198:201], v[214:217], 0
	v_mfma_f32_16x16x32_bf16 v[112:115], v[206:209], v[214:217], 0
	v_mfma_f32_16x16x32_bf16 v[100:103], v[198:201], v[222:225], 0
	v_mfma_f32_16x16x32_bf16 v[96:99], v[206:209], v[222:225], 0
	v_mfma_f32_16x16x32_bf16 v[84:87], v[198:201], v[230:233], 0
	v_mfma_f32_16x16x32_bf16 v[80:83], v[206:209], v[230:233], 0
	v_mfma_f32_16x16x32_bf16 v[68:71], v[198:201], v[238:241], 0
	v_mfma_f32_16x16x32_bf16 v[64:67], v[206:209], v[238:241], 0
	v_mfma_f32_16x16x32_bf16 v[116:119], v[202:205], v[218:221], v[116:119]
	v_mfma_f32_16x16x32_bf16 v[112:115], v[210:213], v[218:221], v[112:115]
	v_mfma_f32_16x16x32_bf16 v[100:103], v[202:205], v[226:229], v[100:103]
	v_mfma_f32_16x16x32_bf16 v[96:99], v[210:213], v[226:229], v[96:99]
	v_mfma_f32_16x16x32_bf16 v[84:87], v[202:205], v[234:237], v[84:87]
	v_mfma_f32_16x16x32_bf16 v[80:83], v[210:213], v[234:237], v[80:83]
	v_mfma_f32_16x16x32_bf16 v[68:71], v[202:205], v[242:245], v[68:71]
	v_mfma_f32_16x16x32_bf16 v[64:67], v[210:213], v[242:245], v[64:67]
	s_barrier
	s_add_u32 s60, s40, 0x80
	s_addc_u32 s61, s41, 0
	s_add_u32 s62, s44, 0x80
	s_addc_u32 s63, s45, 0
	s_add_i32 s18, s21, s23
	s_mov_b32 m0, s18
	ds_read_b128 v[214:217], v157 offset:16384
	ds_read_b128 v[218:221], v157 offset:17408
	ds_read_b128 v[222:225], v157 offset:18432
	ds_read_b128 v[226:229], v157 offset:19456
	ds_read_b128 v[230:233], v157 offset:20480
	ds_read_b128 v[234:237], v157 offset:21504
	ds_read_b128 v[238:241], v157 offset:22528
	ds_read_b128 v[242:245], v157 offset:23552
	global_load_lds_dwordx4 v130, s[40:41]
	s_add_i32 m0, s18, 0x2000
	s_add_u32 s18, s40, 0x40000
	s_addc_u32 s19, s41, 0
	s_add_i32 s21, s24, s23
	global_load_lds_dwordx4 v142, s[40:41]
	s_mov_b32 m0, s21
	s_nop 0
	global_load_lds_dwordx4 v130, s[18:19]
	s_add_i32 m0, s21, 0x2000
	s_nop 0
	global_load_lds_dwordx4 v142, s[18:19]
	s_mov_b32 m0, s26
	s_nop 0
	global_load_lds_dwordx4 v146, s[44:45]
	s_mov_b32 m0, s34
	s_nop 0
	global_load_lds_dwordx4 v144, s[44:45]
	s_waitcnt vmcnt(8)
	s_waitcnt lgkmcnt(0)
	s_barrier
	v_mfma_f32_16x16x32_bf16 v[60:63], v[182:185], v[214:217], 0
	v_mfma_f32_16x16x32_bf16 v[56:59], v[190:193], v[214:217], 0
	v_mfma_f32_16x16x32_bf16 v[44:47], v[182:185], v[222:225], 0
	v_mfma_f32_16x16x32_bf16 v[40:43], v[190:193], v[222:225], 0
	v_mfma_f32_16x16x32_bf16 v[28:31], v[182:185], v[230:233], 0
	v_mfma_f32_16x16x32_bf16 v[24:27], v[190:193], v[230:233], 0
	v_mfma_f32_16x16x32_bf16 v[12:15], v[182:185], v[238:241], 0
	v_mfma_f32_16x16x32_bf16 v[8:11], v[190:193], v[238:241], 0
	v_mfma_f32_16x16x32_bf16 v[60:63], v[186:189], v[218:221], v[60:63]
	v_mfma_f32_16x16x32_bf16 v[56:59], v[194:197], v[218:221], v[56:59]
	v_mfma_f32_16x16x32_bf16 v[44:47], v[186:189], v[226:229], v[44:47]
	v_mfma_f32_16x16x32_bf16 v[40:43], v[194:197], v[226:229], v[40:43]
	v_mfma_f32_16x16x32_bf16 v[28:31], v[186:189], v[234:237], v[28:31]
	v_mfma_f32_16x16x32_bf16 v[24:27], v[194:197], v[234:237], v[24:27]
	v_mfma_f32_16x16x32_bf16 v[12:15], v[186:189], v[242:245], v[12:15]
	v_mfma_f32_16x16x32_bf16 v[8:11], v[194:197], v[242:245], v[8:11]
	v_mfma_f32_16x16x32_bf16 v[52:55], v[198:201], v[214:217], 0
	v_mfma_f32_16x16x32_bf16 v[48:51], v[206:209], v[214:217], 0
	v_mfma_f32_16x16x32_bf16 v[36:39], v[198:201], v[222:225], 0
	v_mfma_f32_16x16x32_bf16 v[32:35], v[206:209], v[222:225], 0
	v_mfma_f32_16x16x32_bf16 v[20:23], v[198:201], v[230:233], 0
	v_mfma_f32_16x16x32_bf16 v[16:19], v[206:209], v[230:233], 0
	v_mfma_f32_16x16x32_bf16 v[4:7], v[198:201], v[238:241], 0
	v_mfma_f32_16x16x32_bf16 v[0:3], v[206:209], v[238:241], 0
	v_mfma_f32_16x16x32_bf16 v[52:55], v[202:205], v[218:221], v[52:55]
	v_mfma_f32_16x16x32_bf16 v[48:51], v[210:213], v[218:221], v[48:51]
	v_mfma_f32_16x16x32_bf16 v[36:39], v[202:205], v[226:229], v[36:39]
	v_mfma_f32_16x16x32_bf16 v[32:35], v[210:213], v[226:229], v[32:35]
	v_mfma_f32_16x16x32_bf16 v[20:23], v[202:205], v[234:237], v[20:23]
	v_mfma_f32_16x16x32_bf16 v[16:19], v[210:213], v[234:237], v[16:19]
	v_mfma_f32_16x16x32_bf16 v[4:7], v[202:205], v[242:245], v[4:7]
	v_mfma_f32_16x16x32_bf16 v[0:3], v[210:213], v[242:245], v[0:3]
	s_barrier
	s_add_i32 s21, 0, 0x18000
	v_add_u32_e32 v178, s21, v155
	s_add_i32 s24, 0, 0x1c000
	ds_read_b128 v[182:185], v178
	ds_read_b128 v[186:189], v178 offset:1024
	ds_read_b128 v[190:193], v178 offset:2048
	ds_read_b128 v[194:197], v178 offset:3072
	v_add_u32_e32 v178, s24, v155
	ds_read_b128 v[198:201], v178
	ds_read_b128 v[202:205], v178 offset:1024
	ds_read_b128 v[206:209], v178 offset:2048
	ds_read_b128 v[210:213], v178 offset:3072
	s_add_u32 s18, s44, 0x40000
	s_addc_u32 s19, s45, 0
	s_mov_b32 m0, s35
	ds_read_b128 v[214:217], v157 offset:32768
	ds_read_b128 v[218:221], v157 offset:33792
	ds_read_b128 v[222:225], v157 offset:34816
	ds_read_b128 v[226:229], v157 offset:35840
	ds_read_b128 v[230:233], v157 offset:36864
	ds_read_b128 v[234:237], v157 offset:37888
	ds_read_b128 v[238:241], v157 offset:38912
	ds_read_b128 v[242:245], v157 offset:39936
	global_load_lds_dwordx4 v146, s[18:19]
	s_mov_b32 m0, s46
	s_nop 0
	global_load_lds_dwordx4 v144, s[18:19]
	s_waitcnt vmcnt(8)
	s_waitcnt lgkmcnt(0)
	s_barrier
	v_mfma_f32_16x16x32_bf16 v[124:127], v[182:185], v[214:217], v[124:127]
	v_mfma_f32_16x16x32_bf16 v[120:123], v[190:193], v[214:217], v[120:123]
	v_mfma_f32_16x16x32_bf16 v[108:111], v[182:185], v[222:225], v[108:111]
	v_mfma_f32_16x16x32_bf16 v[104:107], v[190:193], v[222:225], v[104:107]
	v_mfma_f32_16x16x32_bf16 v[92:95], v[182:185], v[230:233], v[92:95]
	v_mfma_f32_16x16x32_bf16 v[88:91], v[190:193], v[230:233], v[88:91]
	v_mfma_f32_16x16x32_bf16 v[76:79], v[182:185], v[238:241], v[76:79]
	v_mfma_f32_16x16x32_bf16 v[72:75], v[190:193], v[238:241], v[72:75]
	v_mfma_f32_16x16x32_bf16 v[124:127], v[186:189], v[218:221], v[124:127]
	v_mfma_f32_16x16x32_bf16 v[120:123], v[194:197], v[218:221], v[120:123]
	v_mfma_f32_16x16x32_bf16 v[108:111], v[186:189], v[226:229], v[108:111]
	v_mfma_f32_16x16x32_bf16 v[104:107], v[194:197], v[226:229], v[104:107]
	v_mfma_f32_16x16x32_bf16 v[92:95], v[186:189], v[234:237], v[92:95]
	v_mfma_f32_16x16x32_bf16 v[88:91], v[194:197], v[234:237], v[88:91]
	v_mfma_f32_16x16x32_bf16 v[76:79], v[186:189], v[242:245], v[76:79]
	v_mfma_f32_16x16x32_bf16 v[72:75], v[194:197], v[242:245], v[72:75]
	v_mfma_f32_16x16x32_bf16 v[116:119], v[198:201], v[214:217], v[116:119]
	v_mfma_f32_16x16x32_bf16 v[112:115], v[206:209], v[214:217], v[112:115]
	v_mfma_f32_16x16x32_bf16 v[100:103], v[198:201], v[222:225], v[100:103]
	v_mfma_f32_16x16x32_bf16 v[96:99], v[206:209], v[222:225], v[96:99]
	v_mfma_f32_16x16x32_bf16 v[84:87], v[198:201], v[230:233], v[84:87]
	v_mfma_f32_16x16x32_bf16 v[80:83], v[206:209], v[230:233], v[80:83]
	v_mfma_f32_16x16x32_bf16 v[68:71], v[198:201], v[238:241], v[68:71]
	v_mfma_f32_16x16x32_bf16 v[64:67], v[206:209], v[238:241], v[64:67]
	v_mfma_f32_16x16x32_bf16 v[116:119], v[202:205], v[218:221], v[116:119]
	v_mfma_f32_16x16x32_bf16 v[112:115], v[210:213], v[218:221], v[112:115]
	v_mfma_f32_16x16x32_bf16 v[100:103], v[202:205], v[226:229], v[100:103]
	v_mfma_f32_16x16x32_bf16 v[96:99], v[210:213], v[226:229], v[96:99]
	v_mfma_f32_16x16x32_bf16 v[84:87], v[202:205], v[234:237], v[84:87]
	v_mfma_f32_16x16x32_bf16 v[80:83], v[210:213], v[234:237], v[80:83]
	v_mfma_f32_16x16x32_bf16 v[68:71], v[202:205], v[242:245], v[68:71]
	v_mfma_f32_16x16x32_bf16 v[64:67], v[210:213], v[242:245], v[64:67]
	s_barrier
	s_add_i32 s18, s21, s23
	s_mov_b32 m0, s18
	ds_read_b128 v[214:217], v157 offset:49152
	ds_read_b128 v[218:221], v157 offset:50176
	ds_read_b128 v[222:225], v157 offset:51200
	ds_read_b128 v[226:229], v157 offset:52224
	ds_read_b128 v[230:233], v157 offset:53248
	ds_read_b128 v[234:237], v157 offset:54272
	ds_read_b128 v[238:241], v157 offset:55296
	ds_read_b128 v[242:245], v157 offset:56320
	global_load_lds_dwordx4 v130, s[60:61]
	s_add_i32 m0, s18, 0x2000
	s_add_u32 s18, s40, 0x40080
	s_addc_u32 s19, s41, 0
	s_add_i32 s21, s24, s23
	global_load_lds_dwordx4 v142, s[60:61]
	s_mov_b32 m0, s21
	s_nop 0
	global_load_lds_dwordx4 v130, s[18:19]
	s_add_i32 m0, s21, 0x2000
	s_nop 0
	global_load_lds_dwordx4 v142, s[18:19]
	s_mov_b32 m0, s47
	s_nop 0
	global_load_lds_dwordx4 v146, s[62:63]
	s_mov_b32 m0, s48
	s_nop 0
	global_load_lds_dwordx4 v144, s[62:63]
	s_waitcnt vmcnt(8)
	s_waitcnt lgkmcnt(0)
	s_barrier
	v_mfma_f32_16x16x32_bf16 v[60:63], v[182:185], v[214:217], v[60:63]
	v_mfma_f32_16x16x32_bf16 v[56:59], v[190:193], v[214:217], v[56:59]
	v_mfma_f32_16x16x32_bf16 v[44:47], v[182:185], v[222:225], v[44:47]
	v_mfma_f32_16x16x32_bf16 v[40:43], v[190:193], v[222:225], v[40:43]
	v_mfma_f32_16x16x32_bf16 v[28:31], v[182:185], v[230:233], v[28:31]
	v_mfma_f32_16x16x32_bf16 v[24:27], v[190:193], v[230:233], v[24:27]
	v_mfma_f32_16x16x32_bf16 v[12:15], v[182:185], v[238:241], v[12:15]
	v_mfma_f32_16x16x32_bf16 v[8:11], v[190:193], v[238:241], v[8:11]
	v_mfma_f32_16x16x32_bf16 v[60:63], v[186:189], v[218:221], v[60:63]
	v_mfma_f32_16x16x32_bf16 v[56:59], v[194:197], v[218:221], v[56:59]
	v_mfma_f32_16x16x32_bf16 v[44:47], v[186:189], v[226:229], v[44:47]
	v_mfma_f32_16x16x32_bf16 v[40:43], v[194:197], v[226:229], v[40:43]
	v_mfma_f32_16x16x32_bf16 v[28:31], v[186:189], v[234:237], v[28:31]
	v_mfma_f32_16x16x32_bf16 v[24:27], v[194:197], v[234:237], v[24:27]
	v_mfma_f32_16x16x32_bf16 v[12:15], v[186:189], v[242:245], v[12:15]
	v_mfma_f32_16x16x32_bf16 v[8:11], v[194:197], v[242:245], v[8:11]
	v_mfma_f32_16x16x32_bf16 v[52:55], v[198:201], v[214:217], v[52:55]
	v_mfma_f32_16x16x32_bf16 v[48:51], v[206:209], v[214:217], v[48:51]
	v_mfma_f32_16x16x32_bf16 v[36:39], v[198:201], v[222:225], v[36:39]
	v_mfma_f32_16x16x32_bf16 v[32:35], v[206:209], v[222:225], v[32:35]
	v_mfma_f32_16x16x32_bf16 v[20:23], v[198:201], v[230:233], v[20:23]
	v_mfma_f32_16x16x32_bf16 v[16:19], v[206:209], v[230:233], v[16:19]
	v_mfma_f32_16x16x32_bf16 v[4:7], v[198:201], v[238:241], v[4:7]
	v_mfma_f32_16x16x32_bf16 v[0:3], v[206:209], v[238:241], v[0:3]
	v_mfma_f32_16x16x32_bf16 v[52:55], v[202:205], v[218:221], v[52:55]
	v_mfma_f32_16x16x32_bf16 v[48:51], v[210:213], v[218:221], v[48:51]
	v_mfma_f32_16x16x32_bf16 v[36:39], v[202:205], v[226:229], v[36:39]
	v_mfma_f32_16x16x32_bf16 v[32:35], v[210:213], v[226:229], v[32:35]
	v_mfma_f32_16x16x32_bf16 v[20:23], v[202:205], v[234:237], v[20:23]
	v_mfma_f32_16x16x32_bf16 v[16:19], v[210:213], v[234:237], v[16:19]
	v_mfma_f32_16x16x32_bf16 v[4:7], v[202:205], v[242:245], v[4:7]
	v_mfma_f32_16x16x32_bf16 v[0:3], v[210:213], v[242:245], v[0:3]
	s_barrier
	s_add_i32 s15, s15, 2
	s_add_u32 s16, s16, 0x100
	s_addc_u32 s17, s17, 0
	s_add_u32 s13, s13, 0x100
	s_addc_u32 s14, s14, 0
	s_cmp_gt_u32 s15, 13
	s_cbranch_scc1 .Lpeel_done_213
.LBB0_213:
	s_add_u32 s18, s16, 0xfffc0080
	s_addc_u32 s19, s17, -1
	s_add_i32 s21, 0, 0x10000
	s_cmp_eq_u32 s15, 12
	s_cselect_b32 s45, s3, s19
	s_cselect_b32 s44, s11, s18
	v_add_u32_e32 v152, s21, v155
	s_cselect_b32 s41, s9, s14
	s_cselect_b32 s40, s12, s13
	s_add_i32 s24, 0, 0x14000
	ds_read_b128 v[182:185], v152
	ds_read_b128 v[186:189], v152 offset:1024
	ds_read_b128 v[190:193], v152 offset:2048
	ds_read_b128 v[194:197], v152 offset:3072
	v_add_u32_e32 v152, s24, v155
	ds_read_b128 v[198:201], v152
	ds_read_b128 v[202:205], v152 offset:1024
	ds_read_b128 v[206:209], v152 offset:2048
	ds_read_b128 v[210:213], v152 offset:3072
	s_add_i32 m0, s26, 0xc000
	ds_read_b128 v[214:217], v157
	ds_read_b128 v[218:221], v157 offset:1024
	ds_read_b128 v[222:225], v157 offset:2048
	ds_read_b128 v[226:229], v157 offset:3072
	ds_read_b128 v[230:233], v157 offset:4096
	ds_read_b128 v[234:237], v157 offset:5120
	ds_read_b128 v[238:241], v157 offset:6144
	ds_read_b128 v[242:245], v157 offset:7168
	global_load_lds_dwordx4 v148, s[16:17]
	s_add_i32 m0, s26, 0xe000
	s_nop 0
	global_load_lds_dwordx4 v150, s[16:17]
	s_waitcnt vmcnt(8)
	s_waitcnt lgkmcnt(0)
	s_barrier
	v_mfma_f32_16x16x32_bf16 v[124:127], v[182:185], v[214:217], v[124:127]
	v_mfma_f32_16x16x32_bf16 v[120:123], v[190:193], v[214:217], v[120:123]
	v_mfma_f32_16x16x32_bf16 v[108:111], v[182:185], v[222:225], v[108:111]
	v_mfma_f32_16x16x32_bf16 v[104:107], v[190:193], v[222:225], v[104:107]
	v_mfma_f32_16x16x32_bf16 v[92:95], v[182:185], v[230:233], v[92:95]
	v_mfma_f32_16x16x32_bf16 v[88:91], v[190:193], v[230:233], v[88:91]
	v_mfma_f32_16x16x32_bf16 v[76:79], v[182:185], v[238:241], v[76:79]
	v_mfma_f32_16x16x32_bf16 v[72:75], v[190:193], v[238:241], v[72:75]
	v_mfma_f32_16x16x32_bf16 v[124:127], v[186:189], v[218:221], v[124:127]
	v_mfma_f32_16x16x32_bf16 v[120:123], v[194:197], v[218:221], v[120:123]
	v_mfma_f32_16x16x32_bf16 v[108:111], v[186:189], v[226:229], v[108:111]
	v_mfma_f32_16x16x32_bf16 v[104:107], v[194:197], v[226:229], v[104:107]
	v_mfma_f32_16x16x32_bf16 v[92:95], v[186:189], v[234:237], v[92:95]
	v_mfma_f32_16x16x32_bf16 v[88:91], v[194:197], v[234:237], v[88:91]
	v_mfma_f32_16x16x32_bf16 v[76:79], v[186:189], v[242:245], v[76:79]
	v_mfma_f32_16x16x32_bf16 v[72:75], v[194:197], v[242:245], v[72:75]
	v_mfma_f32_16x16x32_bf16 v[116:119], v[198:201], v[214:217], v[116:119]
	v_mfma_f32_16x16x32_bf16 v[112:115], v[206:209], v[214:217], v[112:115]
	v_mfma_f32_16x16x32_bf16 v[100:103], v[198:201], v[222:225], v[100:103]
	v_mfma_f32_16x16x32_bf16 v[96:99], v[206:209], v[222:225], v[96:99]
	v_mfma_f32_16x16x32_bf16 v[84:87], v[198:201], v[230:233], v[84:87]
	v_mfma_f32_16x16x32_bf16 v[80:83], v[206:209], v[230:233], v[80:83]
	v_mfma_f32_16x16x32_bf16 v[68:71], v[198:201], v[238:241], v[68:71]
	v_mfma_f32_16x16x32_bf16 v[64:67], v[206:209], v[238:241], v[64:67]
	v_mfma_f32_16x16x32_bf16 v[116:119], v[202:205], v[218:221], v[116:119]
	v_mfma_f32_16x16x32_bf16 v[112:115], v[210:213], v[218:221], v[112:115]
	v_mfma_f32_16x16x32_bf16 v[100:103], v[202:205], v[226:229], v[100:103]
	v_mfma_f32_16x16x32_bf16 v[96:99], v[210:213], v[226:229], v[96:99]
	v_mfma_f32_16x16x32_bf16 v[84:87], v[202:205], v[234:237], v[84:87]
	v_mfma_f32_16x16x32_bf16 v[80:83], v[210:213], v[234:237], v[80:83]
	v_mfma_f32_16x16x32_bf16 v[68:71], v[202:205], v[242:245], v[68:71]
	v_mfma_f32_16x16x32_bf16 v[64:67], v[210:213], v[242:245], v[64:67]
	s_barrier
	s_add_u32 s60, s40, 0x80
	s_addc_u32 s61, s41, 0
	s_add_u32 s62, s44, 0x80
	s_addc_u32 s63, s45, 0
	s_add_i32 s18, s21, s23
	s_mov_b32 m0, s18
	ds_read_b128 v[214:217], v157 offset:16384
	ds_read_b128 v[218:221], v157 offset:17408
	ds_read_b128 v[222:225], v157 offset:18432
	ds_read_b128 v[226:229], v157 offset:19456
	ds_read_b128 v[230:233], v157 offset:20480
	ds_read_b128 v[234:237], v157 offset:21504
	ds_read_b128 v[238:241], v157 offset:22528
	ds_read_b128 v[242:245], v157 offset:23552
	global_load_lds_dwordx4 v130, s[40:41]
	s_add_i32 m0, s18, 0x2000
	s_add_u32 s18, s40, 0x40000
	s_addc_u32 s19, s41, 0
	s_add_i32 s21, s24, s23
	global_load_lds_dwordx4 v142, s[40:41]
	s_mov_b32 m0, s21
	s_nop 0
	global_load_lds_dwordx4 v130, s[18:19]
	s_add_i32 m0, s21, 0x2000
	s_nop 0
	global_load_lds_dwordx4 v142, s[18:19]
	s_mov_b32 m0, s26
	s_nop 0
	global_load_lds_dwordx4 v146, s[44:45]
	s_mov_b32 m0, s34
	s_nop 0
	global_load_lds_dwordx4 v144, s[44:45]
	s_waitcnt vmcnt(8)
	s_waitcnt lgkmcnt(0)
	s_barrier
	v_mfma_f32_16x16x32_bf16 v[60:63], v[182:185], v[214:217], v[60:63]
	v_mfma_f32_16x16x32_bf16 v[56:59], v[190:193], v[214:217], v[56:59]
	v_mfma_f32_16x16x32_bf16 v[44:47], v[182:185], v[222:225], v[44:47]
	v_mfma_f32_16x16x32_bf16 v[40:43], v[190:193], v[222:225], v[40:43]
	v_mfma_f32_16x16x32_bf16 v[28:31], v[182:185], v[230:233], v[28:31]
	v_mfma_f32_16x16x32_bf16 v[24:27], v[190:193], v[230:233], v[24:27]
	v_mfma_f32_16x16x32_bf16 v[12:15], v[182:185], v[238:241], v[12:15]
	v_mfma_f32_16x16x32_bf16 v[8:11], v[190:193], v[238:241], v[8:11]
	v_mfma_f32_16x16x32_bf16 v[60:63], v[186:189], v[218:221], v[60:63]
	v_mfma_f32_16x16x32_bf16 v[56:59], v[194:197], v[218:221], v[56:59]
	v_mfma_f32_16x16x32_bf16 v[44:47], v[186:189], v[226:229], v[44:47]
	v_mfma_f32_16x16x32_bf16 v[40:43], v[194:197], v[226:229], v[40:43]
	v_mfma_f32_16x16x32_bf16 v[28:31], v[186:189], v[234:237], v[28:31]
	v_mfma_f32_16x16x32_bf16 v[24:27], v[194:197], v[234:237], v[24:27]
	v_mfma_f32_16x16x32_bf16 v[12:15], v[186:189], v[242:245], v[12:15]
	v_mfma_f32_16x16x32_bf16 v[8:11], v[194:197], v[242:245], v[8:11]
	v_mfma_f32_16x16x32_bf16 v[52:55], v[198:201], v[214:217], v[52:55]
	v_mfma_f32_16x16x32_bf16 v[48:51], v[206:209], v[214:217], v[48:51]
	v_mfma_f32_16x16x32_bf16 v[36:39], v[198:201], v[222:225], v[36:39]
	v_mfma_f32_16x16x32_bf16 v[32:35], v[206:209], v[222:225], v[32:35]
	v_mfma_f32_16x16x32_bf16 v[20:23], v[198:201], v[230:233], v[20:23]
	v_mfma_f32_16x16x32_bf16 v[16:19], v[206:209], v[230:233], v[16:19]
	v_mfma_f32_16x16x32_bf16 v[4:7], v[198:201], v[238:241], v[4:7]
	v_mfma_f32_16x16x32_bf16 v[0:3], v[206:209], v[238:241], v[0:3]
	v_mfma_f32_16x16x32_bf16 v[52:55], v[202:205], v[218:221], v[52:55]
	v_mfma_f32_16x16x32_bf16 v[48:51], v[210:213], v[218:221], v[48:51]
	v_mfma_f32_16x16x32_bf16 v[36:39], v[202:205], v[226:229], v[36:39]
	v_mfma_f32_16x16x32_bf16 v[32:35], v[210:213], v[226:229], v[32:35]
	v_mfma_f32_16x16x32_bf16 v[20:23], v[202:205], v[234:237], v[20:23]
	v_mfma_f32_16x16x32_bf16 v[16:19], v[210:213], v[234:237], v[16:19]
	v_mfma_f32_16x16x32_bf16 v[4:7], v[202:205], v[242:245], v[4:7]
	v_mfma_f32_16x16x32_bf16 v[0:3], v[210:213], v[242:245], v[0:3]
	s_barrier
	s_add_i32 s21, 0, 0x18000
	v_add_u32_e32 v178, s21, v155
	s_add_i32 s24, 0, 0x1c000
	ds_read_b128 v[182:185], v178
	ds_read_b128 v[186:189], v178 offset:1024
	ds_read_b128 v[190:193], v178 offset:2048
	ds_read_b128 v[194:197], v178 offset:3072
	v_add_u32_e32 v178, s24, v155
	ds_read_b128 v[198:201], v178
	ds_read_b128 v[202:205], v178 offset:1024
	ds_read_b128 v[206:209], v178 offset:2048
	ds_read_b128 v[210:213], v178 offset:3072
	s_add_u32 s18, s44, 0x40000
	s_addc_u32 s19, s45, 0
	s_mov_b32 m0, s35
	ds_read_b128 v[214:217], v157 offset:32768
	ds_read_b128 v[218:221], v157 offset:33792
	ds_read_b128 v[222:225], v157 offset:34816
	ds_read_b128 v[226:229], v157 offset:35840
	ds_read_b128 v[230:233], v157 offset:36864
	ds_read_b128 v[234:237], v157 offset:37888
	ds_read_b128 v[238:241], v157 offset:38912
	ds_read_b128 v[242:245], v157 offset:39936
	global_load_lds_dwordx4 v146, s[18:19]
	s_mov_b32 m0, s46
	s_nop 0
	global_load_lds_dwordx4 v144, s[18:19]
	s_waitcnt vmcnt(8)
	s_waitcnt lgkmcnt(0)
	s_barrier
	v_mfma_f32_16x16x32_bf16 v[124:127], v[182:185], v[214:217], v[124:127]
	v_mfma_f32_16x16x32_bf16 v[120:123], v[190:193], v[214:217], v[120:123]
	v_mfma_f32_16x16x32_bf16 v[108:111], v[182:185], v[222:225], v[108:111]
	v_mfma_f32_16x16x32_bf16 v[104:107], v[190:193], v[222:225], v[104:107]
	v_mfma_f32_16x16x32_bf16 v[92:95], v[182:185], v[230:233], v[92:95]
	v_mfma_f32_16x16x32_bf16 v[88:91], v[190:193], v[230:233], v[88:91]
	v_mfma_f32_16x16x32_bf16 v[76:79], v[182:185], v[238:241], v[76:79]
	v_mfma_f32_16x16x32_bf16 v[72:75], v[190:193], v[238:241], v[72:75]
	v_mfma_f32_16x16x32_bf16 v[124:127], v[186:189], v[218:221], v[124:127]
	v_mfma_f32_16x16x32_bf16 v[120:123], v[194:197], v[218:221], v[120:123]
	v_mfma_f32_16x16x32_bf16 v[108:111], v[186:189], v[226:229], v[108:111]
	v_mfma_f32_16x16x32_bf16 v[104:107], v[194:197], v[226:229], v[104:107]
	v_mfma_f32_16x16x32_bf16 v[92:95], v[186:189], v[234:237], v[92:95]
	v_mfma_f32_16x16x32_bf16 v[88:91], v[194:197], v[234:237], v[88:91]
	v_mfma_f32_16x16x32_bf16 v[76:79], v[186:189], v[242:245], v[76:79]
	v_mfma_f32_16x16x32_bf16 v[72:75], v[194:197], v[242:245], v[72:75]
	v_mfma_f32_16x16x32_bf16 v[116:119], v[198:201], v[214:217], v[116:119]
	v_mfma_f32_16x16x32_bf16 v[112:115], v[206:209], v[214:217], v[112:115]
	v_mfma_f32_16x16x32_bf16 v[100:103], v[198:201], v[222:225], v[100:103]
	v_mfma_f32_16x16x32_bf16 v[96:99], v[206:209], v[222:225], v[96:99]
	v_mfma_f32_16x16x32_bf16 v[84:87], v[198:201], v[230:233], v[84:87]
	v_mfma_f32_16x16x32_bf16 v[80:83], v[206:209], v[230:233], v[80:83]
	v_mfma_f32_16x16x32_bf16 v[68:71], v[198:201], v[238:241], v[68:71]
	v_mfma_f32_16x16x32_bf16 v[64:67], v[206:209], v[238:241], v[64:67]
	v_mfma_f32_16x16x32_bf16 v[116:119], v[202:205], v[218:221], v[116:119]
	v_mfma_f32_16x16x32_bf16 v[112:115], v[210:213], v[218:221], v[112:115]
	v_mfma_f32_16x16x32_bf16 v[100:103], v[202:205], v[226:229], v[100:103]
	v_mfma_f32_16x16x32_bf16 v[96:99], v[210:213], v[226:229], v[96:99]
	v_mfma_f32_16x16x32_bf16 v[84:87], v[202:205], v[234:237], v[84:87]
	v_mfma_f32_16x16x32_bf16 v[80:83], v[210:213], v[234:237], v[80:83]
	v_mfma_f32_16x16x32_bf16 v[68:71], v[202:205], v[242:245], v[68:71]
	v_mfma_f32_16x16x32_bf16 v[64:67], v[210:213], v[242:245], v[64:67]
	s_barrier
	s_add_i32 s18, s21, s23
	s_mov_b32 m0, s18
	ds_read_b128 v[214:217], v157 offset:49152
	ds_read_b128 v[218:221], v157 offset:50176
	ds_read_b128 v[222:225], v157 offset:51200
	ds_read_b128 v[226:229], v157 offset:52224
	ds_read_b128 v[230:233], v157 offset:53248
	ds_read_b128 v[234:237], v157 offset:54272
	ds_read_b128 v[238:241], v157 offset:55296
	ds_read_b128 v[242:245], v157 offset:56320
	global_load_lds_dwordx4 v130, s[60:61]
	s_add_i32 m0, s18, 0x2000
	s_add_u32 s18, s40, 0x40080
	s_addc_u32 s19, s41, 0
	s_add_i32 s21, s24, s23
	global_load_lds_dwordx4 v142, s[60:61]
	s_mov_b32 m0, s21
	s_nop 0
	global_load_lds_dwordx4 v130, s[18:19]
	s_add_i32 m0, s21, 0x2000
	s_nop 0
	global_load_lds_dwordx4 v142, s[18:19]
	s_mov_b32 m0, s47
	s_nop 0
	global_load_lds_dwordx4 v146, s[62:63]
	s_mov_b32 m0, s48
	s_nop 0
	global_load_lds_dwordx4 v144, s[62:63]
	s_waitcnt vmcnt(8)
	s_waitcnt lgkmcnt(0)
	s_barrier
	v_mfma_f32_16x16x32_bf16 v[60:63], v[182:185], v[214:217], v[60:63]
	v_mfma_f32_16x16x32_bf16 v[56:59], v[190:193], v[214:217], v[56:59]
	v_mfma_f32_16x16x32_bf16 v[44:47], v[182:185], v[222:225], v[44:47]
	v_mfma_f32_16x16x32_bf16 v[40:43], v[190:193], v[222:225], v[40:43]
	v_mfma_f32_16x16x32_bf16 v[28:31], v[182:185], v[230:233], v[28:31]
	v_mfma_f32_16x16x32_bf16 v[24:27], v[190:193], v[230:233], v[24:27]
	v_mfma_f32_16x16x32_bf16 v[12:15], v[182:185], v[238:241], v[12:15]
	v_mfma_f32_16x16x32_bf16 v[8:11], v[190:193], v[238:241], v[8:11]
	v_mfma_f32_16x16x32_bf16 v[60:63], v[186:189], v[218:221], v[60:63]
	v_mfma_f32_16x16x32_bf16 v[56:59], v[194:197], v[218:221], v[56:59]
	v_mfma_f32_16x16x32_bf16 v[44:47], v[186:189], v[226:229], v[44:47]
	v_mfma_f32_16x16x32_bf16 v[40:43], v[194:197], v[226:229], v[40:43]
	v_mfma_f32_16x16x32_bf16 v[28:31], v[186:189], v[234:237], v[28:31]
	v_mfma_f32_16x16x32_bf16 v[24:27], v[194:197], v[234:237], v[24:27]
	v_mfma_f32_16x16x32_bf16 v[12:15], v[186:189], v[242:245], v[12:15]
	v_mfma_f32_16x16x32_bf16 v[8:11], v[194:197], v[242:245], v[8:11]
	v_mfma_f32_16x16x32_bf16 v[52:55], v[198:201], v[214:217], v[52:55]
	v_mfma_f32_16x16x32_bf16 v[48:51], v[206:209], v[214:217], v[48:51]
	v_mfma_f32_16x16x32_bf16 v[36:39], v[198:201], v[222:225], v[36:39]
	v_mfma_f32_16x16x32_bf16 v[32:35], v[206:209], v[222:225], v[32:35]
	v_mfma_f32_16x16x32_bf16 v[20:23], v[198:201], v[230:233], v[20:23]
	v_mfma_f32_16x16x32_bf16 v[16:19], v[206:209], v[230:233], v[16:19]
	v_mfma_f32_16x16x32_bf16 v[4:7], v[198:201], v[238:241], v[4:7]
	v_mfma_f32_16x16x32_bf16 v[0:3], v[206:209], v[238:241], v[0:3]
	v_mfma_f32_16x16x32_bf16 v[52:55], v[202:205], v[218:221], v[52:55]
	v_mfma_f32_16x16x32_bf16 v[48:51], v[210:213], v[218:221], v[48:51]
	v_mfma_f32_16x16x32_bf16 v[36:39], v[202:205], v[226:229], v[36:39]
	v_mfma_f32_16x16x32_bf16 v[32:35], v[210:213], v[226:229], v[32:35]
	v_mfma_f32_16x16x32_bf16 v[20:23], v[202:205], v[234:237], v[20:23]
	v_mfma_f32_16x16x32_bf16 v[16:19], v[210:213], v[234:237], v[16:19]
	v_mfma_f32_16x16x32_bf16 v[4:7], v[202:205], v[242:245], v[4:7]
	v_mfma_f32_16x16x32_bf16 v[0:3], v[210:213], v[242:245], v[0:3]
	s_barrier
	s_add_i32 s15, s15, 2
	s_add_u32 s16, s16, 0x100
	s_addc_u32 s17, s17, 0
	s_add_u32 s13, s13, 0x100
	s_addc_u32 s14, s14, 0
	s_cmp_gt_u32 s15, 13
	s_cbranch_scc0 .LBB0_213

.LBB0_285:
	s_add_i32 s11, s49, -2
	s_add_u32 s50, s40, 0x100
	s_addc_u32 s51, s41, 0
	s_mov_b32 s42, 0
	s_add_i32 s52, s42, 2
	s_add_u32 s40, s36, 0x100
	s_addc_u32 s41, s37, 0
	s_add_i32 s22, 0, 0x10000
	s_cmp_eq_u32 s11, s42
	s_cselect_b32 s45, s17, s41
	s_cselect_b32 s44, s16, s40
	v_add_u32_e32 v156, s22, v153
	s_cselect_b32 s43, s29, s51
	s_cselect_b32 s42, s28, s50
	s_add_i32 s23, 0, 0x14000
	ds_read_b128 v[182:185], v156
	ds_read_b128 v[186:189], v156 offset:1024
	ds_read_b128 v[190:193], v156 offset:2048
	ds_read_b128 v[194:197], v156 offset:3072
	v_add_u32_e32 v156, s23, v153
	ds_read_b128 v[198:201], v156
	ds_read_b128 v[202:205], v156 offset:1024
	ds_read_b128 v[206:209], v156 offset:2048
	ds_read_b128 v[210:213], v156 offset:3072
	s_add_i32 m0, s13, 0xc000
	ds_read_b128 v[214:217], v155
	ds_read_b128 v[218:221], v155 offset:1024
	ds_read_b128 v[222:225], v155 offset:2048
	ds_read_b128 v[226:229], v155 offset:3072
	ds_read_b128 v[230:233], v155 offset:4096
	ds_read_b128 v[234:237], v155 offset:5120
	ds_read_b128 v[238:241], v155 offset:6144
	ds_read_b128 v[242:245], v155 offset:7168
	global_load_lds_dwordx4 v148, s[36:37]
	s_add_i32 m0, s13, 0xe000
	s_nop 0
	global_load_lds_dwordx4 v150, s[36:37]
	s_waitcnt vmcnt(8)
	s_waitcnt lgkmcnt(0)
	s_barrier
	v_mfma_f32_16x16x32_bf16 v[124:127], v[182:185], v[214:217], 0
	v_mfma_f32_16x16x32_bf16 v[120:123], v[190:193], v[214:217], 0
	v_mfma_f32_16x16x32_bf16 v[116:119], v[182:185], v[222:225], 0
	v_mfma_f32_16x16x32_bf16 v[112:115], v[190:193], v[222:225], 0
	v_mfma_f32_16x16x32_bf16 v[100:103], v[182:185], v[230:233], 0
	v_mfma_f32_16x16x32_bf16 v[96:99], v[190:193], v[230:233], 0
	v_mfma_f32_16x16x32_bf16 v[84:87], v[182:185], v[238:241], 0
	v_mfma_f32_16x16x32_bf16 v[80:83], v[190:193], v[238:241], 0
	v_mfma_f32_16x16x32_bf16 v[124:127], v[186:189], v[218:221], v[124:127]
	v_mfma_f32_16x16x32_bf16 v[120:123], v[194:197], v[218:221], v[120:123]
	v_mfma_f32_16x16x32_bf16 v[116:119], v[186:189], v[226:229], v[116:119]
	v_mfma_f32_16x16x32_bf16 v[112:115], v[194:197], v[226:229], v[112:115]
	v_mfma_f32_16x16x32_bf16 v[100:103], v[186:189], v[234:237], v[100:103]
	v_mfma_f32_16x16x32_bf16 v[96:99], v[194:197], v[234:237], v[96:99]
	v_mfma_f32_16x16x32_bf16 v[84:87], v[186:189], v[242:245], v[84:87]
	v_mfma_f32_16x16x32_bf16 v[80:83], v[194:197], v[242:245], v[80:83]
	v_mfma_f32_16x16x32_bf16 v[108:111], v[198:201], v[214:217], 0
	v_mfma_f32_16x16x32_bf16 v[104:107], v[206:209], v[214:217], 0
	v_mfma_f32_16x16x32_bf16 v[92:95], v[198:201], v[222:225], 0
	v_mfma_f32_16x16x32_bf16 v[88:91], v[206:209], v[222:225], 0
	v_mfma_f32_16x16x32_bf16 v[76:79], v[198:201], v[230:233], 0
	v_mfma_f32_16x16x32_bf16 v[72:75], v[206:209], v[230:233], 0
	v_mfma_f32_16x16x32_bf16 v[68:71], v[198:201], v[238:241], 0
	v_mfma_f32_16x16x32_bf16 v[64:67], v[206:209], v[238:241], 0
	v_mfma_f32_16x16x32_bf16 v[108:111], v[202:205], v[218:221], v[108:111]
	v_mfma_f32_16x16x32_bf16 v[104:107], v[210:213], v[218:221], v[104:107]
	v_mfma_f32_16x16x32_bf16 v[92:95], v[202:205], v[226:229], v[92:95]
	v_mfma_f32_16x16x32_bf16 v[88:91], v[210:213], v[226:229], v[88:91]
	v_mfma_f32_16x16x32_bf16 v[76:79], v[202:205], v[234:237], v[76:79]
	v_mfma_f32_16x16x32_bf16 v[72:75], v[210:213], v[234:237], v[72:75]
	v_mfma_f32_16x16x32_bf16 v[68:71], v[202:205], v[242:245], v[68:71]
	v_mfma_f32_16x16x32_bf16 v[64:67], v[210:213], v[242:245], v[64:67]
	s_barrier
	s_add_u32 s60, s42, 0x80
	s_addc_u32 s61, s43, 0
	s_add_u32 s62, s44, 0x80
	s_addc_u32 s63, s45, 0
	s_add_i32 s21, s22, s12
	s_mov_b32 m0, s21
	ds_read_b128 v[214:217], v155 offset:16384
	ds_read_b128 v[218:221], v155 offset:17408
	ds_read_b128 v[222:225], v155 offset:18432
	ds_read_b128 v[226:229], v155 offset:19456
	ds_read_b128 v[230:233], v155 offset:20480
	ds_read_b128 v[234:237], v155 offset:21504
	ds_read_b128 v[238:241], v155 offset:22528
	ds_read_b128 v[242:245], v155 offset:23552
	global_load_lds_dwordx4 v130, s[42:43]
	s_add_i32 m0, s21, 0x2000
	s_add_u32 s34, s42, 0xb0000
	s_addc_u32 s35, s43, 0
	s_add_i32 s21, s23, s12
	global_load_lds_dwordx4 v146, s[42:43]
	s_mov_b32 m0, s21
	s_nop 0
	global_load_lds_dwordx4 v130, s[34:35]
	s_add_i32 m0, s21, 0x2000
	s_nop 0
	global_load_lds_dwordx4 v146, s[34:35]
	s_mov_b32 m0, s13
	s_nop 0
	global_load_lds_dwordx4 v142, s[44:45]
	s_mov_b32 m0, s19
	s_nop 0
	global_load_lds_dwordx4 v144, s[44:45]
	s_waitcnt vmcnt(8)
	s_waitcnt lgkmcnt(0)
	s_barrier
	v_mfma_f32_16x16x32_bf16 v[60:63], v[182:185], v[214:217], 0
	v_mfma_f32_16x16x32_bf16 v[56:59], v[190:193], v[214:217], 0
	v_mfma_f32_16x16x32_bf16 v[52:55], v[182:185], v[222:225], 0
	v_mfma_f32_16x16x32_bf16 v[48:51], v[190:193], v[222:225], 0
	v_mfma_f32_16x16x32_bf16 v[36:39], v[182:185], v[230:233], 0
	v_mfma_f32_16x16x32_bf16 v[32:35], v[190:193], v[230:233], 0
	v_mfma_f32_16x16x32_bf16 v[20:23], v[182:185], v[238:241], 0
	v_mfma_f32_16x16x32_bf16 v[16:19], v[190:193], v[238:241], 0
	v_mfma_f32_16x16x32_bf16 v[60:63], v[186:189], v[218:221], v[60:63]
	v_mfma_f32_16x16x32_bf16 v[56:59], v[194:197], v[218:221], v[56:59]
	v_mfma_f32_16x16x32_bf16 v[52:55], v[186:189], v[226:229], v[52:55]
	v_mfma_f32_16x16x32_bf16 v[48:51], v[194:197], v[226:229], v[48:51]
	v_mfma_f32_16x16x32_bf16 v[36:39], v[186:189], v[234:237], v[36:39]
	v_mfma_f32_16x16x32_bf16 v[32:35], v[194:197], v[234:237], v[32:35]
	v_mfma_f32_16x16x32_bf16 v[20:23], v[186:189], v[242:245], v[20:23]
	v_mfma_f32_16x16x32_bf16 v[16:19], v[194:197], v[242:245], v[16:19]
	v_mfma_f32_16x16x32_bf16 v[44:47], v[198:201], v[214:217], 0
	v_mfma_f32_16x16x32_bf16 v[40:43], v[206:209], v[214:217], 0
	v_mfma_f32_16x16x32_bf16 v[28:31], v[198:201], v[222:225], 0
	v_mfma_f32_16x16x32_bf16 v[24:27], v[206:209], v[222:225], 0
	v_mfma_f32_16x16x32_bf16 v[12:15], v[198:201], v[230:233], 0
	v_mfma_f32_16x16x32_bf16 v[8:11], v[206:209], v[230:233], 0
	v_mfma_f32_16x16x32_bf16 v[4:7], v[198:201], v[238:241], 0
	v_mfma_f32_16x16x32_bf16 v[0:3], v[206:209], v[238:241], 0
	v_mfma_f32_16x16x32_bf16 v[44:47], v[202:205], v[218:221], v[44:47]
	v_mfma_f32_16x16x32_bf16 v[40:43], v[210:213], v[218:221], v[40:43]
	v_mfma_f32_16x16x32_bf16 v[28:31], v[202:205], v[226:229], v[28:31]
	v_mfma_f32_16x16x32_bf16 v[24:27], v[210:213], v[226:229], v[24:27]
	v_mfma_f32_16x16x32_bf16 v[12:15], v[202:205], v[234:237], v[12:15]
	v_mfma_f32_16x16x32_bf16 v[8:11], v[210:213], v[234:237], v[8:11]
	v_mfma_f32_16x16x32_bf16 v[4:7], v[202:205], v[242:245], v[4:7]
	v_mfma_f32_16x16x32_bf16 v[0:3], v[210:213], v[242:245], v[0:3]
	s_barrier
	s_add_i32 s34, 0, 0x18000
	v_add_u32_e32 v181, s34, v153
	s_add_i32 s35, 0, 0x1c000
	ds_read_b128 v[182:185], v181
	ds_read_b128 v[186:189], v181 offset:1024
	ds_read_b128 v[190:193], v181 offset:2048
	ds_read_b128 v[194:197], v181 offset:3072
	v_add_u32_e32 v181, s35, v153
	ds_read_b128 v[198:201], v181
	ds_read_b128 v[202:205], v181 offset:1024
	ds_read_b128 v[206:209], v181 offset:2048
	ds_read_b128 v[210:213], v181 offset:3072
	s_add_u32 s36, s44, 0xb0000
	s_addc_u32 s37, s45, 0
	s_mov_b32 m0, s20
	ds_read_b128 v[214:217], v155 offset:32768
	ds_read_b128 v[218:221], v155 offset:33792
	ds_read_b128 v[222:225], v155 offset:34816
	ds_read_b128 v[226:229], v155 offset:35840
	ds_read_b128 v[230:233], v155 offset:36864
	ds_read_b128 v[234:237], v155 offset:37888
	ds_read_b128 v[238:241], v155 offset:38912
	ds_read_b128 v[242:245], v155 offset:39936
	global_load_lds_dwordx4 v142, s[36:37]
	s_mov_b32 m0, s26
	s_nop 0
	global_load_lds_dwordx4 v144, s[36:37]
	s_waitcnt vmcnt(8)
	s_waitcnt lgkmcnt(0)
	s_barrier
	v_mfma_f32_16x16x32_bf16 v[124:127], v[182:185], v[214:217], v[124:127]
	v_mfma_f32_16x16x32_bf16 v[120:123], v[190:193], v[214:217], v[120:123]
	v_mfma_f32_16x16x32_bf16 v[116:119], v[182:185], v[222:225], v[116:119]
	v_mfma_f32_16x16x32_bf16 v[112:115], v[190:193], v[222:225], v[112:115]
	v_mfma_f32_16x16x32_bf16 v[100:103], v[182:185], v[230:233], v[100:103]
	v_mfma_f32_16x16x32_bf16 v[96:99], v[190:193], v[230:233], v[96:99]
	v_mfma_f32_16x16x32_bf16 v[84:87], v[182:185], v[238:241], v[84:87]
	v_mfma_f32_16x16x32_bf16 v[80:83], v[190:193], v[238:241], v[80:83]
	v_mfma_f32_16x16x32_bf16 v[124:127], v[186:189], v[218:221], v[124:127]
	v_mfma_f32_16x16x32_bf16 v[120:123], v[194:197], v[218:221], v[120:123]
	v_mfma_f32_16x16x32_bf16 v[116:119], v[186:189], v[226:229], v[116:119]
	v_mfma_f32_16x16x32_bf16 v[112:115], v[194:197], v[226:229], v[112:115]
	v_mfma_f32_16x16x32_bf16 v[100:103], v[186:189], v[234:237], v[100:103]
	v_mfma_f32_16x16x32_bf16 v[96:99], v[194:197], v[234:237], v[96:99]
	v_mfma_f32_16x16x32_bf16 v[84:87], v[186:189], v[242:245], v[84:87]
	v_mfma_f32_16x16x32_bf16 v[80:83], v[194:197], v[242:245], v[80:83]
	v_mfma_f32_16x16x32_bf16 v[108:111], v[198:201], v[214:217], v[108:111]
	v_mfma_f32_16x16x32_bf16 v[104:107], v[206:209], v[214:217], v[104:107]
	v_mfma_f32_16x16x32_bf16 v[92:95], v[198:201], v[222:225], v[92:95]
	v_mfma_f32_16x16x32_bf16 v[88:91], v[206:209], v[222:225], v[88:91]
	v_mfma_f32_16x16x32_bf16 v[76:79], v[198:201], v[230:233], v[76:79]
	v_mfma_f32_16x16x32_bf16 v[72:75], v[206:209], v[230:233], v[72:75]
	v_mfma_f32_16x16x32_bf16 v[68:71], v[198:201], v[238:241], v[68:71]
	v_mfma_f32_16x16x32_bf16 v[64:67], v[206:209], v[238:241], v[64:67]
	v_mfma_f32_16x16x32_bf16 v[108:111], v[202:205], v[218:221], v[108:111]
	v_mfma_f32_16x16x32_bf16 v[104:107], v[210:213], v[218:221], v[104:107]
	v_mfma_f32_16x16x32_bf16 v[92:95], v[202:205], v[226:229], v[92:95]
	v_mfma_f32_16x16x32_bf16 v[88:91], v[210:213], v[226:229], v[88:91]
	v_mfma_f32_16x16x32_bf16 v[76:79], v[202:205], v[234:237], v[76:79]
	v_mfma_f32_16x16x32_bf16 v[72:75], v[210:213], v[234:237], v[72:75]
	v_mfma_f32_16x16x32_bf16 v[68:71], v[202:205], v[242:245], v[68:71]
	v_mfma_f32_16x16x32_bf16 v[64:67], v[210:213], v[242:245], v[64:67]
	s_barrier
	s_add_i32 s21, s34, s12
	s_mov_b32 m0, s21
	ds_read_b128 v[214:217], v155 offset:49152
	ds_read_b128 v[218:221], v155 offset:50176
	ds_read_b128 v[222:225], v155 offset:51200
	ds_read_b128 v[226:229], v155 offset:52224
	ds_read_b128 v[230:233], v155 offset:53248
	ds_read_b128 v[234:237], v155 offset:54272
	ds_read_b128 v[238:241], v155 offset:55296
	ds_read_b128 v[242:245], v155 offset:56320
	global_load_lds_dwordx4 v130, s[60:61]
	s_add_i32 m0, s21, 0x2000
	s_add_u32 s36, s42, 0xb0080
	s_addc_u32 s37, s43, 0
	s_add_i32 s21, s35, s12
	global_load_lds_dwordx4 v146, s[60:61]
	s_mov_b32 m0, s21
	s_nop 0
	global_load_lds_dwordx4 v130, s[36:37]
	s_add_i32 m0, s21, 0x2000
	s_nop 0
	global_load_lds_dwordx4 v146, s[36:37]
	s_mov_b32 m0, s33
	s_nop 0
	global_load_lds_dwordx4 v142, s[62:63]
	s_mov_b32 m0, s38
	s_nop 0
	global_load_lds_dwordx4 v144, s[62:63]
	s_waitcnt vmcnt(8)
	s_waitcnt lgkmcnt(0)
	s_barrier
	v_mfma_f32_16x16x32_bf16 v[60:63], v[182:185], v[214:217], v[60:63]
	v_mfma_f32_16x16x32_bf16 v[56:59], v[190:193], v[214:217], v[56:59]
	v_mfma_f32_16x16x32_bf16 v[52:55], v[182:185], v[222:225], v[52:55]
	v_mfma_f32_16x16x32_bf16 v[48:51], v[190:193], v[222:225], v[48:51]
	v_mfma_f32_16x16x32_bf16 v[36:39], v[182:185], v[230:233], v[36:39]
	v_mfma_f32_16x16x32_bf16 v[32:35], v[190:193], v[230:233], v[32:35]
	v_mfma_f32_16x16x32_bf16 v[20:23], v[182:185], v[238:241], v[20:23]
	v_mfma_f32_16x16x32_bf16 v[16:19], v[190:193], v[238:241], v[16:19]
	v_mfma_f32_16x16x32_bf16 v[60:63], v[186:189], v[218:221], v[60:63]
	v_mfma_f32_16x16x32_bf16 v[56:59], v[194:197], v[218:221], v[56:59]
	v_mfma_f32_16x16x32_bf16 v[52:55], v[186:189], v[226:229], v[52:55]
	v_mfma_f32_16x16x32_bf16 v[48:51], v[194:197], v[226:229], v[48:51]
	v_mfma_f32_16x16x32_bf16 v[36:39], v[186:189], v[234:237], v[36:39]
	v_mfma_f32_16x16x32_bf16 v[32:35], v[194:197], v[234:237], v[32:35]
	v_mfma_f32_16x16x32_bf16 v[20:23], v[186:189], v[242:245], v[20:23]
	v_mfma_f32_16x16x32_bf16 v[16:19], v[194:197], v[242:245], v[16:19]
	v_mfma_f32_16x16x32_bf16 v[44:47], v[198:201], v[214:217], v[44:47]
	v_mfma_f32_16x16x32_bf16 v[40:43], v[206:209], v[214:217], v[40:43]
	v_mfma_f32_16x16x32_bf16 v[28:31], v[198:201], v[222:225], v[28:31]
	v_mfma_f32_16x16x32_bf16 v[24:27], v[206:209], v[222:225], v[24:27]
	v_mfma_f32_16x16x32_bf16 v[12:15], v[198:201], v[230:233], v[12:15]
	v_mfma_f32_16x16x32_bf16 v[8:11], v[206:209], v[230:233], v[8:11]
	v_mfma_f32_16x16x32_bf16 v[4:7], v[198:201], v[238:241], v[4:7]
	v_mfma_f32_16x16x32_bf16 v[0:3], v[206:209], v[238:241], v[0:3]
	v_mfma_f32_16x16x32_bf16 v[44:47], v[202:205], v[218:221], v[44:47]
	v_mfma_f32_16x16x32_bf16 v[40:43], v[210:213], v[218:221], v[40:43]
	v_mfma_f32_16x16x32_bf16 v[28:31], v[202:205], v[226:229], v[28:31]
	v_mfma_f32_16x16x32_bf16 v[24:27], v[210:213], v[226:229], v[24:27]
	v_mfma_f32_16x16x32_bf16 v[12:15], v[202:205], v[234:237], v[12:15]
	v_mfma_f32_16x16x32_bf16 v[8:11], v[210:213], v[234:237], v[8:11]
	v_mfma_f32_16x16x32_bf16 v[4:7], v[202:205], v[242:245], v[4:7]
	v_mfma_f32_16x16x32_bf16 v[0:3], v[210:213], v[242:245], v[0:3]
	s_barrier
	s_add_u32 s50, s50, 0x100
	s_addc_u32 s51, s51, 0
	s_cmp_ge_i32 s52, s49
	s_mov_b64 s[36:37], s[40:41]
	s_mov_b32 s42, s52
	s_cbranch_scc1 .Lpeel_done_286
.LBB0_286:
	s_add_i32 s52, s42, 2
	s_add_u32 s40, s36, 0x100
	s_addc_u32 s41, s37, 0
	s_add_i32 s22, 0, 0x10000
	s_cmp_eq_u32 s11, s42
	s_cselect_b32 s45, s17, s41
	s_cselect_b32 s44, s16, s40
	v_add_u32_e32 v156, s22, v153
	s_cselect_b32 s43, s29, s51
	s_cselect_b32 s42, s28, s50
	s_add_i32 s23, 0, 0x14000
	ds_read_b128 v[182:185], v156
	ds_read_b128 v[186:189], v156 offset:1024
	ds_read_b128 v[190:193], v156 offset:2048
	ds_read_b128 v[194:197], v156 offset:3072
	v_add_u32_e32 v156, s23, v153
	ds_read_b128 v[198:201], v156
	ds_read_b128 v[202:205], v156 offset:1024
	ds_read_b128 v[206:209], v156 offset:2048
	ds_read_b128 v[210:213], v156 offset:3072
	s_add_i32 m0, s13, 0xc000
	ds_read_b128 v[214:217], v155
	ds_read_b128 v[218:221], v155 offset:1024
	ds_read_b128 v[222:225], v155 offset:2048
	ds_read_b128 v[226:229], v155 offset:3072
	ds_read_b128 v[230:233], v155 offset:4096
	ds_read_b128 v[234:237], v155 offset:5120
	ds_read_b128 v[238:241], v155 offset:6144
	ds_read_b128 v[242:245], v155 offset:7168
	global_load_lds_dwordx4 v148, s[36:37]
	s_add_i32 m0, s13, 0xe000
	s_nop 0
	global_load_lds_dwordx4 v150, s[36:37]
	s_waitcnt vmcnt(8)
	s_waitcnt lgkmcnt(0)
	s_barrier
	v_mfma_f32_16x16x32_bf16 v[124:127], v[182:185], v[214:217], v[124:127]
	v_mfma_f32_16x16x32_bf16 v[120:123], v[190:193], v[214:217], v[120:123]
	v_mfma_f32_16x16x32_bf16 v[116:119], v[182:185], v[222:225], v[116:119]
	v_mfma_f32_16x16x32_bf16 v[112:115], v[190:193], v[222:225], v[112:115]
	v_mfma_f32_16x16x32_bf16 v[100:103], v[182:185], v[230:233], v[100:103]
	v_mfma_f32_16x16x32_bf16 v[96:99], v[190:193], v[230:233], v[96:99]
	v_mfma_f32_16x16x32_bf16 v[84:87], v[182:185], v[238:241], v[84:87]
	v_mfma_f32_16x16x32_bf16 v[80:83], v[190:193], v[238:241], v[80:83]
	v_mfma_f32_16x16x32_bf16 v[124:127], v[186:189], v[218:221], v[124:127]
	v_mfma_f32_16x16x32_bf16 v[120:123], v[194:197], v[218:221], v[120:123]
	v_mfma_f32_16x16x32_bf16 v[116:119], v[186:189], v[226:229], v[116:119]
	v_mfma_f32_16x16x32_bf16 v[112:115], v[194:197], v[226:229], v[112:115]
	v_mfma_f32_16x16x32_bf16 v[100:103], v[186:189], v[234:237], v[100:103]
	v_mfma_f32_16x16x32_bf16 v[96:99], v[194:197], v[234:237], v[96:99]
	v_mfma_f32_16x16x32_bf16 v[84:87], v[186:189], v[242:245], v[84:87]
	v_mfma_f32_16x16x32_bf16 v[80:83], v[194:197], v[242:245], v[80:83]
	v_mfma_f32_16x16x32_bf16 v[108:111], v[198:201], v[214:217], v[108:111]
	v_mfma_f32_16x16x32_bf16 v[104:107], v[206:209], v[214:217], v[104:107]
	v_mfma_f32_16x16x32_bf16 v[92:95], v[198:201], v[222:225], v[92:95]
	v_mfma_f32_16x16x32_bf16 v[88:91], v[206:209], v[222:225], v[88:91]
	v_mfma_f32_16x16x32_bf16 v[76:79], v[198:201], v[230:233], v[76:79]
	v_mfma_f32_16x16x32_bf16 v[72:75], v[206:209], v[230:233], v[72:75]
	v_mfma_f32_16x16x32_bf16 v[68:71], v[198:201], v[238:241], v[68:71]
	v_mfma_f32_16x16x32_bf16 v[64:67], v[206:209], v[238:241], v[64:67]
	v_mfma_f32_16x16x32_bf16 v[108:111], v[202:205], v[218:221], v[108:111]
	v_mfma_f32_16x16x32_bf16 v[104:107], v[210:213], v[218:221], v[104:107]
	v_mfma_f32_16x16x32_bf16 v[92:95], v[202:205], v[226:229], v[92:95]
	v_mfma_f32_16x16x32_bf16 v[88:91], v[210:213], v[226:229], v[88:91]
	v_mfma_f32_16x16x32_bf16 v[76:79], v[202:205], v[234:237], v[76:79]
	v_mfma_f32_16x16x32_bf16 v[72:75], v[210:213], v[234:237], v[72:75]
	v_mfma_f32_16x16x32_bf16 v[68:71], v[202:205], v[242:245], v[68:71]
	v_mfma_f32_16x16x32_bf16 v[64:67], v[210:213], v[242:245], v[64:67]
	s_barrier
	s_add_u32 s60, s42, 0x80
	s_addc_u32 s61, s43, 0
	s_add_u32 s62, s44, 0x80
	s_addc_u32 s63, s45, 0
	s_add_i32 s21, s22, s12
	s_mov_b32 m0, s21
	ds_read_b128 v[214:217], v155 offset:16384
	ds_read_b128 v[218:221], v155 offset:17408
	ds_read_b128 v[222:225], v155 offset:18432
	ds_read_b128 v[226:229], v155 offset:19456
	ds_read_b128 v[230:233], v155 offset:20480
	ds_read_b128 v[234:237], v155 offset:21504
	ds_read_b128 v[238:241], v155 offset:22528
	ds_read_b128 v[242:245], v155 offset:23552
	global_load_lds_dwordx4 v130, s[42:43]
	s_add_i32 m0, s21, 0x2000
	s_add_u32 s34, s42, 0xb0000
	s_addc_u32 s35, s43, 0
	s_add_i32 s21, s23, s12
	global_load_lds_dwordx4 v146, s[42:43]
	s_mov_b32 m0, s21
	s_nop 0
	global_load_lds_dwordx4 v130, s[34:35]
	s_add_i32 m0, s21, 0x2000
	s_nop 0
	global_load_lds_dwordx4 v146, s[34:35]
	s_mov_b32 m0, s13
	s_nop 0
	global_load_lds_dwordx4 v142, s[44:45]
	s_mov_b32 m0, s19
	s_nop 0
	global_load_lds_dwordx4 v144, s[44:45]
	s_waitcnt vmcnt(8)
	s_waitcnt lgkmcnt(0)
	s_barrier
	v_mfma_f32_16x16x32_bf16 v[60:63], v[182:185], v[214:217], v[60:63]
	v_mfma_f32_16x16x32_bf16 v[56:59], v[190:193], v[214:217], v[56:59]
	v_mfma_f32_16x16x32_bf16 v[52:55], v[182:185], v[222:225], v[52:55]
	v_mfma_f32_16x16x32_bf16 v[48:51], v[190:193], v[222:225], v[48:51]
	v_mfma_f32_16x16x32_bf16 v[36:39], v[182:185], v[230:233], v[36:39]
	v_mfma_f32_16x16x32_bf16 v[32:35], v[190:193], v[230:233], v[32:35]
	v_mfma_f32_16x16x32_bf16 v[20:23], v[182:185], v[238:241], v[20:23]
	v_mfma_f32_16x16x32_bf16 v[16:19], v[190:193], v[238:241], v[16:19]
	v_mfma_f32_16x16x32_bf16 v[60:63], v[186:189], v[218:221], v[60:63]
	v_mfma_f32_16x16x32_bf16 v[56:59], v[194:197], v[218:221], v[56:59]
	v_mfma_f32_16x16x32_bf16 v[52:55], v[186:189], v[226:229], v[52:55]
	v_mfma_f32_16x16x32_bf16 v[48:51], v[194:197], v[226:229], v[48:51]
	v_mfma_f32_16x16x32_bf16 v[36:39], v[186:189], v[234:237], v[36:39]
	v_mfma_f32_16x16x32_bf16 v[32:35], v[194:197], v[234:237], v[32:35]
	v_mfma_f32_16x16x32_bf16 v[20:23], v[186:189], v[242:245], v[20:23]
	v_mfma_f32_16x16x32_bf16 v[16:19], v[194:197], v[242:245], v[16:19]
	v_mfma_f32_16x16x32_bf16 v[44:47], v[198:201], v[214:217], v[44:47]
	v_mfma_f32_16x16x32_bf16 v[40:43], v[206:209], v[214:217], v[40:43]
	v_mfma_f32_16x16x32_bf16 v[28:31], v[198:201], v[222:225], v[28:31]
	v_mfma_f32_16x16x32_bf16 v[24:27], v[206:209], v[222:225], v[24:27]
	v_mfma_f32_16x16x32_bf16 v[12:15], v[198:201], v[230:233], v[12:15]
	v_mfma_f32_16x16x32_bf16 v[8:11], v[206:209], v[230:233], v[8:11]
	v_mfma_f32_16x16x32_bf16 v[4:7], v[198:201], v[238:241], v[4:7]
	v_mfma_f32_16x16x32_bf16 v[0:3], v[206:209], v[238:241], v[0:3]
	v_mfma_f32_16x16x32_bf16 v[44:47], v[202:205], v[218:221], v[44:47]
	v_mfma_f32_16x16x32_bf16 v[40:43], v[210:213], v[218:221], v[40:43]
	v_mfma_f32_16x16x32_bf16 v[28:31], v[202:205], v[226:229], v[28:31]
	v_mfma_f32_16x16x32_bf16 v[24:27], v[210:213], v[226:229], v[24:27]
	v_mfma_f32_16x16x32_bf16 v[12:15], v[202:205], v[234:237], v[12:15]
	v_mfma_f32_16x16x32_bf16 v[8:11], v[210:213], v[234:237], v[8:11]
	v_mfma_f32_16x16x32_bf16 v[4:7], v[202:205], v[242:245], v[4:7]
	v_mfma_f32_16x16x32_bf16 v[0:3], v[210:213], v[242:245], v[0:3]
	s_barrier
	s_add_i32 s34, 0, 0x18000
	v_add_u32_e32 v181, s34, v153
	s_add_i32 s35, 0, 0x1c000
	ds_read_b128 v[182:185], v181
	ds_read_b128 v[186:189], v181 offset:1024
	ds_read_b128 v[190:193], v181 offset:2048
	ds_read_b128 v[194:197], v181 offset:3072
	v_add_u32_e32 v181, s35, v153
	ds_read_b128 v[198:201], v181
	ds_read_b128 v[202:205], v181 offset:1024
	ds_read_b128 v[206:209], v181 offset:2048
	ds_read_b128 v[210:213], v181 offset:3072
	s_add_u32 s36, s44, 0xb0000
	s_addc_u32 s37, s45, 0
	s_mov_b32 m0, s20
	ds_read_b128 v[214:217], v155 offset:32768
	ds_read_b128 v[218:221], v155 offset:33792
	ds_read_b128 v[222:225], v155 offset:34816
	ds_read_b128 v[226:229], v155 offset:35840
	ds_read_b128 v[230:233], v155 offset:36864
	ds_read_b128 v[234:237], v155 offset:37888
	ds_read_b128 v[238:241], v155 offset:38912
	ds_read_b128 v[242:245], v155 offset:39936
	global_load_lds_dwordx4 v142, s[36:37]
	s_mov_b32 m0, s26
	s_nop 0
	global_load_lds_dwordx4 v144, s[36:37]
	s_waitcnt vmcnt(8)
	s_waitcnt lgkmcnt(0)
	s_barrier
	v_mfma_f32_16x16x32_bf16 v[124:127], v[182:185], v[214:217], v[124:127]
	v_mfma_f32_16x16x32_bf16 v[120:123], v[190:193], v[214:217], v[120:123]
	v_mfma_f32_16x16x32_bf16 v[116:119], v[182:185], v[222:225], v[116:119]
	v_mfma_f32_16x16x32_bf16 v[112:115], v[190:193], v[222:225], v[112:115]
	v_mfma_f32_16x16x32_bf16 v[100:103], v[182:185], v[230:233], v[100:103]
	v_mfma_f32_16x16x32_bf16 v[96:99], v[190:193], v[230:233], v[96:99]
	v_mfma_f32_16x16x32_bf16 v[84:87], v[182:185], v[238:241], v[84:87]
	v_mfma_f32_16x16x32_bf16 v[80:83], v[190:193], v[238:241], v[80:83]
	v_mfma_f32_16x16x32_bf16 v[124:127], v[186:189], v[218:221], v[124:127]
	v_mfma_f32_16x16x32_bf16 v[120:123], v[194:197], v[218:221], v[120:123]
	v_mfma_f32_16x16x32_bf16 v[116:119], v[186:189], v[226:229], v[116:119]
	v_mfma_f32_16x16x32_bf16 v[112:115], v[194:197], v[226:229], v[112:115]
	v_mfma_f32_16x16x32_bf16 v[100:103], v[186:189], v[234:237], v[100:103]
	v_mfma_f32_16x16x32_bf16 v[96:99], v[194:197], v[234:237], v[96:99]
	v_mfma_f32_16x16x32_bf16 v[84:87], v[186:189], v[242:245], v[84:87]
	v_mfma_f32_16x16x32_bf16 v[80:83], v[194:197], v[242:245], v[80:83]
	v_mfma_f32_16x16x32_bf16 v[108:111], v[198:201], v[214:217], v[108:111]
	v_mfma_f32_16x16x32_bf16 v[104:107], v[206:209], v[214:217], v[104:107]
	v_mfma_f32_16x16x32_bf16 v[92:95], v[198:201], v[222:225], v[92:95]
	v_mfma_f32_16x16x32_bf16 v[88:91], v[206:209], v[222:225], v[88:91]
	v_mfma_f32_16x16x32_bf16 v[76:79], v[198:201], v[230:233], v[76:79]
	v_mfma_f32_16x16x32_bf16 v[72:75], v[206:209], v[230:233], v[72:75]
	v_mfma_f32_16x16x32_bf16 v[68:71], v[198:201], v[238:241], v[68:71]
	v_mfma_f32_16x16x32_bf16 v[64:67], v[206:209], v[238:241], v[64:67]
	v_mfma_f32_16x16x32_bf16 v[108:111], v[202:205], v[218:221], v[108:111]
	v_mfma_f32_16x16x32_bf16 v[104:107], v[210:213], v[218:221], v[104:107]
	v_mfma_f32_16x16x32_bf16 v[92:95], v[202:205], v[226:229], v[92:95]
	v_mfma_f32_16x16x32_bf16 v[88:91], v[210:213], v[226:229], v[88:91]
	v_mfma_f32_16x16x32_bf16 v[76:79], v[202:205], v[234:237], v[76:79]
	v_mfma_f32_16x16x32_bf16 v[72:75], v[210:213], v[234:237], v[72:75]
	v_mfma_f32_16x16x32_bf16 v[68:71], v[202:205], v[242:245], v[68:71]
	v_mfma_f32_16x16x32_bf16 v[64:67], v[210:213], v[242:245], v[64:67]
	s_barrier
	s_add_i32 s21, s34, s12
	s_mov_b32 m0, s21
	ds_read_b128 v[214:217], v155 offset:49152
	ds_read_b128 v[218:221], v155 offset:50176
	ds_read_b128 v[222:225], v155 offset:51200
	ds_read_b128 v[226:229], v155 offset:52224
	ds_read_b128 v[230:233], v155 offset:53248
	ds_read_b128 v[234:237], v155 offset:54272
	ds_read_b128 v[238:241], v155 offset:55296
	ds_read_b128 v[242:245], v155 offset:56320
	global_load_lds_dwordx4 v130, s[60:61]
	s_add_i32 m0, s21, 0x2000
	s_add_u32 s36, s42, 0xb0080
	s_addc_u32 s37, s43, 0
	s_add_i32 s21, s35, s12
	global_load_lds_dwordx4 v146, s[60:61]
	s_mov_b32 m0, s21
	s_nop 0
	global_load_lds_dwordx4 v130, s[36:37]
	s_add_i32 m0, s21, 0x2000
	s_nop 0
	global_load_lds_dwordx4 v146, s[36:37]
	s_mov_b32 m0, s33
	s_nop 0
	global_load_lds_dwordx4 v142, s[62:63]
	s_mov_b32 m0, s38
	s_nop 0
	global_load_lds_dwordx4 v144, s[62:63]
	s_waitcnt vmcnt(8)
	s_waitcnt lgkmcnt(0)
	s_barrier
	v_mfma_f32_16x16x32_bf16 v[60:63], v[182:185], v[214:217], v[60:63]
	v_mfma_f32_16x16x32_bf16 v[56:59], v[190:193], v[214:217], v[56:59]
	v_mfma_f32_16x16x32_bf16 v[52:55], v[182:185], v[222:225], v[52:55]
	v_mfma_f32_16x16x32_bf16 v[48:51], v[190:193], v[222:225], v[48:51]
	v_mfma_f32_16x16x32_bf16 v[36:39], v[182:185], v[230:233], v[36:39]
	v_mfma_f32_16x16x32_bf16 v[32:35], v[190:193], v[230:233], v[32:35]
	v_mfma_f32_16x16x32_bf16 v[20:23], v[182:185], v[238:241], v[20:23]
	v_mfma_f32_16x16x32_bf16 v[16:19], v[190:193], v[238:241], v[16:19]
	v_mfma_f32_16x16x32_bf16 v[60:63], v[186:189], v[218:221], v[60:63]
	v_mfma_f32_16x16x32_bf16 v[56:59], v[194:197], v[218:221], v[56:59]
	v_mfma_f32_16x16x32_bf16 v[52:55], v[186:189], v[226:229], v[52:55]
	v_mfma_f32_16x16x32_bf16 v[48:51], v[194:197], v[226:229], v[48:51]
	v_mfma_f32_16x16x32_bf16 v[36:39], v[186:189], v[234:237], v[36:39]
	v_mfma_f32_16x16x32_bf16 v[32:35], v[194:197], v[234:237], v[32:35]
	v_mfma_f32_16x16x32_bf16 v[20:23], v[186:189], v[242:245], v[20:23]
	v_mfma_f32_16x16x32_bf16 v[16:19], v[194:197], v[242:245], v[16:19]
	v_mfma_f32_16x16x32_bf16 v[44:47], v[198:201], v[214:217], v[44:47]
	v_mfma_f32_16x16x32_bf16 v[40:43], v[206:209], v[214:217], v[40:43]
	v_mfma_f32_16x16x32_bf16 v[28:31], v[198:201], v[222:225], v[28:31]
	v_mfma_f32_16x16x32_bf16 v[24:27], v[206:209], v[222:225], v[24:27]
	v_mfma_f32_16x16x32_bf16 v[12:15], v[198:201], v[230:233], v[12:15]
	v_mfma_f32_16x16x32_bf16 v[8:11], v[206:209], v[230:233], v[8:11]
	v_mfma_f32_16x16x32_bf16 v[4:7], v[198:201], v[238:241], v[4:7]
	v_mfma_f32_16x16x32_bf16 v[0:3], v[206:209], v[238:241], v[0:3]
	v_mfma_f32_16x16x32_bf16 v[44:47], v[202:205], v[218:221], v[44:47]
	v_mfma_f32_16x16x32_bf16 v[40:43], v[210:213], v[218:221], v[40:43]
	v_mfma_f32_16x16x32_bf16 v[28:31], v[202:205], v[226:229], v[28:31]
	v_mfma_f32_16x16x32_bf16 v[24:27], v[210:213], v[226:229], v[24:27]
	v_mfma_f32_16x16x32_bf16 v[12:15], v[202:205], v[234:237], v[12:15]
	v_mfma_f32_16x16x32_bf16 v[8:11], v[210:213], v[234:237], v[8:11]
	v_mfma_f32_16x16x32_bf16 v[4:7], v[202:205], v[242:245], v[4:7]
	v_mfma_f32_16x16x32_bf16 v[0:3], v[210:213], v[242:245], v[0:3]
	s_barrier
	s_add_u32 s50, s50, 0x100
	s_addc_u32 s51, s51, 0
	s_cmp_ge_i32 s52, s49
	s_mov_b64 s[36:37], s[40:41]
	s_mov_b32 s42, s52
	s_cbranch_scc0 .LBB0_286

.LBB0_510:
	s_ashr_i32 s17, s16, 31
	s_lshl_b64 s[18:19], s[16:17], 19
	v_readlane_b32 s24, v252, 27
	v_readlane_b32 s25, v252, 28
	s_add_u32 s28, s24, s18
	s_addc_u32 s29, s25, s19
	s_and_b64 s[18:19], s[4:5], exec
	s_cselect_b32 s17, s29, s41
	s_cselect_b32 s18, s28, s40
	s_ashr_i32 s11, s10, 31
	s_lshl_b64 s[36:37], s[10:11], 19
	v_readlane_b32 s11, v252, 8
	s_add_u32 s36, s11, s36
	v_readlane_b32 s11, v252, 9
	s_addc_u32 s37, s11, s37
	s_and_b64 s[38:39], s[4:5], exec
	s_cselect_b32 s11, s37, s43
	s_cselect_b32 s19, s36, s42
	s_add_u32 s40, s40, 0x40080
	s_addc_u32 s41, s41, 0
	s_add_u32 s38, s42, 0x100
	s_addc_u32 s39, s43, 0
	s_mov_b32 s46, -2
	v_add_u32_e32 v156, s22, v153
	ds_read_b128 v[182:185], v156
	ds_read_b128 v[186:189], v156 offset:1024
	ds_read_b128 v[190:193], v156 offset:2048
	ds_read_b128 v[194:197], v156 offset:3072
	v_add_u32_e32 v156, s23, v153
	ds_read_b128 v[198:201], v156
	ds_read_b128 v[202:205], v156 offset:1024
	ds_read_b128 v[206:209], v156 offset:2048
	ds_read_b128 v[210:213], v156 offset:3072
	s_add_u32 s21, s40, 0xfffc0080
	s_addc_u32 s24, s41, -1
	s_cmp_eq_u32 s46, 12
	s_cselect_b32 s45, s17, s24
	s_cselect_b32 s44, s18, s21
	s_cselect_b32 s43, s11, s39
	s_cselect_b32 s42, s19, s38
	s_add_i32 m0, s12, 0xc000
	ds_read_b128 v[214:217], v155
	ds_read_b128 v[218:221], v155 offset:1024
	ds_read_b128 v[222:225], v155 offset:2048
	ds_read_b128 v[226:229], v155 offset:3072
	ds_read_b128 v[230:233], v155 offset:4096
	ds_read_b128 v[234:237], v155 offset:5120
	ds_read_b128 v[238:241], v155 offset:6144
	ds_read_b128 v[242:245], v155 offset:7168
	global_load_lds_dwordx4 v148, s[40:41]
	s_add_i32 m0, s12, 0xe000
	s_nop 0
	global_load_lds_dwordx4 v150, s[40:41]
	s_waitcnt vmcnt(8)
	s_waitcnt lgkmcnt(0)
	s_barrier
	v_mfma_f32_16x16x32_bf16 v[124:127], v[182:185], v[214:217], 0
	v_mfma_f32_16x16x32_bf16 v[120:123], v[190:193], v[214:217], 0
	v_mfma_f32_16x16x32_bf16 v[116:119], v[182:185], v[222:225], 0
	v_mfma_f32_16x16x32_bf16 v[112:115], v[190:193], v[222:225], 0
	v_mfma_f32_16x16x32_bf16 v[100:103], v[182:185], v[230:233], 0
	v_mfma_f32_16x16x32_bf16 v[96:99], v[190:193], v[230:233], 0
	v_mfma_f32_16x16x32_bf16 v[84:87], v[182:185], v[238:241], 0
	v_mfma_f32_16x16x32_bf16 v[80:83], v[190:193], v[238:241], 0
	v_mfma_f32_16x16x32_bf16 v[124:127], v[186:189], v[218:221], v[124:127]
	v_mfma_f32_16x16x32_bf16 v[120:123], v[194:197], v[218:221], v[120:123]
	v_mfma_f32_16x16x32_bf16 v[116:119], v[186:189], v[226:229], v[116:119]
	v_mfma_f32_16x16x32_bf16 v[112:115], v[194:197], v[226:229], v[112:115]
	v_mfma_f32_16x16x32_bf16 v[100:103], v[186:189], v[234:237], v[100:103]
	v_mfma_f32_16x16x32_bf16 v[96:99], v[194:197], v[234:237], v[96:99]
	v_mfma_f32_16x16x32_bf16 v[84:87], v[186:189], v[242:245], v[84:87]
	v_mfma_f32_16x16x32_bf16 v[80:83], v[194:197], v[242:245], v[80:83]
	v_mfma_f32_16x16x32_bf16 v[108:111], v[198:201], v[214:217], 0
	v_mfma_f32_16x16x32_bf16 v[104:107], v[206:209], v[214:217], 0
	v_mfma_f32_16x16x32_bf16 v[92:95], v[198:201], v[222:225], 0
	v_mfma_f32_16x16x32_bf16 v[88:91], v[206:209], v[222:225], 0
	v_mfma_f32_16x16x32_bf16 v[76:79], v[198:201], v[230:233], 0
	v_mfma_f32_16x16x32_bf16 v[72:75], v[206:209], v[230:233], 0
	v_mfma_f32_16x16x32_bf16 v[68:71], v[198:201], v[238:241], 0
	v_mfma_f32_16x16x32_bf16 v[64:67], v[206:209], v[238:241], 0
	v_mfma_f32_16x16x32_bf16 v[108:111], v[202:205], v[218:221], v[108:111]
	v_mfma_f32_16x16x32_bf16 v[104:107], v[210:213], v[218:221], v[104:107]
	v_mfma_f32_16x16x32_bf16 v[92:95], v[202:205], v[226:229], v[92:95]
	v_mfma_f32_16x16x32_bf16 v[88:91], v[210:213], v[226:229], v[88:91]
	v_mfma_f32_16x16x32_bf16 v[76:79], v[202:205], v[234:237], v[76:79]
	v_mfma_f32_16x16x32_bf16 v[72:75], v[210:213], v[234:237], v[72:75]
	v_mfma_f32_16x16x32_bf16 v[68:71], v[202:205], v[242:245], v[68:71]
	v_mfma_f32_16x16x32_bf16 v[64:67], v[210:213], v[242:245], v[64:67]
	s_barrier
	s_add_u32 s60, s42, 0x80
	s_addc_u32 s61, s43, 0
	s_add_u32 s62, s44, 0x80
	s_addc_u32 s63, s45, 0
	s_add_i32 s21, s22, s3
	s_mov_b32 m0, s21
	ds_read_b128 v[214:217], v155 offset:16384
	ds_read_b128 v[218:221], v155 offset:17408
	ds_read_b128 v[222:225], v155 offset:18432
	ds_read_b128 v[226:229], v155 offset:19456
	ds_read_b128 v[230:233], v155 offset:20480
	ds_read_b128 v[234:237], v155 offset:21504
	ds_read_b128 v[238:241], v155 offset:22528
	ds_read_b128 v[242:245], v155 offset:23552
	global_load_lds_dwordx4 v130, s[42:43]
	s_add_i32 m0, s21, 0x2000
	s_add_u32 s48, s42, 0x40000
	s_addc_u32 s49, s43, 0
	s_add_i32 s21, s23, s3
	global_load_lds_dwordx4 v142, s[42:43]
	s_mov_b32 m0, s21
	s_nop 0
	global_load_lds_dwordx4 v130, s[48:49]
	s_add_i32 m0, s21, 0x2000
	s_nop 0
	global_load_lds_dwordx4 v142, s[48:49]
	s_mov_b32 m0, s12
	s_nop 0
	global_load_lds_dwordx4 v146, s[44:45]
	s_mov_b32 m0, s13
	s_nop 0
	global_load_lds_dwordx4 v144, s[44:45]
	s_waitcnt vmcnt(8)
	s_waitcnt lgkmcnt(0)
	s_barrier
	v_mfma_f32_16x16x32_bf16 v[60:63], v[182:185], v[214:217], 0
	v_mfma_f32_16x16x32_bf16 v[56:59], v[190:193], v[214:217], 0
	v_mfma_f32_16x16x32_bf16 v[52:55], v[182:185], v[222:225], 0
	v_mfma_f32_16x16x32_bf16 v[48:51], v[190:193], v[222:225], 0
	v_mfma_f32_16x16x32_bf16 v[36:39], v[182:185], v[230:233], 0
	v_mfma_f32_16x16x32_bf16 v[32:35], v[190:193], v[230:233], 0
	v_mfma_f32_16x16x32_bf16 v[20:23], v[182:185], v[238:241], 0
	v_mfma_f32_16x16x32_bf16 v[16:19], v[190:193], v[238:241], 0
	v_mfma_f32_16x16x32_bf16 v[60:63], v[186:189], v[218:221], v[60:63]
	v_mfma_f32_16x16x32_bf16 v[56:59], v[194:197], v[218:221], v[56:59]
	v_mfma_f32_16x16x32_bf16 v[52:55], v[186:189], v[226:229], v[52:55]
	v_mfma_f32_16x16x32_bf16 v[48:51], v[194:197], v[226:229], v[48:51]
	v_mfma_f32_16x16x32_bf16 v[36:39], v[186:189], v[234:237], v[36:39]
	v_mfma_f32_16x16x32_bf16 v[32:35], v[194:197], v[234:237], v[32:35]
	v_mfma_f32_16x16x32_bf16 v[20:23], v[186:189], v[242:245], v[20:23]
	v_mfma_f32_16x16x32_bf16 v[16:19], v[194:197], v[242:245], v[16:19]
	v_mfma_f32_16x16x32_bf16 v[44:47], v[198:201], v[214:217], 0
	v_mfma_f32_16x16x32_bf16 v[40:43], v[206:209], v[214:217], 0
	v_mfma_f32_16x16x32_bf16 v[28:31], v[198:201], v[222:225], 0
	v_mfma_f32_16x16x32_bf16 v[24:27], v[206:209], v[222:225], 0
	v_mfma_f32_16x16x32_bf16 v[12:15], v[198:201], v[230:233], 0
	v_mfma_f32_16x16x32_bf16 v[8:11], v[206:209], v[230:233], 0
	v_mfma_f32_16x16x32_bf16 v[4:7], v[198:201], v[238:241], 0
	v_mfma_f32_16x16x32_bf16 v[0:3], v[206:209], v[238:241], 0
	v_mfma_f32_16x16x32_bf16 v[44:47], v[202:205], v[218:221], v[44:47]
	v_mfma_f32_16x16x32_bf16 v[40:43], v[210:213], v[218:221], v[40:43]
	v_mfma_f32_16x16x32_bf16 v[28:31], v[202:205], v[226:229], v[28:31]
	v_mfma_f32_16x16x32_bf16 v[24:27], v[210:213], v[226:229], v[24:27]
	v_mfma_f32_16x16x32_bf16 v[12:15], v[202:205], v[234:237], v[12:15]
	v_mfma_f32_16x16x32_bf16 v[8:11], v[210:213], v[234:237], v[8:11]
	v_mfma_f32_16x16x32_bf16 v[4:7], v[202:205], v[242:245], v[4:7]
	v_mfma_f32_16x16x32_bf16 v[0:3], v[210:213], v[242:245], v[0:3]
	s_barrier
	v_add_u32_e32 v181, s34, v153
	ds_read_b128 v[182:185], v181
	ds_read_b128 v[186:189], v181 offset:1024
	ds_read_b128 v[190:193], v181 offset:2048
	ds_read_b128 v[194:197], v181 offset:3072
	v_add_u32_e32 v181, s35, v153
	ds_read_b128 v[198:201], v181
	ds_read_b128 v[202:205], v181 offset:1024
	ds_read_b128 v[206:209], v181 offset:2048
	ds_read_b128 v[210:213], v181 offset:3072
	s_add_u32 s44, s44, 0x40000
	s_addc_u32 s45, s45, 0
	s_mov_b32 m0, s20
	ds_read_b128 v[214:217], v155 offset:32768
	ds_read_b128 v[218:221], v155 offset:33792
	ds_read_b128 v[222:225], v155 offset:34816
	ds_read_b128 v[226:229], v155 offset:35840
	ds_read_b128 v[230:233], v155 offset:36864
	ds_read_b128 v[234:237], v155 offset:37888
	ds_read_b128 v[238:241], v155 offset:38912
	ds_read_b128 v[242:245], v155 offset:39936
	global_load_lds_dwordx4 v146, s[44:45]
	s_mov_b32 m0, s26
	s_nop 0
	global_load_lds_dwordx4 v144, s[44:45]
	s_waitcnt vmcnt(8)
	s_waitcnt lgkmcnt(0)
	s_barrier
	v_mfma_f32_16x16x32_bf16 v[124:127], v[182:185], v[214:217], v[124:127]
	v_mfma_f32_16x16x32_bf16 v[120:123], v[190:193], v[214:217], v[120:123]
	v_mfma_f32_16x16x32_bf16 v[116:119], v[182:185], v[222:225], v[116:119]
	v_mfma_f32_16x16x32_bf16 v[112:115], v[190:193], v[222:225], v[112:115]
	v_mfma_f32_16x16x32_bf16 v[100:103], v[182:185], v[230:233], v[100:103]
	v_mfma_f32_16x16x32_bf16 v[96:99], v[190:193], v[230:233], v[96:99]
	v_mfma_f32_16x16x32_bf16 v[84:87], v[182:185], v[238:241], v[84:87]
	v_mfma_f32_16x16x32_bf16 v[80:83], v[190:193], v[238:241], v[80:83]
	v_mfma_f32_16x16x32_bf16 v[124:127], v[186:189], v[218:221], v[124:127]
	v_mfma_f32_16x16x32_bf16 v[120:123], v[194:197], v[218:221], v[120:123]
	v_mfma_f32_16x16x32_bf16 v[116:119], v[186:189], v[226:229], v[116:119]
	v_mfma_f32_16x16x32_bf16 v[112:115], v[194:197], v[226:229], v[112:115]
	v_mfma_f32_16x16x32_bf16 v[100:103], v[186:189], v[234:237], v[100:103]
	v_mfma_f32_16x16x32_bf16 v[96:99], v[194:197], v[234:237], v[96:99]
	v_mfma_f32_16x16x32_bf16 v[84:87], v[186:189], v[242:245], v[84:87]
	v_mfma_f32_16x16x32_bf16 v[80:83], v[194:197], v[242:245], v[80:83]
	v_mfma_f32_16x16x32_bf16 v[108:111], v[198:201], v[214:217], v[108:111]
	v_mfma_f32_16x16x32_bf16 v[104:107], v[206:209], v[214:217], v[104:107]
	v_mfma_f32_16x16x32_bf16 v[92:95], v[198:201], v[222:225], v[92:95]
	v_mfma_f32_16x16x32_bf16 v[88:91], v[206:209], v[222:225], v[88:91]
	v_mfma_f32_16x16x32_bf16 v[76:79], v[198:201], v[230:233], v[76:79]
	v_mfma_f32_16x16x32_bf16 v[72:75], v[206:209], v[230:233], v[72:75]
	v_mfma_f32_16x16x32_bf16 v[68:71], v[198:201], v[238:241], v[68:71]
	v_mfma_f32_16x16x32_bf16 v[64:67], v[206:209], v[238:241], v[64:67]
	v_mfma_f32_16x16x32_bf16 v[108:111], v[202:205], v[218:221], v[108:111]
	v_mfma_f32_16x16x32_bf16 v[104:107], v[210:213], v[218:221], v[104:107]
	v_mfma_f32_16x16x32_bf16 v[92:95], v[202:205], v[226:229], v[92:95]
	v_mfma_f32_16x16x32_bf16 v[88:91], v[210:213], v[226:229], v[88:91]
	v_mfma_f32_16x16x32_bf16 v[76:79], v[202:205], v[234:237], v[76:79]
	v_mfma_f32_16x16x32_bf16 v[72:75], v[210:213], v[234:237], v[72:75]
	v_mfma_f32_16x16x32_bf16 v[68:71], v[202:205], v[242:245], v[68:71]
	v_mfma_f32_16x16x32_bf16 v[64:67], v[210:213], v[242:245], v[64:67]
	s_barrier
	s_add_i32 s21, s34, s3
	s_mov_b32 m0, s21
	ds_read_b128 v[214:217], v155 offset:49152
	ds_read_b128 v[218:221], v155 offset:50176
	ds_read_b128 v[222:225], v155 offset:51200
	ds_read_b128 v[226:229], v155 offset:52224
	ds_read_b128 v[230:233], v155 offset:53248
	ds_read_b128 v[234:237], v155 offset:54272
	ds_read_b128 v[238:241], v155 offset:55296
	ds_read_b128 v[242:245], v155 offset:56320
	global_load_lds_dwordx4 v130, s[60:61]
	s_add_i32 m0, s21, 0x2000
	s_add_u32 s42, s42, 0x40080
	s_addc_u32 s43, s43, 0
	s_add_i32 s21, s35, s3
	global_load_lds_dwordx4 v142, s[60:61]
	s_mov_b32 m0, s21
	s_nop 0
	global_load_lds_dwordx4 v130, s[42:43]
	s_add_i32 m0, s21, 0x2000
	s_nop 0
	global_load_lds_dwordx4 v142, s[42:43]
	s_mov_b32 m0, s0
	s_nop 0
	global_load_lds_dwordx4 v146, s[62:63]
	s_mov_b32 m0, s1
	s_nop 0
	global_load_lds_dwordx4 v144, s[62:63]
	s_waitcnt vmcnt(8)
	s_waitcnt lgkmcnt(0)
	s_barrier
	v_mfma_f32_16x16x32_bf16 v[60:63], v[182:185], v[214:217], v[60:63]
	v_mfma_f32_16x16x32_bf16 v[56:59], v[190:193], v[214:217], v[56:59]
	v_mfma_f32_16x16x32_bf16 v[52:55], v[182:185], v[222:225], v[52:55]
	v_mfma_f32_16x16x32_bf16 v[48:51], v[190:193], v[222:225], v[48:51]
	v_mfma_f32_16x16x32_bf16 v[36:39], v[182:185], v[230:233], v[36:39]
	v_mfma_f32_16x16x32_bf16 v[32:35], v[190:193], v[230:233], v[32:35]
	v_mfma_f32_16x16x32_bf16 v[20:23], v[182:185], v[238:241], v[20:23]
	v_mfma_f32_16x16x32_bf16 v[16:19], v[190:193], v[238:241], v[16:19]
	v_mfma_f32_16x16x32_bf16 v[60:63], v[186:189], v[218:221], v[60:63]
	v_mfma_f32_16x16x32_bf16 v[56:59], v[194:197], v[218:221], v[56:59]
	v_mfma_f32_16x16x32_bf16 v[52:55], v[186:189], v[226:229], v[52:55]
	v_mfma_f32_16x16x32_bf16 v[48:51], v[194:197], v[226:229], v[48:51]
	v_mfma_f32_16x16x32_bf16 v[36:39], v[186:189], v[234:237], v[36:39]
	v_mfma_f32_16x16x32_bf16 v[32:35], v[194:197], v[234:237], v[32:35]
	v_mfma_f32_16x16x32_bf16 v[20:23], v[186:189], v[242:245], v[20:23]
	v_mfma_f32_16x16x32_bf16 v[16:19], v[194:197], v[242:245], v[16:19]
	v_mfma_f32_16x16x32_bf16 v[44:47], v[198:201], v[214:217], v[44:47]
	v_mfma_f32_16x16x32_bf16 v[40:43], v[206:209], v[214:217], v[40:43]
	v_mfma_f32_16x16x32_bf16 v[28:31], v[198:201], v[222:225], v[28:31]
	v_mfma_f32_16x16x32_bf16 v[24:27], v[206:209], v[222:225], v[24:27]
	v_mfma_f32_16x16x32_bf16 v[12:15], v[198:201], v[230:233], v[12:15]
	v_mfma_f32_16x16x32_bf16 v[8:11], v[206:209], v[230:233], v[8:11]
	v_mfma_f32_16x16x32_bf16 v[4:7], v[198:201], v[238:241], v[4:7]
	v_mfma_f32_16x16x32_bf16 v[0:3], v[206:209], v[238:241], v[0:3]
	v_mfma_f32_16x16x32_bf16 v[44:47], v[202:205], v[218:221], v[44:47]
	v_mfma_f32_16x16x32_bf16 v[40:43], v[210:213], v[218:221], v[40:43]
	v_mfma_f32_16x16x32_bf16 v[28:31], v[202:205], v[226:229], v[28:31]
	v_mfma_f32_16x16x32_bf16 v[24:27], v[210:213], v[226:229], v[24:27]
	v_mfma_f32_16x16x32_bf16 v[12:15], v[202:205], v[234:237], v[12:15]
	v_mfma_f32_16x16x32_bf16 v[8:11], v[210:213], v[234:237], v[8:11]
	v_mfma_f32_16x16x32_bf16 v[4:7], v[202:205], v[242:245], v[4:7]
	v_mfma_f32_16x16x32_bf16 v[0:3], v[210:213], v[242:245], v[0:3]
	s_barrier
	s_add_i32 s46, s46, 2
	s_add_u32 s40, s40, 0x100
	s_addc_u32 s41, s41, 0
	s_add_u32 s38, s38, 0x100
	s_addc_u32 s39, s39, 0
	s_cmp_gt_u32 s46, 13
	s_cbranch_scc1 .Lpeel_done_511
.LBB0_511:
	v_add_u32_e32 v156, s22, v153
	ds_read_b128 v[182:185], v156
	ds_read_b128 v[186:189], v156 offset:1024
	ds_read_b128 v[190:193], v156 offset:2048
	ds_read_b128 v[194:197], v156 offset:3072
	v_add_u32_e32 v156, s23, v153
	ds_read_b128 v[198:201], v156
	ds_read_b128 v[202:205], v156 offset:1024
	ds_read_b128 v[206:209], v156 offset:2048
	ds_read_b128 v[210:213], v156 offset:3072
	s_add_u32 s21, s40, 0xfffc0080
	s_addc_u32 s24, s41, -1
	s_cmp_eq_u32 s46, 12
	s_cselect_b32 s45, s17, s24
	s_cselect_b32 s44, s18, s21
	s_cselect_b32 s43, s11, s39
	s_cselect_b32 s42, s19, s38
	s_add_i32 m0, s12, 0xc000
	ds_read_b128 v[214:217], v155
	ds_read_b128 v[218:221], v155 offset:1024
	ds_read_b128 v[222:225], v155 offset:2048
	ds_read_b128 v[226:229], v155 offset:3072
	ds_read_b128 v[230:233], v155 offset:4096
	ds_read_b128 v[234:237], v155 offset:5120
	ds_read_b128 v[238:241], v155 offset:6144
	ds_read_b128 v[242:245], v155 offset:7168
	global_load_lds_dwordx4 v148, s[40:41]
	s_add_i32 m0, s12, 0xe000
	s_nop 0
	global_load_lds_dwordx4 v150, s[40:41]
	s_waitcnt vmcnt(8)
	s_waitcnt lgkmcnt(0)
	s_barrier
	v_mfma_f32_16x16x32_bf16 v[124:127], v[182:185], v[214:217], v[124:127]
	v_mfma_f32_16x16x32_bf16 v[120:123], v[190:193], v[214:217], v[120:123]
	v_mfma_f32_16x16x32_bf16 v[116:119], v[182:185], v[222:225], v[116:119]
	v_mfma_f32_16x16x32_bf16 v[112:115], v[190:193], v[222:225], v[112:115]
	v_mfma_f32_16x16x32_bf16 v[100:103], v[182:185], v[230:233], v[100:103]
	v_mfma_f32_16x16x32_bf16 v[96:99], v[190:193], v[230:233], v[96:99]
	v_mfma_f32_16x16x32_bf16 v[84:87], v[182:185], v[238:241], v[84:87]
	v_mfma_f32_16x16x32_bf16 v[80:83], v[190:193], v[238:241], v[80:83]
	v_mfma_f32_16x16x32_bf16 v[124:127], v[186:189], v[218:221], v[124:127]
	v_mfma_f32_16x16x32_bf16 v[120:123], v[194:197], v[218:221], v[120:123]
	v_mfma_f32_16x16x32_bf16 v[116:119], v[186:189], v[226:229], v[116:119]
	v_mfma_f32_16x16x32_bf16 v[112:115], v[194:197], v[226:229], v[112:115]
	v_mfma_f32_16x16x32_bf16 v[100:103], v[186:189], v[234:237], v[100:103]
	v_mfma_f32_16x16x32_bf16 v[96:99], v[194:197], v[234:237], v[96:99]
	v_mfma_f32_16x16x32_bf16 v[84:87], v[186:189], v[242:245], v[84:87]
	v_mfma_f32_16x16x32_bf16 v[80:83], v[194:197], v[242:245], v[80:83]
	v_mfma_f32_16x16x32_bf16 v[108:111], v[198:201], v[214:217], v[108:111]
	v_mfma_f32_16x16x32_bf16 v[104:107], v[206:209], v[214:217], v[104:107]
	v_mfma_f32_16x16x32_bf16 v[92:95], v[198:201], v[222:225], v[92:95]
	v_mfma_f32_16x16x32_bf16 v[88:91], v[206:209], v[222:225], v[88:91]
	v_mfma_f32_16x16x32_bf16 v[76:79], v[198:201], v[230:233], v[76:79]
	v_mfma_f32_16x16x32_bf16 v[72:75], v[206:209], v[230:233], v[72:75]
	v_mfma_f32_16x16x32_bf16 v[68:71], v[198:201], v[238:241], v[68:71]
	v_mfma_f32_16x16x32_bf16 v[64:67], v[206:209], v[238:241], v[64:67]
	v_mfma_f32_16x16x32_bf16 v[108:111], v[202:205], v[218:221], v[108:111]
	v_mfma_f32_16x16x32_bf16 v[104:107], v[210:213], v[218:221], v[104:107]
	v_mfma_f32_16x16x32_bf16 v[92:95], v[202:205], v[226:229], v[92:95]
	v_mfma_f32_16x16x32_bf16 v[88:91], v[210:213], v[226:229], v[88:91]
	v_mfma_f32_16x16x32_bf16 v[76:79], v[202:205], v[234:237], v[76:79]
	v_mfma_f32_16x16x32_bf16 v[72:75], v[210:213], v[234:237], v[72:75]
	v_mfma_f32_16x16x32_bf16 v[68:71], v[202:205], v[242:245], v[68:71]
	v_mfma_f32_16x16x32_bf16 v[64:67], v[210:213], v[242:245], v[64:67]
	s_barrier
	s_add_u32 s60, s42, 0x80
	s_addc_u32 s61, s43, 0
	s_add_u32 s62, s44, 0x80
	s_addc_u32 s63, s45, 0
	s_add_i32 s21, s22, s3
	s_mov_b32 m0, s21
	ds_read_b128 v[214:217], v155 offset:16384
	ds_read_b128 v[218:221], v155 offset:17408
	ds_read_b128 v[222:225], v155 offset:18432
	ds_read_b128 v[226:229], v155 offset:19456
	ds_read_b128 v[230:233], v155 offset:20480
	ds_read_b128 v[234:237], v155 offset:21504
	ds_read_b128 v[238:241], v155 offset:22528
	ds_read_b128 v[242:245], v155 offset:23552
	global_load_lds_dwordx4 v130, s[42:43]
	s_add_i32 m0, s21, 0x2000
	s_add_u32 s48, s42, 0x40000
	s_addc_u32 s49, s43, 0
	s_add_i32 s21, s23, s3
	global_load_lds_dwordx4 v142, s[42:43]
	s_mov_b32 m0, s21
	s_nop 0
	global_load_lds_dwordx4 v130, s[48:49]
	s_add_i32 m0, s21, 0x2000
	s_nop 0
	global_load_lds_dwordx4 v142, s[48:49]
	s_mov_b32 m0, s12
	s_nop 0
	global_load_lds_dwordx4 v146, s[44:45]
	s_mov_b32 m0, s13
	s_nop 0
	global_load_lds_dwordx4 v144, s[44:45]
	s_waitcnt vmcnt(8)
	s_waitcnt lgkmcnt(0)
	s_barrier
	v_mfma_f32_16x16x32_bf16 v[60:63], v[182:185], v[214:217], v[60:63]
	v_mfma_f32_16x16x32_bf16 v[56:59], v[190:193], v[214:217], v[56:59]
	v_mfma_f32_16x16x32_bf16 v[52:55], v[182:185], v[222:225], v[52:55]
	v_mfma_f32_16x16x32_bf16 v[48:51], v[190:193], v[222:225], v[48:51]
	v_mfma_f32_16x16x32_bf16 v[36:39], v[182:185], v[230:233], v[36:39]
	v_mfma_f32_16x16x32_bf16 v[32:35], v[190:193], v[230:233], v[32:35]
	v_mfma_f32_16x16x32_bf16 v[20:23], v[182:185], v[238:241], v[20:23]
	v_mfma_f32_16x16x32_bf16 v[16:19], v[190:193], v[238:241], v[16:19]
	v_mfma_f32_16x16x32_bf16 v[60:63], v[186:189], v[218:221], v[60:63]
	v_mfma_f32_16x16x32_bf16 v[56:59], v[194:197], v[218:221], v[56:59]
	v_mfma_f32_16x16x32_bf16 v[52:55], v[186:189], v[226:229], v[52:55]
	v_mfma_f32_16x16x32_bf16 v[48:51], v[194:197], v[226:229], v[48:51]
	v_mfma_f32_16x16x32_bf16 v[36:39], v[186:189], v[234:237], v[36:39]
	v_mfma_f32_16x16x32_bf16 v[32:35], v[194:197], v[234:237], v[32:35]
	v_mfma_f32_16x16x32_bf16 v[20:23], v[186:189], v[242:245], v[20:23]
	v_mfma_f32_16x16x32_bf16 v[16:19], v[194:197], v[242:245], v[16:19]
	v_mfma_f32_16x16x32_bf16 v[44:47], v[198:201], v[214:217], v[44:47]
	v_mfma_f32_16x16x32_bf16 v[40:43], v[206:209], v[214:217], v[40:43]
	v_mfma_f32_16x16x32_bf16 v[28:31], v[198:201], v[222:225], v[28:31]
	v_mfma_f32_16x16x32_bf16 v[24:27], v[206:209], v[222:225], v[24:27]
	v_mfma_f32_16x16x32_bf16 v[12:15], v[198:201], v[230:233], v[12:15]
	v_mfma_f32_16x16x32_bf16 v[8:11], v[206:209], v[230:233], v[8:11]
	v_mfma_f32_16x16x32_bf16 v[4:7], v[198:201], v[238:241], v[4:7]
	v_mfma_f32_16x16x32_bf16 v[0:3], v[206:209], v[238:241], v[0:3]
	v_mfma_f32_16x16x32_bf16 v[44:47], v[202:205], v[218:221], v[44:47]
	v_mfma_f32_16x16x32_bf16 v[40:43], v[210:213], v[218:221], v[40:43]
	v_mfma_f32_16x16x32_bf16 v[28:31], v[202:205], v[226:229], v[28:31]
	v_mfma_f32_16x16x32_bf16 v[24:27], v[210:213], v[226:229], v[24:27]
	v_mfma_f32_16x16x32_bf16 v[12:15], v[202:205], v[234:237], v[12:15]
	v_mfma_f32_16x16x32_bf16 v[8:11], v[210:213], v[234:237], v[8:11]
	v_mfma_f32_16x16x32_bf16 v[4:7], v[202:205], v[242:245], v[4:7]
	v_mfma_f32_16x16x32_bf16 v[0:3], v[210:213], v[242:245], v[0:3]
	s_barrier
	v_add_u32_e32 v181, s34, v153
	ds_read_b128 v[182:185], v181
	ds_read_b128 v[186:189], v181 offset:1024
	ds_read_b128 v[190:193], v181 offset:2048
	ds_read_b128 v[194:197], v181 offset:3072
	v_add_u32_e32 v181, s35, v153
	ds_read_b128 v[198:201], v181
	ds_read_b128 v[202:205], v181 offset:1024
	ds_read_b128 v[206:209], v181 offset:2048
	ds_read_b128 v[210:213], v181 offset:3072
	s_add_u32 s44, s44, 0x40000
	s_addc_u32 s45, s45, 0
	s_mov_b32 m0, s20
	ds_read_b128 v[214:217], v155 offset:32768
	ds_read_b128 v[218:221], v155 offset:33792
	ds_read_b128 v[222:225], v155 offset:34816
	ds_read_b128 v[226:229], v155 offset:35840
	ds_read_b128 v[230:233], v155 offset:36864
	ds_read_b128 v[234:237], v155 offset:37888
	ds_read_b128 v[238:241], v155 offset:38912
	ds_read_b128 v[242:245], v155 offset:39936
	global_load_lds_dwordx4 v146, s[44:45]
	s_mov_b32 m0, s26
	s_nop 0
	global_load_lds_dwordx4 v144, s[44:45]
	s_waitcnt vmcnt(8)
	s_waitcnt lgkmcnt(0)
	s_barrier
	v_mfma_f32_16x16x32_bf16 v[124:127], v[182:185], v[214:217], v[124:127]
	v_mfma_f32_16x16x32_bf16 v[120:123], v[190:193], v[214:217], v[120:123]
	v_mfma_f32_16x16x32_bf16 v[116:119], v[182:185], v[222:225], v[116:119]
	v_mfma_f32_16x16x32_bf16 v[112:115], v[190:193], v[222:225], v[112:115]
	v_mfma_f32_16x16x32_bf16 v[100:103], v[182:185], v[230:233], v[100:103]
	v_mfma_f32_16x16x32_bf16 v[96:99], v[190:193], v[230:233], v[96:99]
	v_mfma_f32_16x16x32_bf16 v[84:87], v[182:185], v[238:241], v[84:87]
	v_mfma_f32_16x16x32_bf16 v[80:83], v[190:193], v[238:241], v[80:83]
	v_mfma_f32_16x16x32_bf16 v[124:127], v[186:189], v[218:221], v[124:127]
	v_mfma_f32_16x16x32_bf16 v[120:123], v[194:197], v[218:221], v[120:123]
	v_mfma_f32_16x16x32_bf16 v[116:119], v[186:189], v[226:229], v[116:119]
	v_mfma_f32_16x16x32_bf16 v[112:115], v[194:197], v[226:229], v[112:115]
	v_mfma_f32_16x16x32_bf16 v[100:103], v[186:189], v[234:237], v[100:103]
	v_mfma_f32_16x16x32_bf16 v[96:99], v[194:197], v[234:237], v[96:99]
	v_mfma_f32_16x16x32_bf16 v[84:87], v[186:189], v[242:245], v[84:87]
	v_mfma_f32_16x16x32_bf16 v[80:83], v[194:197], v[242:245], v[80:83]
	v_mfma_f32_16x16x32_bf16 v[108:111], v[198:201], v[214:217], v[108:111]
	v_mfma_f32_16x16x32_bf16 v[104:107], v[206:209], v[214:217], v[104:107]
	v_mfma_f32_16x16x32_bf16 v[92:95], v[198:201], v[222:225], v[92:95]
	v_mfma_f32_16x16x32_bf16 v[88:91], v[206:209], v[222:225], v[88:91]
	v_mfma_f32_16x16x32_bf16 v[76:79], v[198:201], v[230:233], v[76:79]
	v_mfma_f32_16x16x32_bf16 v[72:75], v[206:209], v[230:233], v[72:75]
	v_mfma_f32_16x16x32_bf16 v[68:71], v[198:201], v[238:241], v[68:71]
	v_mfma_f32_16x16x32_bf16 v[64:67], v[206:209], v[238:241], v[64:67]
	v_mfma_f32_16x16x32_bf16 v[108:111], v[202:205], v[218:221], v[108:111]
	v_mfma_f32_16x16x32_bf16 v[104:107], v[210:213], v[218:221], v[104:107]
	v_mfma_f32_16x16x32_bf16 v[92:95], v[202:205], v[226:229], v[92:95]
	v_mfma_f32_16x16x32_bf16 v[88:91], v[210:213], v[226:229], v[88:91]
	v_mfma_f32_16x16x32_bf16 v[76:79], v[202:205], v[234:237], v[76:79]
	v_mfma_f32_16x16x32_bf16 v[72:75], v[210:213], v[234:237], v[72:75]
	v_mfma_f32_16x16x32_bf16 v[68:71], v[202:205], v[242:245], v[68:71]
	v_mfma_f32_16x16x32_bf16 v[64:67], v[210:213], v[242:245], v[64:67]
	s_barrier
	s_add_i32 s21, s34, s3
	s_mov_b32 m0, s21
	ds_read_b128 v[214:217], v155 offset:49152
	ds_read_b128 v[218:221], v155 offset:50176
	ds_read_b128 v[222:225], v155 offset:51200
	ds_read_b128 v[226:229], v155 offset:52224
	ds_read_b128 v[230:233], v155 offset:53248
	ds_read_b128 v[234:237], v155 offset:54272
	ds_read_b128 v[238:241], v155 offset:55296
	ds_read_b128 v[242:245], v155 offset:56320
	global_load_lds_dwordx4 v130, s[60:61]
	s_add_i32 m0, s21, 0x2000
	s_add_u32 s42, s42, 0x40080
	s_addc_u32 s43, s43, 0
	s_add_i32 s21, s35, s3
	global_load_lds_dwordx4 v142, s[60:61]
	s_mov_b32 m0, s21
	s_nop 0
	global_load_lds_dwordx4 v130, s[42:43]
	s_add_i32 m0, s21, 0x2000
	s_nop 0
	global_load_lds_dwordx4 v142, s[42:43]
	s_mov_b32 m0, s0
	s_nop 0
	global_load_lds_dwordx4 v146, s[62:63]
	s_mov_b32 m0, s1
	s_nop 0
	global_load_lds_dwordx4 v144, s[62:63]
	s_waitcnt vmcnt(8)
	s_waitcnt lgkmcnt(0)
	s_barrier
	v_mfma_f32_16x16x32_bf16 v[60:63], v[182:185], v[214:217], v[60:63]
	v_mfma_f32_16x16x32_bf16 v[56:59], v[190:193], v[214:217], v[56:59]
	v_mfma_f32_16x16x32_bf16 v[52:55], v[182:185], v[222:225], v[52:55]
	v_mfma_f32_16x16x32_bf16 v[48:51], v[190:193], v[222:225], v[48:51]
	v_mfma_f32_16x16x32_bf16 v[36:39], v[182:185], v[230:233], v[36:39]
	v_mfma_f32_16x16x32_bf16 v[32:35], v[190:193], v[230:233], v[32:35]
	v_mfma_f32_16x16x32_bf16 v[20:23], v[182:185], v[238:241], v[20:23]
	v_mfma_f32_16x16x32_bf16 v[16:19], v[190:193], v[238:241], v[16:19]
	v_mfma_f32_16x16x32_bf16 v[60:63], v[186:189], v[218:221], v[60:63]
	v_mfma_f32_16x16x32_bf16 v[56:59], v[194:197], v[218:221], v[56:59]
	v_mfma_f32_16x16x32_bf16 v[52:55], v[186:189], v[226:229], v[52:55]
	v_mfma_f32_16x16x32_bf16 v[48:51], v[194:197], v[226:229], v[48:51]
	v_mfma_f32_16x16x32_bf16 v[36:39], v[186:189], v[234:237], v[36:39]
	v_mfma_f32_16x16x32_bf16 v[32:35], v[194:197], v[234:237], v[32:35]
	v_mfma_f32_16x16x32_bf16 v[20:23], v[186:189], v[242:245], v[20:23]
	v_mfma_f32_16x16x32_bf16 v[16:19], v[194:197], v[242:245], v[16:19]
	v_mfma_f32_16x16x32_bf16 v[44:47], v[198:201], v[214:217], v[44:47]
	v_mfma_f32_16x16x32_bf16 v[40:43], v[206:209], v[214:217], v[40:43]
	v_mfma_f32_16x16x32_bf16 v[28:31], v[198:201], v[222:225], v[28:31]
	v_mfma_f32_16x16x32_bf16 v[24:27], v[206:209], v[222:225], v[24:27]
	v_mfma_f32_16x16x32_bf16 v[12:15], v[198:201], v[230:233], v[12:15]
	v_mfma_f32_16x16x32_bf16 v[8:11], v[206:209], v[230:233], v[8:11]
	v_mfma_f32_16x16x32_bf16 v[4:7], v[198:201], v[238:241], v[4:7]
	v_mfma_f32_16x16x32_bf16 v[0:3], v[206:209], v[238:241], v[0:3]
	v_mfma_f32_16x16x32_bf16 v[44:47], v[202:205], v[218:221], v[44:47]
	v_mfma_f32_16x16x32_bf16 v[40:43], v[210:213], v[218:221], v[40:43]
	v_mfma_f32_16x16x32_bf16 v[28:31], v[202:205], v[226:229], v[28:31]
	v_mfma_f32_16x16x32_bf16 v[24:27], v[210:213], v[226:229], v[24:27]
	v_mfma_f32_16x16x32_bf16 v[12:15], v[202:205], v[234:237], v[12:15]
	v_mfma_f32_16x16x32_bf16 v[8:11], v[210:213], v[234:237], v[8:11]
	v_mfma_f32_16x16x32_bf16 v[4:7], v[202:205], v[242:245], v[4:7]
	v_mfma_f32_16x16x32_bf16 v[0:3], v[210:213], v[242:245], v[0:3]
	s_barrier
	s_add_i32 s46, s46, 2
	s_add_u32 s40, s40, 0x100
	s_addc_u32 s41, s41, 0
	s_add_u32 s38, s38, 0x100
	s_addc_u32 s39, s39, 0
	s_cmp_gt_u32 s46, 13
	s_cbranch_scc0 .LBB0_511

.LBB0_854:
	s_add_i32 s11, s48, -2
	s_add_u32 s29, s42, 0x100
	s_addc_u32 s49, s43, 0
	s_mov_b32 s44, 0
	v_add_u32_e32 v156, s22, v153
	ds_read_b128 v[182:185], v156
	ds_read_b128 v[186:189], v156 offset:1024
	ds_read_b128 v[190:193], v156 offset:2048
	ds_read_b128 v[194:197], v156 offset:3072
	v_add_u32_e32 v156, s23, v153
	ds_read_b128 v[198:201], v156
	ds_read_b128 v[202:205], v156 offset:1024
	ds_read_b128 v[206:209], v156 offset:2048
	ds_read_b128 v[210:213], v156 offset:3072
	s_add_i32 s50, s44, 2
	s_add_u32 s42, s40, 0x100
	s_addc_u32 s43, s41, 0
	s_cmp_eq_u32 s11, s44
	s_cselect_b32 s44, s36, s29
	s_cselect_b32 s47, s17, s43
	s_cselect_b32 s46, s16, s42
	s_cselect_b32 s45, s37, s49
	s_add_i32 m0, s12, 0xc000
	ds_read_b128 v[214:217], v155
	ds_read_b128 v[218:221], v155 offset:1024
	ds_read_b128 v[222:225], v155 offset:2048
	ds_read_b128 v[226:229], v155 offset:3072
	ds_read_b128 v[230:233], v155 offset:4096
	ds_read_b128 v[234:237], v155 offset:5120
	ds_read_b128 v[238:241], v155 offset:6144
	ds_read_b128 v[242:245], v155 offset:7168
	global_load_lds_dwordx4 v148, s[40:41]
	s_add_i32 m0, s12, 0xe000
	s_nop 0
	global_load_lds_dwordx4 v150, s[40:41]
	s_waitcnt vmcnt(8)
	s_waitcnt lgkmcnt(0)
	s_barrier
	v_mfma_f32_16x16x32_bf16 v[124:127], v[182:185], v[214:217], 0
	v_mfma_f32_16x16x32_bf16 v[120:123], v[190:193], v[214:217], 0
	v_mfma_f32_16x16x32_bf16 v[116:119], v[182:185], v[222:225], 0
	v_mfma_f32_16x16x32_bf16 v[112:115], v[190:193], v[222:225], 0
	v_mfma_f32_16x16x32_bf16 v[100:103], v[182:185], v[230:233], 0
	v_mfma_f32_16x16x32_bf16 v[96:99], v[190:193], v[230:233], 0
	v_mfma_f32_16x16x32_bf16 v[84:87], v[182:185], v[238:241], 0
	v_mfma_f32_16x16x32_bf16 v[80:83], v[190:193], v[238:241], 0
	v_mfma_f32_16x16x32_bf16 v[124:127], v[186:189], v[218:221], v[124:127]
	v_mfma_f32_16x16x32_bf16 v[120:123], v[194:197], v[218:221], v[120:123]
	v_mfma_f32_16x16x32_bf16 v[116:119], v[186:189], v[226:229], v[116:119]
	v_mfma_f32_16x16x32_bf16 v[112:115], v[194:197], v[226:229], v[112:115]
	v_mfma_f32_16x16x32_bf16 v[100:103], v[186:189], v[234:237], v[100:103]
	v_mfma_f32_16x16x32_bf16 v[96:99], v[194:197], v[234:237], v[96:99]
	v_mfma_f32_16x16x32_bf16 v[84:87], v[186:189], v[242:245], v[84:87]
	v_mfma_f32_16x16x32_bf16 v[80:83], v[194:197], v[242:245], v[80:83]
	v_mfma_f32_16x16x32_bf16 v[108:111], v[198:201], v[214:217], 0
	v_mfma_f32_16x16x32_bf16 v[104:107], v[206:209], v[214:217], 0
	v_mfma_f32_16x16x32_bf16 v[92:95], v[198:201], v[222:225], 0
	v_mfma_f32_16x16x32_bf16 v[88:91], v[206:209], v[222:225], 0
	v_mfma_f32_16x16x32_bf16 v[76:79], v[198:201], v[230:233], 0
	v_mfma_f32_16x16x32_bf16 v[72:75], v[206:209], v[230:233], 0
	v_mfma_f32_16x16x32_bf16 v[68:71], v[198:201], v[238:241], 0
	v_mfma_f32_16x16x32_bf16 v[64:67], v[206:209], v[238:241], 0
	v_mfma_f32_16x16x32_bf16 v[108:111], v[202:205], v[218:221], v[108:111]
	v_mfma_f32_16x16x32_bf16 v[104:107], v[210:213], v[218:221], v[104:107]
	v_mfma_f32_16x16x32_bf16 v[92:95], v[202:205], v[226:229], v[92:95]
	v_mfma_f32_16x16x32_bf16 v[88:91], v[210:213], v[226:229], v[88:91]
	v_mfma_f32_16x16x32_bf16 v[76:79], v[202:205], v[234:237], v[76:79]
	v_mfma_f32_16x16x32_bf16 v[72:75], v[210:213], v[234:237], v[72:75]
	v_mfma_f32_16x16x32_bf16 v[68:71], v[202:205], v[242:245], v[68:71]
	v_mfma_f32_16x16x32_bf16 v[64:67], v[210:213], v[242:245], v[64:67]
	s_barrier
	s_add_u32 s60, s44, 0x80
	s_addc_u32 s61, s45, 0
	s_add_u32 s62, s46, 0x80
	s_addc_u32 s63, s47, 0
	s_add_i32 s21, s22, s3
	s_mov_b32 m0, s21
	ds_read_b128 v[214:217], v155 offset:16384
	ds_read_b128 v[218:221], v155 offset:17408
	ds_read_b128 v[222:225], v155 offset:18432
	ds_read_b128 v[226:229], v155 offset:19456
	ds_read_b128 v[230:233], v155 offset:20480
	ds_read_b128 v[234:237], v155 offset:21504
	ds_read_b128 v[238:241], v155 offset:22528
	ds_read_b128 v[242:245], v155 offset:23552
	global_load_lds_dwordx4 v130, s[44:45]
	s_add_i32 m0, s21, 0x2000
	s_add_u32 s24, s44, 0x40000
	s_addc_u32 s25, s45, 0
	s_add_i32 s21, s23, s3
	global_load_lds_dwordx4 v146, s[44:45]
	s_mov_b32 m0, s21
	s_nop 0
	global_load_lds_dwordx4 v130, s[24:25]
	s_add_i32 m0, s21, 0x2000
	s_nop 0
	global_load_lds_dwordx4 v146, s[24:25]
	s_mov_b32 m0, s12
	s_nop 0
	global_load_lds_dwordx4 v142, s[46:47]
	s_mov_b32 m0, s13
	s_nop 0
	global_load_lds_dwordx4 v144, s[46:47]
	s_waitcnt vmcnt(8)
	s_waitcnt lgkmcnt(0)
	s_barrier
	v_mfma_f32_16x16x32_bf16 v[60:63], v[182:185], v[214:217], 0
	v_mfma_f32_16x16x32_bf16 v[56:59], v[190:193], v[214:217], 0
	v_mfma_f32_16x16x32_bf16 v[52:55], v[182:185], v[222:225], 0
	v_mfma_f32_16x16x32_bf16 v[48:51], v[190:193], v[222:225], 0
	v_mfma_f32_16x16x32_bf16 v[36:39], v[182:185], v[230:233], 0
	v_mfma_f32_16x16x32_bf16 v[32:35], v[190:193], v[230:233], 0
	v_mfma_f32_16x16x32_bf16 v[20:23], v[182:185], v[238:241], 0
	v_mfma_f32_16x16x32_bf16 v[16:19], v[190:193], v[238:241], 0
	v_mfma_f32_16x16x32_bf16 v[60:63], v[186:189], v[218:221], v[60:63]
	v_mfma_f32_16x16x32_bf16 v[56:59], v[194:197], v[218:221], v[56:59]
	v_mfma_f32_16x16x32_bf16 v[52:55], v[186:189], v[226:229], v[52:55]
	v_mfma_f32_16x16x32_bf16 v[48:51], v[194:197], v[226:229], v[48:51]
	v_mfma_f32_16x16x32_bf16 v[36:39], v[186:189], v[234:237], v[36:39]
	v_mfma_f32_16x16x32_bf16 v[32:35], v[194:197], v[234:237], v[32:35]
	v_mfma_f32_16x16x32_bf16 v[20:23], v[186:189], v[242:245], v[20:23]
	v_mfma_f32_16x16x32_bf16 v[16:19], v[194:197], v[242:245], v[16:19]
	v_mfma_f32_16x16x32_bf16 v[44:47], v[198:201], v[214:217], 0
	v_mfma_f32_16x16x32_bf16 v[40:43], v[206:209], v[214:217], 0
	v_mfma_f32_16x16x32_bf16 v[28:31], v[198:201], v[222:225], 0
	v_mfma_f32_16x16x32_bf16 v[24:27], v[206:209], v[222:225], 0
	v_mfma_f32_16x16x32_bf16 v[12:15], v[198:201], v[230:233], 0
	v_mfma_f32_16x16x32_bf16 v[8:11], v[206:209], v[230:233], 0
	v_mfma_f32_16x16x32_bf16 v[4:7], v[198:201], v[238:241], 0
	v_mfma_f32_16x16x32_bf16 v[0:3], v[206:209], v[238:241], 0
	v_mfma_f32_16x16x32_bf16 v[44:47], v[202:205], v[218:221], v[44:47]
	v_mfma_f32_16x16x32_bf16 v[40:43], v[210:213], v[218:221], v[40:43]
	v_mfma_f32_16x16x32_bf16 v[28:31], v[202:205], v[226:229], v[28:31]
	v_mfma_f32_16x16x32_bf16 v[24:27], v[210:213], v[226:229], v[24:27]
	v_mfma_f32_16x16x32_bf16 v[12:15], v[202:205], v[234:237], v[12:15]
	v_mfma_f32_16x16x32_bf16 v[8:11], v[210:213], v[234:237], v[8:11]
	v_mfma_f32_16x16x32_bf16 v[4:7], v[202:205], v[242:245], v[4:7]
	v_mfma_f32_16x16x32_bf16 v[0:3], v[210:213], v[242:245], v[0:3]
	s_barrier
	v_add_u32_e32 v181, s34, v153
	ds_read_b128 v[182:185], v181
	ds_read_b128 v[186:189], v181 offset:1024
	ds_read_b128 v[190:193], v181 offset:2048
	ds_read_b128 v[194:197], v181 offset:3072
	v_add_u32_e32 v181, s35, v153
	ds_read_b128 v[198:201], v181
	ds_read_b128 v[202:205], v181 offset:1024
	ds_read_b128 v[206:209], v181 offset:2048
	ds_read_b128 v[210:213], v181 offset:3072
	s_add_u32 s24, s46, 0xc0000
	s_addc_u32 s25, s47, 0
	s_mov_b32 m0, s18
	ds_read_b128 v[214:217], v155 offset:32768
	ds_read_b128 v[218:221], v155 offset:33792
	ds_read_b128 v[222:225], v155 offset:34816
	ds_read_b128 v[226:229], v155 offset:35840
	ds_read_b128 v[230:233], v155 offset:36864
	ds_read_b128 v[234:237], v155 offset:37888
	ds_read_b128 v[238:241], v155 offset:38912
	ds_read_b128 v[242:245], v155 offset:39936
	global_load_lds_dwordx4 v142, s[24:25]
	s_mov_b32 m0, s19
	s_nop 0
	global_load_lds_dwordx4 v144, s[24:25]
	s_waitcnt vmcnt(8)
	s_waitcnt lgkmcnt(0)
	s_barrier
	v_mfma_f32_16x16x32_bf16 v[124:127], v[182:185], v[214:217], v[124:127]
	v_mfma_f32_16x16x32_bf16 v[120:123], v[190:193], v[214:217], v[120:123]
	v_mfma_f32_16x16x32_bf16 v[116:119], v[182:185], v[222:225], v[116:119]
	v_mfma_f32_16x16x32_bf16 v[112:115], v[190:193], v[222:225], v[112:115]
	v_mfma_f32_16x16x32_bf16 v[100:103], v[182:185], v[230:233], v[100:103]
	v_mfma_f32_16x16x32_bf16 v[96:99], v[190:193], v[230:233], v[96:99]
	v_mfma_f32_16x16x32_bf16 v[84:87], v[182:185], v[238:241], v[84:87]
	v_mfma_f32_16x16x32_bf16 v[80:83], v[190:193], v[238:241], v[80:83]
	v_mfma_f32_16x16x32_bf16 v[124:127], v[186:189], v[218:221], v[124:127]
	v_mfma_f32_16x16x32_bf16 v[120:123], v[194:197], v[218:221], v[120:123]
	v_mfma_f32_16x16x32_bf16 v[116:119], v[186:189], v[226:229], v[116:119]
	v_mfma_f32_16x16x32_bf16 v[112:115], v[194:197], v[226:229], v[112:115]
	v_mfma_f32_16x16x32_bf16 v[100:103], v[186:189], v[234:237], v[100:103]
	v_mfma_f32_16x16x32_bf16 v[96:99], v[194:197], v[234:237], v[96:99]
	v_mfma_f32_16x16x32_bf16 v[84:87], v[186:189], v[242:245], v[84:87]
	v_mfma_f32_16x16x32_bf16 v[80:83], v[194:197], v[242:245], v[80:83]
	v_mfma_f32_16x16x32_bf16 v[108:111], v[198:201], v[214:217], v[108:111]
	v_mfma_f32_16x16x32_bf16 v[104:107], v[206:209], v[214:217], v[104:107]
	v_mfma_f32_16x16x32_bf16 v[92:95], v[198:201], v[222:225], v[92:95]
	v_mfma_f32_16x16x32_bf16 v[88:91], v[206:209], v[222:225], v[88:91]
	v_mfma_f32_16x16x32_bf16 v[76:79], v[198:201], v[230:233], v[76:79]
	v_mfma_f32_16x16x32_bf16 v[72:75], v[206:209], v[230:233], v[72:75]
	v_mfma_f32_16x16x32_bf16 v[68:71], v[198:201], v[238:241], v[68:71]
	v_mfma_f32_16x16x32_bf16 v[64:67], v[206:209], v[238:241], v[64:67]
	v_mfma_f32_16x16x32_bf16 v[108:111], v[202:205], v[218:221], v[108:111]
	v_mfma_f32_16x16x32_bf16 v[104:107], v[210:213], v[218:221], v[104:107]
	v_mfma_f32_16x16x32_bf16 v[92:95], v[202:205], v[226:229], v[92:95]
	v_mfma_f32_16x16x32_bf16 v[88:91], v[210:213], v[226:229], v[88:91]
	v_mfma_f32_16x16x32_bf16 v[76:79], v[202:205], v[234:237], v[76:79]
	v_mfma_f32_16x16x32_bf16 v[72:75], v[210:213], v[234:237], v[72:75]
	v_mfma_f32_16x16x32_bf16 v[68:71], v[202:205], v[242:245], v[68:71]
	v_mfma_f32_16x16x32_bf16 v[64:67], v[210:213], v[242:245], v[64:67]
	s_barrier
	s_add_i32 s21, s34, s3
	s_mov_b32 m0, s21
	ds_read_b128 v[214:217], v155 offset:49152
	ds_read_b128 v[218:221], v155 offset:50176
	ds_read_b128 v[222:225], v155 offset:51200
	ds_read_b128 v[226:229], v155 offset:52224
	ds_read_b128 v[230:233], v155 offset:53248
	ds_read_b128 v[234:237], v155 offset:54272
	ds_read_b128 v[238:241], v155 offset:55296
	ds_read_b128 v[242:245], v155 offset:56320
	global_load_lds_dwordx4 v130, s[60:61]
	s_add_i32 m0, s21, 0x2000
	s_add_u32 s24, s44, 0x40080
	s_addc_u32 s25, s45, 0
	s_add_i32 s21, s35, s3
	global_load_lds_dwordx4 v146, s[60:61]
	s_mov_b32 m0, s21
	s_nop 0
	global_load_lds_dwordx4 v130, s[24:25]
	s_add_i32 m0, s21, 0x2000
	s_nop 0
	global_load_lds_dwordx4 v146, s[24:25]
	s_mov_b32 m0, s20
	s_nop 0
	global_load_lds_dwordx4 v142, s[62:63]
	s_mov_b32 m0, s26
	s_nop 0
	global_load_lds_dwordx4 v144, s[62:63]
	s_waitcnt vmcnt(8)
	s_waitcnt lgkmcnt(0)
	s_barrier
	v_mfma_f32_16x16x32_bf16 v[60:63], v[182:185], v[214:217], v[60:63]
	v_mfma_f32_16x16x32_bf16 v[56:59], v[190:193], v[214:217], v[56:59]
	v_mfma_f32_16x16x32_bf16 v[52:55], v[182:185], v[222:225], v[52:55]
	v_mfma_f32_16x16x32_bf16 v[48:51], v[190:193], v[222:225], v[48:51]
	v_mfma_f32_16x16x32_bf16 v[36:39], v[182:185], v[230:233], v[36:39]
	v_mfma_f32_16x16x32_bf16 v[32:35], v[190:193], v[230:233], v[32:35]
	v_mfma_f32_16x16x32_bf16 v[20:23], v[182:185], v[238:241], v[20:23]
	v_mfma_f32_16x16x32_bf16 v[16:19], v[190:193], v[238:241], v[16:19]
	v_mfma_f32_16x16x32_bf16 v[60:63], v[186:189], v[218:221], v[60:63]
	v_mfma_f32_16x16x32_bf16 v[56:59], v[194:197], v[218:221], v[56:59]
	v_mfma_f32_16x16x32_bf16 v[52:55], v[186:189], v[226:229], v[52:55]
	v_mfma_f32_16x16x32_bf16 v[48:51], v[194:197], v[226:229], v[48:51]
	v_mfma_f32_16x16x32_bf16 v[36:39], v[186:189], v[234:237], v[36:39]
	v_mfma_f32_16x16x32_bf16 v[32:35], v[194:197], v[234:237], v[32:35]
	v_mfma_f32_16x16x32_bf16 v[20:23], v[186:189], v[242:245], v[20:23]
	v_mfma_f32_16x16x32_bf16 v[16:19], v[194:197], v[242:245], v[16:19]
	v_mfma_f32_16x16x32_bf16 v[44:47], v[198:201], v[214:217], v[44:47]
	v_mfma_f32_16x16x32_bf16 v[40:43], v[206:209], v[214:217], v[40:43]
	v_mfma_f32_16x16x32_bf16 v[28:31], v[198:201], v[222:225], v[28:31]
	v_mfma_f32_16x16x32_bf16 v[24:27], v[206:209], v[222:225], v[24:27]
	v_mfma_f32_16x16x32_bf16 v[12:15], v[198:201], v[230:233], v[12:15]
	v_mfma_f32_16x16x32_bf16 v[8:11], v[206:209], v[230:233], v[8:11]
	v_mfma_f32_16x16x32_bf16 v[4:7], v[198:201], v[238:241], v[4:7]
	v_mfma_f32_16x16x32_bf16 v[0:3], v[206:209], v[238:241], v[0:3]
	v_mfma_f32_16x16x32_bf16 v[44:47], v[202:205], v[218:221], v[44:47]
	v_mfma_f32_16x16x32_bf16 v[40:43], v[210:213], v[218:221], v[40:43]
	v_mfma_f32_16x16x32_bf16 v[28:31], v[202:205], v[226:229], v[28:31]
	v_mfma_f32_16x16x32_bf16 v[24:27], v[210:213], v[226:229], v[24:27]
	v_mfma_f32_16x16x32_bf16 v[12:15], v[202:205], v[234:237], v[12:15]
	v_mfma_f32_16x16x32_bf16 v[8:11], v[210:213], v[234:237], v[8:11]
	v_mfma_f32_16x16x32_bf16 v[4:7], v[202:205], v[242:245], v[4:7]
	v_mfma_f32_16x16x32_bf16 v[0:3], v[210:213], v[242:245], v[0:3]
	s_barrier
	s_add_u32 s29, s29, 0x100
	s_addc_u32 s49, s49, 0
	s_cmp_ge_i32 s50, s48
	s_mov_b64 s[40:41], s[42:43]
	s_mov_b32 s44, s50
	s_cbranch_scc1 .Lpeel_done_855
.LBB0_855:
	v_add_u32_e32 v156, s22, v153
	ds_read_b128 v[182:185], v156
	ds_read_b128 v[186:189], v156 offset:1024
	ds_read_b128 v[190:193], v156 offset:2048
	ds_read_b128 v[194:197], v156 offset:3072
	v_add_u32_e32 v156, s23, v153
	ds_read_b128 v[198:201], v156
	ds_read_b128 v[202:205], v156 offset:1024
	ds_read_b128 v[206:209], v156 offset:2048
	ds_read_b128 v[210:213], v156 offset:3072
	s_add_i32 s50, s44, 2
	s_add_u32 s42, s40, 0x100
	s_addc_u32 s43, s41, 0
	s_cmp_eq_u32 s11, s44
	s_cselect_b32 s44, s36, s29
	s_cselect_b32 s47, s17, s43
	s_cselect_b32 s46, s16, s42
	s_cselect_b32 s45, s37, s49
	s_add_i32 m0, s12, 0xc000
	ds_read_b128 v[214:217], v155
	ds_read_b128 v[218:221], v155 offset:1024
	ds_read_b128 v[222:225], v155 offset:2048
	ds_read_b128 v[226:229], v155 offset:3072
	ds_read_b128 v[230:233], v155 offset:4096
	ds_read_b128 v[234:237], v155 offset:5120
	ds_read_b128 v[238:241], v155 offset:6144
	ds_read_b128 v[242:245], v155 offset:7168
	global_load_lds_dwordx4 v148, s[40:41]
	s_add_i32 m0, s12, 0xe000
	s_nop 0
	global_load_lds_dwordx4 v150, s[40:41]
	s_waitcnt vmcnt(8)
	s_waitcnt lgkmcnt(0)
	s_barrier
	v_mfma_f32_16x16x32_bf16 v[124:127], v[182:185], v[214:217], v[124:127]
	v_mfma_f32_16x16x32_bf16 v[120:123], v[190:193], v[214:217], v[120:123]
	v_mfma_f32_16x16x32_bf16 v[116:119], v[182:185], v[222:225], v[116:119]
	v_mfma_f32_16x16x32_bf16 v[112:115], v[190:193], v[222:225], v[112:115]
	v_mfma_f32_16x16x32_bf16 v[100:103], v[182:185], v[230:233], v[100:103]
	v_mfma_f32_16x16x32_bf16 v[96:99], v[190:193], v[230:233], v[96:99]
	v_mfma_f32_16x16x32_bf16 v[84:87], v[182:185], v[238:241], v[84:87]
	v_mfma_f32_16x16x32_bf16 v[80:83], v[190:193], v[238:241], v[80:83]
	v_mfma_f32_16x16x32_bf16 v[124:127], v[186:189], v[218:221], v[124:127]
	v_mfma_f32_16x16x32_bf16 v[120:123], v[194:197], v[218:221], v[120:123]
	v_mfma_f32_16x16x32_bf16 v[116:119], v[186:189], v[226:229], v[116:119]
	v_mfma_f32_16x16x32_bf16 v[112:115], v[194:197], v[226:229], v[112:115]
	v_mfma_f32_16x16x32_bf16 v[100:103], v[186:189], v[234:237], v[100:103]
	v_mfma_f32_16x16x32_bf16 v[96:99], v[194:197], v[234:237], v[96:99]
	v_mfma_f32_16x16x32_bf16 v[84:87], v[186:189], v[242:245], v[84:87]
	v_mfma_f32_16x16x32_bf16 v[80:83], v[194:197], v[242:245], v[80:83]
	v_mfma_f32_16x16x32_bf16 v[108:111], v[198:201], v[214:217], v[108:111]
	v_mfma_f32_16x16x32_bf16 v[104:107], v[206:209], v[214:217], v[104:107]
	v_mfma_f32_16x16x32_bf16 v[92:95], v[198:201], v[222:225], v[92:95]
	v_mfma_f32_16x16x32_bf16 v[88:91], v[206:209], v[222:225], v[88:91]
	v_mfma_f32_16x16x32_bf16 v[76:79], v[198:201], v[230:233], v[76:79]
	v_mfma_f32_16x16x32_bf16 v[72:75], v[206:209], v[230:233], v[72:75]
	v_mfma_f32_16x16x32_bf16 v[68:71], v[198:201], v[238:241], v[68:71]
	v_mfma_f32_16x16x32_bf16 v[64:67], v[206:209], v[238:241], v[64:67]
	v_mfma_f32_16x16x32_bf16 v[108:111], v[202:205], v[218:221], v[108:111]
	v_mfma_f32_16x16x32_bf16 v[104:107], v[210:213], v[218:221], v[104:107]
	v_mfma_f32_16x16x32_bf16 v[92:95], v[202:205], v[226:229], v[92:95]
	v_mfma_f32_16x16x32_bf16 v[88:91], v[210:213], v[226:229], v[88:91]
	v_mfma_f32_16x16x32_bf16 v[76:79], v[202:205], v[234:237], v[76:79]
	v_mfma_f32_16x16x32_bf16 v[72:75], v[210:213], v[234:237], v[72:75]
	v_mfma_f32_16x16x32_bf16 v[68:71], v[202:205], v[242:245], v[68:71]
	v_mfma_f32_16x16x32_bf16 v[64:67], v[210:213], v[242:245], v[64:67]
	s_barrier
	s_add_u32 s60, s44, 0x80
	s_addc_u32 s61, s45, 0
	s_add_u32 s62, s46, 0x80
	s_addc_u32 s63, s47, 0
	s_add_i32 s21, s22, s3
	s_mov_b32 m0, s21
	ds_read_b128 v[214:217], v155 offset:16384
	ds_read_b128 v[218:221], v155 offset:17408
	ds_read_b128 v[222:225], v155 offset:18432
	ds_read_b128 v[226:229], v155 offset:19456
	ds_read_b128 v[230:233], v155 offset:20480
	ds_read_b128 v[234:237], v155 offset:21504
	ds_read_b128 v[238:241], v155 offset:22528
	ds_read_b128 v[242:245], v155 offset:23552
	global_load_lds_dwordx4 v130, s[44:45]
	s_add_i32 m0, s21, 0x2000
	s_add_u32 s24, s44, 0x40000
	s_addc_u32 s25, s45, 0
	s_add_i32 s21, s23, s3
	global_load_lds_dwordx4 v146, s[44:45]
	s_mov_b32 m0, s21
	s_nop 0
	global_load_lds_dwordx4 v130, s[24:25]
	s_add_i32 m0, s21, 0x2000
	s_nop 0
	global_load_lds_dwordx4 v146, s[24:25]
	s_mov_b32 m0, s12
	s_nop 0
	global_load_lds_dwordx4 v142, s[46:47]
	s_mov_b32 m0, s13
	s_nop 0
	global_load_lds_dwordx4 v144, s[46:47]
	s_waitcnt vmcnt(8)
	s_waitcnt lgkmcnt(0)
	s_barrier
	v_mfma_f32_16x16x32_bf16 v[60:63], v[182:185], v[214:217], v[60:63]
	v_mfma_f32_16x16x32_bf16 v[56:59], v[190:193], v[214:217], v[56:59]
	v_mfma_f32_16x16x32_bf16 v[52:55], v[182:185], v[222:225], v[52:55]
	v_mfma_f32_16x16x32_bf16 v[48:51], v[190:193], v[222:225], v[48:51]
	v_mfma_f32_16x16x32_bf16 v[36:39], v[182:185], v[230:233], v[36:39]
	v_mfma_f32_16x16x32_bf16 v[32:35], v[190:193], v[230:233], v[32:35]
	v_mfma_f32_16x16x32_bf16 v[20:23], v[182:185], v[238:241], v[20:23]
	v_mfma_f32_16x16x32_bf16 v[16:19], v[190:193], v[238:241], v[16:19]
	v_mfma_f32_16x16x32_bf16 v[60:63], v[186:189], v[218:221], v[60:63]
	v_mfma_f32_16x16x32_bf16 v[56:59], v[194:197], v[218:221], v[56:59]
	v_mfma_f32_16x16x32_bf16 v[52:55], v[186:189], v[226:229], v[52:55]
	v_mfma_f32_16x16x32_bf16 v[48:51], v[194:197], v[226:229], v[48:51]
	v_mfma_f32_16x16x32_bf16 v[36:39], v[186:189], v[234:237], v[36:39]
	v_mfma_f32_16x16x32_bf16 v[32:35], v[194:197], v[234:237], v[32:35]
	v_mfma_f32_16x16x32_bf16 v[20:23], v[186:189], v[242:245], v[20:23]
	v_mfma_f32_16x16x32_bf16 v[16:19], v[194:197], v[242:245], v[16:19]
	v_mfma_f32_16x16x32_bf16 v[44:47], v[198:201], v[214:217], v[44:47]
	v_mfma_f32_16x16x32_bf16 v[40:43], v[206:209], v[214:217], v[40:43]
	v_mfma_f32_16x16x32_bf16 v[28:31], v[198:201], v[222:225], v[28:31]
	v_mfma_f32_16x16x32_bf16 v[24:27], v[206:209], v[222:225], v[24:27]
	v_mfma_f32_16x16x32_bf16 v[12:15], v[198:201], v[230:233], v[12:15]
	v_mfma_f32_16x16x32_bf16 v[8:11], v[206:209], v[230:233], v[8:11]
	v_mfma_f32_16x16x32_bf16 v[4:7], v[198:201], v[238:241], v[4:7]
	v_mfma_f32_16x16x32_bf16 v[0:3], v[206:209], v[238:241], v[0:3]
	v_mfma_f32_16x16x32_bf16 v[44:47], v[202:205], v[218:221], v[44:47]
	v_mfma_f32_16x16x32_bf16 v[40:43], v[210:213], v[218:221], v[40:43]
	v_mfma_f32_16x16x32_bf16 v[28:31], v[202:205], v[226:229], v[28:31]
	v_mfma_f32_16x16x32_bf16 v[24:27], v[210:213], v[226:229], v[24:27]
	v_mfma_f32_16x16x32_bf16 v[12:15], v[202:205], v[234:237], v[12:15]
	v_mfma_f32_16x16x32_bf16 v[8:11], v[210:213], v[234:237], v[8:11]
	v_mfma_f32_16x16x32_bf16 v[4:7], v[202:205], v[242:245], v[4:7]
	v_mfma_f32_16x16x32_bf16 v[0:3], v[210:213], v[242:245], v[0:3]
	s_barrier
	v_add_u32_e32 v181, s34, v153
	ds_read_b128 v[182:185], v181
	ds_read_b128 v[186:189], v181 offset:1024
	ds_read_b128 v[190:193], v181 offset:2048
	ds_read_b128 v[194:197], v181 offset:3072
	v_add_u32_e32 v181, s35, v153
	ds_read_b128 v[198:201], v181
	ds_read_b128 v[202:205], v181 offset:1024
	ds_read_b128 v[206:209], v181 offset:2048
	ds_read_b128 v[210:213], v181 offset:3072
	s_add_u32 s24, s46, 0xc0000
	s_addc_u32 s25, s47, 0
	s_mov_b32 m0, s18
	ds_read_b128 v[214:217], v155 offset:32768
	ds_read_b128 v[218:221], v155 offset:33792
	ds_read_b128 v[222:225], v155 offset:34816
	ds_read_b128 v[226:229], v155 offset:35840
	ds_read_b128 v[230:233], v155 offset:36864
	ds_read_b128 v[234:237], v155 offset:37888
	ds_read_b128 v[238:241], v155 offset:38912
	ds_read_b128 v[242:245], v155 offset:39936
	global_load_lds_dwordx4 v142, s[24:25]
	s_mov_b32 m0, s19
	s_nop 0
	global_load_lds_dwordx4 v144, s[24:25]
	s_waitcnt vmcnt(8)
	s_waitcnt lgkmcnt(0)
	s_barrier
	v_mfma_f32_16x16x32_bf16 v[124:127], v[182:185], v[214:217], v[124:127]
	v_mfma_f32_16x16x32_bf16 v[120:123], v[190:193], v[214:217], v[120:123]
	v_mfma_f32_16x16x32_bf16 v[116:119], v[182:185], v[222:225], v[116:119]
	v_mfma_f32_16x16x32_bf16 v[112:115], v[190:193], v[222:225], v[112:115]
	v_mfma_f32_16x16x32_bf16 v[100:103], v[182:185], v[230:233], v[100:103]
	v_mfma_f32_16x16x32_bf16 v[96:99], v[190:193], v[230:233], v[96:99]
	v_mfma_f32_16x16x32_bf16 v[84:87], v[182:185], v[238:241], v[84:87]
	v_mfma_f32_16x16x32_bf16 v[80:83], v[190:193], v[238:241], v[80:83]
	v_mfma_f32_16x16x32_bf16 v[124:127], v[186:189], v[218:221], v[124:127]
	v_mfma_f32_16x16x32_bf16 v[120:123], v[194:197], v[218:221], v[120:123]
	v_mfma_f32_16x16x32_bf16 v[116:119], v[186:189], v[226:229], v[116:119]
	v_mfma_f32_16x16x32_bf16 v[112:115], v[194:197], v[226:229], v[112:115]
	v_mfma_f32_16x16x32_bf16 v[100:103], v[186:189], v[234:237], v[100:103]
	v_mfma_f32_16x16x32_bf16 v[96:99], v[194:197], v[234:237], v[96:99]
	v_mfma_f32_16x16x32_bf16 v[84:87], v[186:189], v[242:245], v[84:87]
	v_mfma_f32_16x16x32_bf16 v[80:83], v[194:197], v[242:245], v[80:83]
	v_mfma_f32_16x16x32_bf16 v[108:111], v[198:201], v[214:217], v[108:111]
	v_mfma_f32_16x16x32_bf16 v[104:107], v[206:209], v[214:217], v[104:107]
	v_mfma_f32_16x16x32_bf16 v[92:95], v[198:201], v[222:225], v[92:95]
	v_mfma_f32_16x16x32_bf16 v[88:91], v[206:209], v[222:225], v[88:91]
	v_mfma_f32_16x16x32_bf16 v[76:79], v[198:201], v[230:233], v[76:79]
	v_mfma_f32_16x16x32_bf16 v[72:75], v[206:209], v[230:233], v[72:75]
	v_mfma_f32_16x16x32_bf16 v[68:71], v[198:201], v[238:241], v[68:71]
	v_mfma_f32_16x16x32_bf16 v[64:67], v[206:209], v[238:241], v[64:67]
	v_mfma_f32_16x16x32_bf16 v[108:111], v[202:205], v[218:221], v[108:111]
	v_mfma_f32_16x16x32_bf16 v[104:107], v[210:213], v[218:221], v[104:107]
	v_mfma_f32_16x16x32_bf16 v[92:95], v[202:205], v[226:229], v[92:95]
	v_mfma_f32_16x16x32_bf16 v[88:91], v[210:213], v[226:229], v[88:91]
	v_mfma_f32_16x16x32_bf16 v[76:79], v[202:205], v[234:237], v[76:79]
	v_mfma_f32_16x16x32_bf16 v[72:75], v[210:213], v[234:237], v[72:75]
	v_mfma_f32_16x16x32_bf16 v[68:71], v[202:205], v[242:245], v[68:71]
	v_mfma_f32_16x16x32_bf16 v[64:67], v[210:213], v[242:245], v[64:67]
	s_barrier
	s_add_i32 s21, s34, s3
	s_mov_b32 m0, s21
	ds_read_b128 v[214:217], v155 offset:49152
	ds_read_b128 v[218:221], v155 offset:50176
	ds_read_b128 v[222:225], v155 offset:51200
	ds_read_b128 v[226:229], v155 offset:52224
	ds_read_b128 v[230:233], v155 offset:53248
	ds_read_b128 v[234:237], v155 offset:54272
	ds_read_b128 v[238:241], v155 offset:55296
	ds_read_b128 v[242:245], v155 offset:56320
	global_load_lds_dwordx4 v130, s[60:61]
	s_add_i32 m0, s21, 0x2000
	s_add_u32 s24, s44, 0x40080
	s_addc_u32 s25, s45, 0
	s_add_i32 s21, s35, s3
	global_load_lds_dwordx4 v146, s[60:61]
	s_mov_b32 m0, s21
	s_nop 0
	global_load_lds_dwordx4 v130, s[24:25]
	s_add_i32 m0, s21, 0x2000
	s_nop 0
	global_load_lds_dwordx4 v146, s[24:25]
	s_mov_b32 m0, s20
	s_nop 0
	global_load_lds_dwordx4 v142, s[62:63]
	s_mov_b32 m0, s26
	s_nop 0
	global_load_lds_dwordx4 v144, s[62:63]
	s_waitcnt vmcnt(8)
	s_waitcnt lgkmcnt(0)
	s_barrier
	v_mfma_f32_16x16x32_bf16 v[60:63], v[182:185], v[214:217], v[60:63]
	v_mfma_f32_16x16x32_bf16 v[56:59], v[190:193], v[214:217], v[56:59]
	v_mfma_f32_16x16x32_bf16 v[52:55], v[182:185], v[222:225], v[52:55]
	v_mfma_f32_16x16x32_bf16 v[48:51], v[190:193], v[222:225], v[48:51]
	v_mfma_f32_16x16x32_bf16 v[36:39], v[182:185], v[230:233], v[36:39]
	v_mfma_f32_16x16x32_bf16 v[32:35], v[190:193], v[230:233], v[32:35]
	v_mfma_f32_16x16x32_bf16 v[20:23], v[182:185], v[238:241], v[20:23]
	v_mfma_f32_16x16x32_bf16 v[16:19], v[190:193], v[238:241], v[16:19]
	v_mfma_f32_16x16x32_bf16 v[60:63], v[186:189], v[218:221], v[60:63]
	v_mfma_f32_16x16x32_bf16 v[56:59], v[194:197], v[218:221], v[56:59]
	v_mfma_f32_16x16x32_bf16 v[52:55], v[186:189], v[226:229], v[52:55]
	v_mfma_f32_16x16x32_bf16 v[48:51], v[194:197], v[226:229], v[48:51]
	v_mfma_f32_16x16x32_bf16 v[36:39], v[186:189], v[234:237], v[36:39]
	v_mfma_f32_16x16x32_bf16 v[32:35], v[194:197], v[234:237], v[32:35]
	v_mfma_f32_16x16x32_bf16 v[20:23], v[186:189], v[242:245], v[20:23]
	v_mfma_f32_16x16x32_bf16 v[16:19], v[194:197], v[242:245], v[16:19]
	v_mfma_f32_16x16x32_bf16 v[44:47], v[198:201], v[214:217], v[44:47]
	v_mfma_f32_16x16x32_bf16 v[40:43], v[206:209], v[214:217], v[40:43]
	v_mfma_f32_16x16x32_bf16 v[28:31], v[198:201], v[222:225], v[28:31]
	v_mfma_f32_16x16x32_bf16 v[24:27], v[206:209], v[222:225], v[24:27]
	v_mfma_f32_16x16x32_bf16 v[12:15], v[198:201], v[230:233], v[12:15]
	v_mfma_f32_16x16x32_bf16 v[8:11], v[206:209], v[230:233], v[8:11]
	v_mfma_f32_16x16x32_bf16 v[4:7], v[198:201], v[238:241], v[4:7]
	v_mfma_f32_16x16x32_bf16 v[0:3], v[206:209], v[238:241], v[0:3]
	v_mfma_f32_16x16x32_bf16 v[44:47], v[202:205], v[218:221], v[44:47]
	v_mfma_f32_16x16x32_bf16 v[40:43], v[210:213], v[218:221], v[40:43]
	v_mfma_f32_16x16x32_bf16 v[28:31], v[202:205], v[226:229], v[28:31]
	v_mfma_f32_16x16x32_bf16 v[24:27], v[210:213], v[226:229], v[24:27]
	v_mfma_f32_16x16x32_bf16 v[12:15], v[202:205], v[234:237], v[12:15]
	v_mfma_f32_16x16x32_bf16 v[8:11], v[210:213], v[234:237], v[8:11]
	v_mfma_f32_16x16x32_bf16 v[4:7], v[202:205], v[242:245], v[4:7]
	v_mfma_f32_16x16x32_bf16 v[0:3], v[210:213], v[242:245], v[0:3]
	s_barrier
	s_add_u32 s29, s29, 0x100
	s_addc_u32 s49, s49, 0
	s_cmp_ge_i32 s50, s48
	s_mov_b64 s[40:41], s[42:43]
	s_mov_b32 s44, s50
	s_cbranch_scc0 .LBB0_855

.LBB0_871:
	s_ashr_i32 s17, s16, 31
	s_lshl_b64 s[18:19], s[16:17], 19
	v_readlane_b32 s24, v252, 27
	v_readlane_b32 s25, v252, 28
	s_add_u32 s28, s24, s18
	s_addc_u32 s29, s25, s19
	s_and_b64 s[18:19], s[4:5], exec
	s_cselect_b32 s17, s29, s41
	s_cselect_b32 s18, s28, s40
	s_ashr_i32 s11, s10, 31
	s_lshl_b64 s[36:37], s[10:11], 19
	v_readlane_b32 s11, v252, 23
	s_add_u32 s36, s11, s36
	v_readlane_b32 s11, v252, 24
	s_addc_u32 s37, s11, s37
	s_and_b64 s[38:39], s[4:5], exec
	s_cselect_b32 s11, s37, s43
	s_cselect_b32 s19, s36, s42
	s_add_u32 s40, s40, 0x40080
	s_addc_u32 s41, s41, 0
	s_add_u32 s38, s42, 0x100
	s_addc_u32 s39, s43, 0
	s_mov_b32 s46, -2
	v_add_u32_e32 v156, s22, v153
	ds_read_b128 v[182:185], v156
	ds_read_b128 v[186:189], v156 offset:1024
	ds_read_b128 v[190:193], v156 offset:2048
	ds_read_b128 v[194:197], v156 offset:3072
	v_add_u32_e32 v156, s23, v153
	ds_read_b128 v[198:201], v156
	ds_read_b128 v[202:205], v156 offset:1024
	ds_read_b128 v[206:209], v156 offset:2048
	ds_read_b128 v[210:213], v156 offset:3072
	s_add_u32 s21, s40, 0xfffc0080
	s_addc_u32 s24, s41, -1
	s_cmp_eq_u32 s46, 12
	s_cselect_b32 s45, s17, s24
	s_cselect_b32 s44, s18, s21
	s_cselect_b32 s43, s11, s39
	s_cselect_b32 s42, s19, s38
	s_add_i32 m0, s12, 0xc000
	ds_read_b128 v[214:217], v155
	ds_read_b128 v[218:221], v155 offset:1024
	ds_read_b128 v[222:225], v155 offset:2048
	ds_read_b128 v[226:229], v155 offset:3072
	ds_read_b128 v[230:233], v155 offset:4096
	ds_read_b128 v[234:237], v155 offset:5120
	ds_read_b128 v[238:241], v155 offset:6144
	ds_read_b128 v[242:245], v155 offset:7168
	global_load_lds_dwordx4 v148, s[40:41]
	s_add_i32 m0, s12, 0xe000
	s_nop 0
	global_load_lds_dwordx4 v150, s[40:41]
	s_waitcnt vmcnt(8)
	s_waitcnt lgkmcnt(0)
	s_barrier
	v_mfma_f32_16x16x32_bf16 v[124:127], v[182:185], v[214:217], 0
	v_mfma_f32_16x16x32_bf16 v[120:123], v[190:193], v[214:217], 0
	v_mfma_f32_16x16x32_bf16 v[116:119], v[182:185], v[222:225], 0
	v_mfma_f32_16x16x32_bf16 v[112:115], v[190:193], v[222:225], 0
	v_mfma_f32_16x16x32_bf16 v[100:103], v[182:185], v[230:233], 0
	v_mfma_f32_16x16x32_bf16 v[96:99], v[190:193], v[230:233], 0
	v_mfma_f32_16x16x32_bf16 v[84:87], v[182:185], v[238:241], 0
	v_mfma_f32_16x16x32_bf16 v[80:83], v[190:193], v[238:241], 0
	v_mfma_f32_16x16x32_bf16 v[124:127], v[186:189], v[218:221], v[124:127]
	v_mfma_f32_16x16x32_bf16 v[120:123], v[194:197], v[218:221], v[120:123]
	v_mfma_f32_16x16x32_bf16 v[116:119], v[186:189], v[226:229], v[116:119]
	v_mfma_f32_16x16x32_bf16 v[112:115], v[194:197], v[226:229], v[112:115]
	v_mfma_f32_16x16x32_bf16 v[100:103], v[186:189], v[234:237], v[100:103]
	v_mfma_f32_16x16x32_bf16 v[96:99], v[194:197], v[234:237], v[96:99]
	v_mfma_f32_16x16x32_bf16 v[84:87], v[186:189], v[242:245], v[84:87]
	v_mfma_f32_16x16x32_bf16 v[80:83], v[194:197], v[242:245], v[80:83]
	v_mfma_f32_16x16x32_bf16 v[108:111], v[198:201], v[214:217], 0
	v_mfma_f32_16x16x32_bf16 v[104:107], v[206:209], v[214:217], 0
	v_mfma_f32_16x16x32_bf16 v[92:95], v[198:201], v[222:225], 0
	v_mfma_f32_16x16x32_bf16 v[88:91], v[206:209], v[222:225], 0
	v_mfma_f32_16x16x32_bf16 v[76:79], v[198:201], v[230:233], 0
	v_mfma_f32_16x16x32_bf16 v[72:75], v[206:209], v[230:233], 0
	v_mfma_f32_16x16x32_bf16 v[68:71], v[198:201], v[238:241], 0
	v_mfma_f32_16x16x32_bf16 v[64:67], v[206:209], v[238:241], 0
	v_mfma_f32_16x16x32_bf16 v[108:111], v[202:205], v[218:221], v[108:111]
	v_mfma_f32_16x16x32_bf16 v[104:107], v[210:213], v[218:221], v[104:107]
	v_mfma_f32_16x16x32_bf16 v[92:95], v[202:205], v[226:229], v[92:95]
	v_mfma_f32_16x16x32_bf16 v[88:91], v[210:213], v[226:229], v[88:91]
	v_mfma_f32_16x16x32_bf16 v[76:79], v[202:205], v[234:237], v[76:79]
	v_mfma_f32_16x16x32_bf16 v[72:75], v[210:213], v[234:237], v[72:75]
	v_mfma_f32_16x16x32_bf16 v[68:71], v[202:205], v[242:245], v[68:71]
	v_mfma_f32_16x16x32_bf16 v[64:67], v[210:213], v[242:245], v[64:67]
	s_barrier
	s_add_u32 s60, s42, 0x80
	s_addc_u32 s61, s43, 0
	s_add_u32 s62, s44, 0x80
	s_addc_u32 s63, s45, 0
	s_add_i32 s21, s22, s3
	s_mov_b32 m0, s21
	ds_read_b128 v[214:217], v155 offset:16384
	ds_read_b128 v[218:221], v155 offset:17408
	ds_read_b128 v[222:225], v155 offset:18432
	ds_read_b128 v[226:229], v155 offset:19456
	ds_read_b128 v[230:233], v155 offset:20480
	ds_read_b128 v[234:237], v155 offset:21504
	ds_read_b128 v[238:241], v155 offset:22528
	ds_read_b128 v[242:245], v155 offset:23552
	global_load_lds_dwordx4 v130, s[42:43]
	s_add_i32 m0, s21, 0x2000
	s_add_u32 s48, s42, 0x40000
	s_addc_u32 s49, s43, 0
	s_add_i32 s21, s23, s3
	global_load_lds_dwordx4 v142, s[42:43]
	s_mov_b32 m0, s21
	s_nop 0
	global_load_lds_dwordx4 v130, s[48:49]
	s_add_i32 m0, s21, 0x2000
	s_nop 0
	global_load_lds_dwordx4 v142, s[48:49]
	s_mov_b32 m0, s12
	s_nop 0
	global_load_lds_dwordx4 v146, s[44:45]
	s_mov_b32 m0, s13
	s_nop 0
	global_load_lds_dwordx4 v144, s[44:45]
	s_waitcnt vmcnt(8)
	s_waitcnt lgkmcnt(0)
	s_barrier
	v_mfma_f32_16x16x32_bf16 v[60:63], v[182:185], v[214:217], 0
	v_mfma_f32_16x16x32_bf16 v[56:59], v[190:193], v[214:217], 0
	v_mfma_f32_16x16x32_bf16 v[52:55], v[182:185], v[222:225], 0
	v_mfma_f32_16x16x32_bf16 v[48:51], v[190:193], v[222:225], 0
	v_mfma_f32_16x16x32_bf16 v[36:39], v[182:185], v[230:233], 0
	v_mfma_f32_16x16x32_bf16 v[32:35], v[190:193], v[230:233], 0
	v_mfma_f32_16x16x32_bf16 v[20:23], v[182:185], v[238:241], 0
	v_mfma_f32_16x16x32_bf16 v[16:19], v[190:193], v[238:241], 0
	v_mfma_f32_16x16x32_bf16 v[60:63], v[186:189], v[218:221], v[60:63]
	v_mfma_f32_16x16x32_bf16 v[56:59], v[194:197], v[218:221], v[56:59]
	v_mfma_f32_16x16x32_bf16 v[52:55], v[186:189], v[226:229], v[52:55]
	v_mfma_f32_16x16x32_bf16 v[48:51], v[194:197], v[226:229], v[48:51]
	v_mfma_f32_16x16x32_bf16 v[36:39], v[186:189], v[234:237], v[36:39]
	v_mfma_f32_16x16x32_bf16 v[32:35], v[194:197], v[234:237], v[32:35]
	v_mfma_f32_16x16x32_bf16 v[20:23], v[186:189], v[242:245], v[20:23]
	v_mfma_f32_16x16x32_bf16 v[16:19], v[194:197], v[242:245], v[16:19]
	v_mfma_f32_16x16x32_bf16 v[44:47], v[198:201], v[214:217], 0
	v_mfma_f32_16x16x32_bf16 v[40:43], v[206:209], v[214:217], 0
	v_mfma_f32_16x16x32_bf16 v[28:31], v[198:201], v[222:225], 0
	v_mfma_f32_16x16x32_bf16 v[24:27], v[206:209], v[222:225], 0
	v_mfma_f32_16x16x32_bf16 v[12:15], v[198:201], v[230:233], 0
	v_mfma_f32_16x16x32_bf16 v[8:11], v[206:209], v[230:233], 0
	v_mfma_f32_16x16x32_bf16 v[4:7], v[198:201], v[238:241], 0
	v_mfma_f32_16x16x32_bf16 v[0:3], v[206:209], v[238:241], 0
	v_mfma_f32_16x16x32_bf16 v[44:47], v[202:205], v[218:221], v[44:47]
	v_mfma_f32_16x16x32_bf16 v[40:43], v[210:213], v[218:221], v[40:43]
	v_mfma_f32_16x16x32_bf16 v[28:31], v[202:205], v[226:229], v[28:31]
	v_mfma_f32_16x16x32_bf16 v[24:27], v[210:213], v[226:229], v[24:27]
	v_mfma_f32_16x16x32_bf16 v[12:15], v[202:205], v[234:237], v[12:15]
	v_mfma_f32_16x16x32_bf16 v[8:11], v[210:213], v[234:237], v[8:11]
	v_mfma_f32_16x16x32_bf16 v[4:7], v[202:205], v[242:245], v[4:7]
	v_mfma_f32_16x16x32_bf16 v[0:3], v[210:213], v[242:245], v[0:3]
	s_barrier
	v_add_u32_e32 v181, s34, v153
	ds_read_b128 v[182:185], v181
	ds_read_b128 v[186:189], v181 offset:1024
	ds_read_b128 v[190:193], v181 offset:2048
	ds_read_b128 v[194:197], v181 offset:3072
	v_add_u32_e32 v181, s35, v153
	ds_read_b128 v[198:201], v181
	ds_read_b128 v[202:205], v181 offset:1024
	ds_read_b128 v[206:209], v181 offset:2048
	ds_read_b128 v[210:213], v181 offset:3072
	s_add_u32 s44, s44, 0x40000
	s_addc_u32 s45, s45, 0
	s_mov_b32 m0, s20
	ds_read_b128 v[214:217], v155 offset:32768
	ds_read_b128 v[218:221], v155 offset:33792
	ds_read_b128 v[222:225], v155 offset:34816
	ds_read_b128 v[226:229], v155 offset:35840
	ds_read_b128 v[230:233], v155 offset:36864
	ds_read_b128 v[234:237], v155 offset:37888
	ds_read_b128 v[238:241], v155 offset:38912
	ds_read_b128 v[242:245], v155 offset:39936
	global_load_lds_dwordx4 v146, s[44:45]
	s_mov_b32 m0, s26
	s_nop 0
	global_load_lds_dwordx4 v144, s[44:45]
	s_waitcnt vmcnt(8)
	s_waitcnt lgkmcnt(0)
	s_barrier
	v_mfma_f32_16x16x32_bf16 v[124:127], v[182:185], v[214:217], v[124:127]
	v_mfma_f32_16x16x32_bf16 v[120:123], v[190:193], v[214:217], v[120:123]
	v_mfma_f32_16x16x32_bf16 v[116:119], v[182:185], v[222:225], v[116:119]
	v_mfma_f32_16x16x32_bf16 v[112:115], v[190:193], v[222:225], v[112:115]
	v_mfma_f32_16x16x32_bf16 v[100:103], v[182:185], v[230:233], v[100:103]
	v_mfma_f32_16x16x32_bf16 v[96:99], v[190:193], v[230:233], v[96:99]
	v_mfma_f32_16x16x32_bf16 v[84:87], v[182:185], v[238:241], v[84:87]
	v_mfma_f32_16x16x32_bf16 v[80:83], v[190:193], v[238:241], v[80:83]
	v_mfma_f32_16x16x32_bf16 v[124:127], v[186:189], v[218:221], v[124:127]
	v_mfma_f32_16x16x32_bf16 v[120:123], v[194:197], v[218:221], v[120:123]
	v_mfma_f32_16x16x32_bf16 v[116:119], v[186:189], v[226:229], v[116:119]
	v_mfma_f32_16x16x32_bf16 v[112:115], v[194:197], v[226:229], v[112:115]
	v_mfma_f32_16x16x32_bf16 v[100:103], v[186:189], v[234:237], v[100:103]
	v_mfma_f32_16x16x32_bf16 v[96:99], v[194:197], v[234:237], v[96:99]
	v_mfma_f32_16x16x32_bf16 v[84:87], v[186:189], v[242:245], v[84:87]
	v_mfma_f32_16x16x32_bf16 v[80:83], v[194:197], v[242:245], v[80:83]
	v_mfma_f32_16x16x32_bf16 v[108:111], v[198:201], v[214:217], v[108:111]
	v_mfma_f32_16x16x32_bf16 v[104:107], v[206:209], v[214:217], v[104:107]
	v_mfma_f32_16x16x32_bf16 v[92:95], v[198:201], v[222:225], v[92:95]
	v_mfma_f32_16x16x32_bf16 v[88:91], v[206:209], v[222:225], v[88:91]
	v_mfma_f32_16x16x32_bf16 v[76:79], v[198:201], v[230:233], v[76:79]
	v_mfma_f32_16x16x32_bf16 v[72:75], v[206:209], v[230:233], v[72:75]
	v_mfma_f32_16x16x32_bf16 v[68:71], v[198:201], v[238:241], v[68:71]
	v_mfma_f32_16x16x32_bf16 v[64:67], v[206:209], v[238:241], v[64:67]
	v_mfma_f32_16x16x32_bf16 v[108:111], v[202:205], v[218:221], v[108:111]
	v_mfma_f32_16x16x32_bf16 v[104:107], v[210:213], v[218:221], v[104:107]
	v_mfma_f32_16x16x32_bf16 v[92:95], v[202:205], v[226:229], v[92:95]
	v_mfma_f32_16x16x32_bf16 v[88:91], v[210:213], v[226:229], v[88:91]
	v_mfma_f32_16x16x32_bf16 v[76:79], v[202:205], v[234:237], v[76:79]
	v_mfma_f32_16x16x32_bf16 v[72:75], v[210:213], v[234:237], v[72:75]
	v_mfma_f32_16x16x32_bf16 v[68:71], v[202:205], v[242:245], v[68:71]
	v_mfma_f32_16x16x32_bf16 v[64:67], v[210:213], v[242:245], v[64:67]
	s_barrier
	s_add_i32 s21, s34, s3
	s_mov_b32 m0, s21
	ds_read_b128 v[214:217], v155 offset:49152
	ds_read_b128 v[218:221], v155 offset:50176
	ds_read_b128 v[222:225], v155 offset:51200
	ds_read_b128 v[226:229], v155 offset:52224
	ds_read_b128 v[230:233], v155 offset:53248
	ds_read_b128 v[234:237], v155 offset:54272
	ds_read_b128 v[238:241], v155 offset:55296
	ds_read_b128 v[242:245], v155 offset:56320
	global_load_lds_dwordx4 v130, s[60:61]
	s_add_i32 m0, s21, 0x2000
	s_add_u32 s42, s42, 0x40080
	s_addc_u32 s43, s43, 0
	s_add_i32 s21, s35, s3
	global_load_lds_dwordx4 v142, s[60:61]
	s_mov_b32 m0, s21
	s_nop 0
	global_load_lds_dwordx4 v130, s[42:43]
	s_add_i32 m0, s21, 0x2000
	s_nop 0
	global_load_lds_dwordx4 v142, s[42:43]
	s_mov_b32 m0, s0
	s_nop 0
	global_load_lds_dwordx4 v146, s[62:63]
	s_mov_b32 m0, s1
	s_nop 0
	global_load_lds_dwordx4 v144, s[62:63]
	s_waitcnt vmcnt(8)
	s_waitcnt lgkmcnt(0)
	s_barrier
	v_mfma_f32_16x16x32_bf16 v[60:63], v[182:185], v[214:217], v[60:63]
	v_mfma_f32_16x16x32_bf16 v[56:59], v[190:193], v[214:217], v[56:59]
	v_mfma_f32_16x16x32_bf16 v[52:55], v[182:185], v[222:225], v[52:55]
	v_mfma_f32_16x16x32_bf16 v[48:51], v[190:193], v[222:225], v[48:51]
	v_mfma_f32_16x16x32_bf16 v[36:39], v[182:185], v[230:233], v[36:39]
	v_mfma_f32_16x16x32_bf16 v[32:35], v[190:193], v[230:233], v[32:35]
	v_mfma_f32_16x16x32_bf16 v[20:23], v[182:185], v[238:241], v[20:23]
	v_mfma_f32_16x16x32_bf16 v[16:19], v[190:193], v[238:241], v[16:19]
	v_mfma_f32_16x16x32_bf16 v[60:63], v[186:189], v[218:221], v[60:63]
	v_mfma_f32_16x16x32_bf16 v[56:59], v[194:197], v[218:221], v[56:59]
	v_mfma_f32_16x16x32_bf16 v[52:55], v[186:189], v[226:229], v[52:55]
	v_mfma_f32_16x16x32_bf16 v[48:51], v[194:197], v[226:229], v[48:51]
	v_mfma_f32_16x16x32_bf16 v[36:39], v[186:189], v[234:237], v[36:39]
	v_mfma_f32_16x16x32_bf16 v[32:35], v[194:197], v[234:237], v[32:35]
	v_mfma_f32_16x16x32_bf16 v[20:23], v[186:189], v[242:245], v[20:23]
	v_mfma_f32_16x16x32_bf16 v[16:19], v[194:197], v[242:245], v[16:19]
	v_mfma_f32_16x16x32_bf16 v[44:47], v[198:201], v[214:217], v[44:47]
	v_mfma_f32_16x16x32_bf16 v[40:43], v[206:209], v[214:217], v[40:43]
	v_mfma_f32_16x16x32_bf16 v[28:31], v[198:201], v[222:225], v[28:31]
	v_mfma_f32_16x16x32_bf16 v[24:27], v[206:209], v[222:225], v[24:27]
	v_mfma_f32_16x16x32_bf16 v[12:15], v[198:201], v[230:233], v[12:15]
	v_mfma_f32_16x16x32_bf16 v[8:11], v[206:209], v[230:233], v[8:11]
	v_mfma_f32_16x16x32_bf16 v[4:7], v[198:201], v[238:241], v[4:7]
	v_mfma_f32_16x16x32_bf16 v[0:3], v[206:209], v[238:241], v[0:3]
	v_mfma_f32_16x16x32_bf16 v[44:47], v[202:205], v[218:221], v[44:47]
	v_mfma_f32_16x16x32_bf16 v[40:43], v[210:213], v[218:221], v[40:43]
	v_mfma_f32_16x16x32_bf16 v[28:31], v[202:205], v[226:229], v[28:31]
	v_mfma_f32_16x16x32_bf16 v[24:27], v[210:213], v[226:229], v[24:27]
	v_mfma_f32_16x16x32_bf16 v[12:15], v[202:205], v[234:237], v[12:15]
	v_mfma_f32_16x16x32_bf16 v[8:11], v[210:213], v[234:237], v[8:11]
	v_mfma_f32_16x16x32_bf16 v[4:7], v[202:205], v[242:245], v[4:7]
	v_mfma_f32_16x16x32_bf16 v[0:3], v[210:213], v[242:245], v[0:3]
	s_barrier
	s_add_i32 s46, s46, 2
	s_add_u32 s40, s40, 0x100
	s_addc_u32 s41, s41, 0
	s_add_u32 s38, s38, 0x100
	s_addc_u32 s39, s39, 0
	s_cmp_gt_u32 s46, 13
	s_cbranch_scc1 .Lpeel_done_872

.LBB0_1271:
	s_add_i32 s11, s48, -2
	s_add_u32 s29, s42, 0x100
	s_addc_u32 s49, s43, 0
	s_mov_b32 s44, 0
	v_add_u32_e32 v156, s22, v153
	ds_read_b128 v[182:185], v156
	ds_read_b128 v[186:189], v156 offset:1024
	ds_read_b128 v[190:193], v156 offset:2048
	ds_read_b128 v[194:197], v156 offset:3072
	v_add_u32_e32 v156, s23, v153
	ds_read_b128 v[198:201], v156
	ds_read_b128 v[202:205], v156 offset:1024
	ds_read_b128 v[206:209], v156 offset:2048
	ds_read_b128 v[210:213], v156 offset:3072
	s_add_i32 s50, s44, 2
	s_add_u32 s42, s40, 0x100
	s_addc_u32 s43, s41, 0
	s_cmp_eq_u32 s11, s44
	s_cselect_b32 s44, s36, s29
	s_cselect_b32 s47, s17, s43
	s_cselect_b32 s46, s16, s42
	s_cselect_b32 s45, s37, s49
	s_add_i32 m0, s12, 0xc000
	ds_read_b128 v[214:217], v155
	ds_read_b128 v[218:221], v155 offset:1024
	ds_read_b128 v[222:225], v155 offset:2048
	ds_read_b128 v[226:229], v155 offset:3072
	ds_read_b128 v[230:233], v155 offset:4096
	ds_read_b128 v[234:237], v155 offset:5120
	ds_read_b128 v[238:241], v155 offset:6144
	ds_read_b128 v[242:245], v155 offset:7168
	global_load_lds_dwordx4 v148, s[40:41]
	s_add_i32 m0, s12, 0xe000
	s_nop 0
	global_load_lds_dwordx4 v150, s[40:41]
	s_waitcnt vmcnt(8)
	s_waitcnt lgkmcnt(0)
	s_barrier
	v_mfma_f32_16x16x32_bf16 v[124:127], v[182:185], v[214:217], 0
	v_mfma_f32_16x16x32_bf16 v[120:123], v[190:193], v[214:217], 0
	v_mfma_f32_16x16x32_bf16 v[116:119], v[182:185], v[222:225], 0
	v_mfma_f32_16x16x32_bf16 v[112:115], v[190:193], v[222:225], 0
	v_mfma_f32_16x16x32_bf16 v[100:103], v[182:185], v[230:233], 0
	v_mfma_f32_16x16x32_bf16 v[96:99], v[190:193], v[230:233], 0
	v_mfma_f32_16x16x32_bf16 v[84:87], v[182:185], v[238:241], 0
	v_mfma_f32_16x16x32_bf16 v[80:83], v[190:193], v[238:241], 0
	v_mfma_f32_16x16x32_bf16 v[124:127], v[186:189], v[218:221], v[124:127]
	v_mfma_f32_16x16x32_bf16 v[120:123], v[194:197], v[218:221], v[120:123]
	v_mfma_f32_16x16x32_bf16 v[116:119], v[186:189], v[226:229], v[116:119]
	v_mfma_f32_16x16x32_bf16 v[112:115], v[194:197], v[226:229], v[112:115]
	v_mfma_f32_16x16x32_bf16 v[100:103], v[186:189], v[234:237], v[100:103]
	v_mfma_f32_16x16x32_bf16 v[96:99], v[194:197], v[234:237], v[96:99]
	v_mfma_f32_16x16x32_bf16 v[84:87], v[186:189], v[242:245], v[84:87]
	v_mfma_f32_16x16x32_bf16 v[80:83], v[194:197], v[242:245], v[80:83]
	v_mfma_f32_16x16x32_bf16 v[108:111], v[198:201], v[214:217], 0
	v_mfma_f32_16x16x32_bf16 v[104:107], v[206:209], v[214:217], 0
	v_mfma_f32_16x16x32_bf16 v[92:95], v[198:201], v[222:225], 0
	v_mfma_f32_16x16x32_bf16 v[88:91], v[206:209], v[222:225], 0
	v_mfma_f32_16x16x32_bf16 v[76:79], v[198:201], v[230:233], 0
	v_mfma_f32_16x16x32_bf16 v[72:75], v[206:209], v[230:233], 0
	v_mfma_f32_16x16x32_bf16 v[68:71], v[198:201], v[238:241], 0
	v_mfma_f32_16x16x32_bf16 v[64:67], v[206:209], v[238:241], 0
	v_mfma_f32_16x16x32_bf16 v[108:111], v[202:205], v[218:221], v[108:111]
	v_mfma_f32_16x16x32_bf16 v[104:107], v[210:213], v[218:221], v[104:107]
	v_mfma_f32_16x16x32_bf16 v[92:95], v[202:205], v[226:229], v[92:95]
	v_mfma_f32_16x16x32_bf16 v[88:91], v[210:213], v[226:229], v[88:91]
	v_mfma_f32_16x16x32_bf16 v[76:79], v[202:205], v[234:237], v[76:79]
	v_mfma_f32_16x16x32_bf16 v[72:75], v[210:213], v[234:237], v[72:75]
	v_mfma_f32_16x16x32_bf16 v[68:71], v[202:205], v[242:245], v[68:71]
	v_mfma_f32_16x16x32_bf16 v[64:67], v[210:213], v[242:245], v[64:67]
	s_barrier
	s_add_u32 s60, s44, 0x80
	s_addc_u32 s61, s45, 0
	s_add_u32 s62, s46, 0x80
	s_addc_u32 s63, s47, 0
	s_add_i32 s21, s22, s3
	s_mov_b32 m0, s21
	ds_read_b128 v[214:217], v155 offset:16384
	ds_read_b128 v[218:221], v155 offset:17408
	ds_read_b128 v[222:225], v155 offset:18432
	ds_read_b128 v[226:229], v155 offset:19456
	ds_read_b128 v[230:233], v155 offset:20480
	ds_read_b128 v[234:237], v155 offset:21504
	ds_read_b128 v[238:241], v155 offset:22528
	ds_read_b128 v[242:245], v155 offset:23552
	global_load_lds_dwordx4 v130, s[44:45]
	s_add_i32 m0, s21, 0x2000
	s_add_u32 s40, s44, 0x40000
	s_addc_u32 s41, s45, 0
	s_add_i32 s21, s23, s3
	global_load_lds_dwordx4 v146, s[44:45]
	s_mov_b32 m0, s21
	s_nop 0
	global_load_lds_dwordx4 v130, s[40:41]
	s_add_i32 m0, s21, 0x2000
	s_nop 0
	global_load_lds_dwordx4 v146, s[40:41]
	s_mov_b32 m0, s12
	s_nop 0
	global_load_lds_dwordx4 v142, s[46:47]
	s_mov_b32 m0, s13
	s_nop 0
	global_load_lds_dwordx4 v144, s[46:47]
	s_waitcnt vmcnt(8)
	s_waitcnt lgkmcnt(0)
	s_barrier
	v_mfma_f32_16x16x32_bf16 v[60:63], v[182:185], v[214:217], 0
	v_mfma_f32_16x16x32_bf16 v[56:59], v[190:193], v[214:217], 0
	v_mfma_f32_16x16x32_bf16 v[52:55], v[182:185], v[222:225], 0
	v_mfma_f32_16x16x32_bf16 v[48:51], v[190:193], v[222:225], 0
	v_mfma_f32_16x16x32_bf16 v[36:39], v[182:185], v[230:233], 0
	v_mfma_f32_16x16x32_bf16 v[32:35], v[190:193], v[230:233], 0
	v_mfma_f32_16x16x32_bf16 v[20:23], v[182:185], v[238:241], 0
	v_mfma_f32_16x16x32_bf16 v[16:19], v[190:193], v[238:241], 0
	v_mfma_f32_16x16x32_bf16 v[60:63], v[186:189], v[218:221], v[60:63]
	v_mfma_f32_16x16x32_bf16 v[56:59], v[194:197], v[218:221], v[56:59]
	v_mfma_f32_16x16x32_bf16 v[52:55], v[186:189], v[226:229], v[52:55]
	v_mfma_f32_16x16x32_bf16 v[48:51], v[194:197], v[226:229], v[48:51]
	v_mfma_f32_16x16x32_bf16 v[36:39], v[186:189], v[234:237], v[36:39]
	v_mfma_f32_16x16x32_bf16 v[32:35], v[194:197], v[234:237], v[32:35]
	v_mfma_f32_16x16x32_bf16 v[20:23], v[186:189], v[242:245], v[20:23]
	v_mfma_f32_16x16x32_bf16 v[16:19], v[194:197], v[242:245], v[16:19]
	v_mfma_f32_16x16x32_bf16 v[44:47], v[198:201], v[214:217], 0
	v_mfma_f32_16x16x32_bf16 v[40:43], v[206:209], v[214:217], 0
	v_mfma_f32_16x16x32_bf16 v[28:31], v[198:201], v[222:225], 0
	v_mfma_f32_16x16x32_bf16 v[24:27], v[206:209], v[222:225], 0
	v_mfma_f32_16x16x32_bf16 v[12:15], v[198:201], v[230:233], 0
	v_mfma_f32_16x16x32_bf16 v[8:11], v[206:209], v[230:233], 0
	v_mfma_f32_16x16x32_bf16 v[4:7], v[198:201], v[238:241], 0
	v_mfma_f32_16x16x32_bf16 v[0:3], v[206:209], v[238:241], 0
	v_mfma_f32_16x16x32_bf16 v[44:47], v[202:205], v[218:221], v[44:47]
	v_mfma_f32_16x16x32_bf16 v[40:43], v[210:213], v[218:221], v[40:43]
	v_mfma_f32_16x16x32_bf16 v[28:31], v[202:205], v[226:229], v[28:31]
	v_mfma_f32_16x16x32_bf16 v[24:27], v[210:213], v[226:229], v[24:27]
	v_mfma_f32_16x16x32_bf16 v[12:15], v[202:205], v[234:237], v[12:15]
	v_mfma_f32_16x16x32_bf16 v[8:11], v[210:213], v[234:237], v[8:11]
	v_mfma_f32_16x16x32_bf16 v[4:7], v[202:205], v[242:245], v[4:7]
	v_mfma_f32_16x16x32_bf16 v[0:3], v[210:213], v[242:245], v[0:3]
	s_barrier
	v_add_u32_e32 v181, s34, v153
	ds_read_b128 v[182:185], v181
	ds_read_b128 v[186:189], v181 offset:1024
	ds_read_b128 v[190:193], v181 offset:2048
	ds_read_b128 v[194:197], v181 offset:3072
	v_add_u32_e32 v181, s35, v153
	ds_read_b128 v[198:201], v181
	ds_read_b128 v[202:205], v181 offset:1024
	ds_read_b128 v[206:209], v181 offset:2048
	ds_read_b128 v[210:213], v181 offset:3072
	s_add_u32 s40, s46, 0xb0000
	s_addc_u32 s41, s47, 0
	s_mov_b32 m0, s18
	ds_read_b128 v[214:217], v155 offset:32768
	ds_read_b128 v[218:221], v155 offset:33792
	ds_read_b128 v[222:225], v155 offset:34816
	ds_read_b128 v[226:229], v155 offset:35840
	ds_read_b128 v[230:233], v155 offset:36864
	ds_read_b128 v[234:237], v155 offset:37888
	ds_read_b128 v[238:241], v155 offset:38912
	ds_read_b128 v[242:245], v155 offset:39936
	global_load_lds_dwordx4 v142, s[40:41]
	s_mov_b32 m0, s19
	s_nop 0
	global_load_lds_dwordx4 v144, s[40:41]
	s_waitcnt vmcnt(8)
	s_waitcnt lgkmcnt(0)
	s_barrier
	v_mfma_f32_16x16x32_bf16 v[124:127], v[182:185], v[214:217], v[124:127]
	v_mfma_f32_16x16x32_bf16 v[120:123], v[190:193], v[214:217], v[120:123]
	v_mfma_f32_16x16x32_bf16 v[116:119], v[182:185], v[222:225], v[116:119]
	v_mfma_f32_16x16x32_bf16 v[112:115], v[190:193], v[222:225], v[112:115]
	v_mfma_f32_16x16x32_bf16 v[100:103], v[182:185], v[230:233], v[100:103]
	v_mfma_f32_16x16x32_bf16 v[96:99], v[190:193], v[230:233], v[96:99]
	v_mfma_f32_16x16x32_bf16 v[84:87], v[182:185], v[238:241], v[84:87]
	v_mfma_f32_16x16x32_bf16 v[80:83], v[190:193], v[238:241], v[80:83]
	v_mfma_f32_16x16x32_bf16 v[124:127], v[186:189], v[218:221], v[124:127]
	v_mfma_f32_16x16x32_bf16 v[120:123], v[194:197], v[218:221], v[120:123]
	v_mfma_f32_16x16x32_bf16 v[116:119], v[186:189], v[226:229], v[116:119]
	v_mfma_f32_16x16x32_bf16 v[112:115], v[194:197], v[226:229], v[112:115]
	v_mfma_f32_16x16x32_bf16 v[100:103], v[186:189], v[234:237], v[100:103]
	v_mfma_f32_16x16x32_bf16 v[96:99], v[194:197], v[234:237], v[96:99]
	v_mfma_f32_16x16x32_bf16 v[84:87], v[186:189], v[242:245], v[84:87]
	v_mfma_f32_16x16x32_bf16 v[80:83], v[194:197], v[242:245], v[80:83]
	v_mfma_f32_16x16x32_bf16 v[108:111], v[198:201], v[214:217], v[108:111]
	v_mfma_f32_16x16x32_bf16 v[104:107], v[206:209], v[214:217], v[104:107]
	v_mfma_f32_16x16x32_bf16 v[92:95], v[198:201], v[222:225], v[92:95]
	v_mfma_f32_16x16x32_bf16 v[88:91], v[206:209], v[222:225], v[88:91]
	v_mfma_f32_16x16x32_bf16 v[76:79], v[198:201], v[230:233], v[76:79]
	v_mfma_f32_16x16x32_bf16 v[72:75], v[206:209], v[230:233], v[72:75]
	v_mfma_f32_16x16x32_bf16 v[68:71], v[198:201], v[238:241], v[68:71]
	v_mfma_f32_16x16x32_bf16 v[64:67], v[206:209], v[238:241], v[64:67]
	v_mfma_f32_16x16x32_bf16 v[108:111], v[202:205], v[218:221], v[108:111]
	v_mfma_f32_16x16x32_bf16 v[104:107], v[210:213], v[218:221], v[104:107]
	v_mfma_f32_16x16x32_bf16 v[92:95], v[202:205], v[226:229], v[92:95]
	v_mfma_f32_16x16x32_bf16 v[88:91], v[210:213], v[226:229], v[88:91]
	v_mfma_f32_16x16x32_bf16 v[76:79], v[202:205], v[234:237], v[76:79]
	v_mfma_f32_16x16x32_bf16 v[72:75], v[210:213], v[234:237], v[72:75]
	v_mfma_f32_16x16x32_bf16 v[68:71], v[202:205], v[242:245], v[68:71]
	v_mfma_f32_16x16x32_bf16 v[64:67], v[210:213], v[242:245], v[64:67]
	s_barrier
	s_add_i32 s21, s34, s3
	s_mov_b32 m0, s21
	ds_read_b128 v[214:217], v155 offset:49152
	ds_read_b128 v[218:221], v155 offset:50176
	ds_read_b128 v[222:225], v155 offset:51200
	ds_read_b128 v[226:229], v155 offset:52224
	ds_read_b128 v[230:233], v155 offset:53248
	ds_read_b128 v[234:237], v155 offset:54272
	ds_read_b128 v[238:241], v155 offset:55296
	ds_read_b128 v[242:245], v155 offset:56320
	global_load_lds_dwordx4 v130, s[60:61]
	s_add_i32 m0, s21, 0x2000
	s_add_u32 s40, s44, 0x40080
	s_addc_u32 s41, s45, 0
	s_add_i32 s21, s35, s3
	global_load_lds_dwordx4 v146, s[60:61]
	s_mov_b32 m0, s21
	s_nop 0
	global_load_lds_dwordx4 v130, s[40:41]
	s_add_i32 m0, s21, 0x2000
	s_nop 0
	global_load_lds_dwordx4 v146, s[40:41]
	s_mov_b32 m0, s20
	s_nop 0
	global_load_lds_dwordx4 v142, s[62:63]
	s_mov_b32 m0, s26
	s_nop 0
	global_load_lds_dwordx4 v144, s[62:63]
	s_waitcnt vmcnt(8)
	s_waitcnt lgkmcnt(0)
	s_barrier
	v_mfma_f32_16x16x32_bf16 v[60:63], v[182:185], v[214:217], v[60:63]
	v_mfma_f32_16x16x32_bf16 v[56:59], v[190:193], v[214:217], v[56:59]
	v_mfma_f32_16x16x32_bf16 v[52:55], v[182:185], v[222:225], v[52:55]
	v_mfma_f32_16x16x32_bf16 v[48:51], v[190:193], v[222:225], v[48:51]
	v_mfma_f32_16x16x32_bf16 v[36:39], v[182:185], v[230:233], v[36:39]
	v_mfma_f32_16x16x32_bf16 v[32:35], v[190:193], v[230:233], v[32:35]
	v_mfma_f32_16x16x32_bf16 v[20:23], v[182:185], v[238:241], v[20:23]
	v_mfma_f32_16x16x32_bf16 v[16:19], v[190:193], v[238:241], v[16:19]
	v_mfma_f32_16x16x32_bf16 v[60:63], v[186:189], v[218:221], v[60:63]
	v_mfma_f32_16x16x32_bf16 v[56:59], v[194:197], v[218:221], v[56:59]
	v_mfma_f32_16x16x32_bf16 v[52:55], v[186:189], v[226:229], v[52:55]
	v_mfma_f32_16x16x32_bf16 v[48:51], v[194:197], v[226:229], v[48:51]
	v_mfma_f32_16x16x32_bf16 v[36:39], v[186:189], v[234:237], v[36:39]
	v_mfma_f32_16x16x32_bf16 v[32:35], v[194:197], v[234:237], v[32:35]
	v_mfma_f32_16x16x32_bf16 v[20:23], v[186:189], v[242:245], v[20:23]
	v_mfma_f32_16x16x32_bf16 v[16:19], v[194:197], v[242:245], v[16:19]
	v_mfma_f32_16x16x32_bf16 v[44:47], v[198:201], v[214:217], v[44:47]
	v_mfma_f32_16x16x32_bf16 v[40:43], v[206:209], v[214:217], v[40:43]
	v_mfma_f32_16x16x32_bf16 v[28:31], v[198:201], v[222:225], v[28:31]
	v_mfma_f32_16x16x32_bf16 v[24:27], v[206:209], v[222:225], v[24:27]
	v_mfma_f32_16x16x32_bf16 v[12:15], v[198:201], v[230:233], v[12:15]
	v_mfma_f32_16x16x32_bf16 v[8:11], v[206:209], v[230:233], v[8:11]
	v_mfma_f32_16x16x32_bf16 v[4:7], v[198:201], v[238:241], v[4:7]
	v_mfma_f32_16x16x32_bf16 v[0:3], v[206:209], v[238:241], v[0:3]
	v_mfma_f32_16x16x32_bf16 v[44:47], v[202:205], v[218:221], v[44:47]
	v_mfma_f32_16x16x32_bf16 v[40:43], v[210:213], v[218:221], v[40:43]
	v_mfma_f32_16x16x32_bf16 v[28:31], v[202:205], v[226:229], v[28:31]
	v_mfma_f32_16x16x32_bf16 v[24:27], v[210:213], v[226:229], v[24:27]
	v_mfma_f32_16x16x32_bf16 v[12:15], v[202:205], v[234:237], v[12:15]
	v_mfma_f32_16x16x32_bf16 v[8:11], v[210:213], v[234:237], v[8:11]
	v_mfma_f32_16x16x32_bf16 v[4:7], v[202:205], v[242:245], v[4:7]
	v_mfma_f32_16x16x32_bf16 v[0:3], v[210:213], v[242:245], v[0:3]
	s_barrier
	s_add_u32 s29, s29, 0x100
	s_addc_u32 s49, s49, 0
	s_cmp_ge_i32 s50, s48
	s_mov_b64 s[40:41], s[42:43]
	s_mov_b32 s44, s50
	s_cbranch_scc1 .Lpeel_done_1272
.LBB0_1272:
	v_add_u32_e32 v156, s22, v153
	ds_read_b128 v[182:185], v156
	ds_read_b128 v[186:189], v156 offset:1024
	ds_read_b128 v[190:193], v156 offset:2048
	ds_read_b128 v[194:197], v156 offset:3072
	v_add_u32_e32 v156, s23, v153
	ds_read_b128 v[198:201], v156
	ds_read_b128 v[202:205], v156 offset:1024
	ds_read_b128 v[206:209], v156 offset:2048
	ds_read_b128 v[210:213], v156 offset:3072
	s_add_i32 s50, s44, 2
	s_add_u32 s42, s40, 0x100
	s_addc_u32 s43, s41, 0
	s_cmp_eq_u32 s11, s44
	s_cselect_b32 s44, s36, s29
	s_cselect_b32 s47, s17, s43
	s_cselect_b32 s46, s16, s42
	s_cselect_b32 s45, s37, s49
	s_add_i32 m0, s12, 0xc000
	ds_read_b128 v[214:217], v155
	ds_read_b128 v[218:221], v155 offset:1024
	ds_read_b128 v[222:225], v155 offset:2048
	ds_read_b128 v[226:229], v155 offset:3072
	ds_read_b128 v[230:233], v155 offset:4096
	ds_read_b128 v[234:237], v155 offset:5120
	ds_read_b128 v[238:241], v155 offset:6144
	ds_read_b128 v[242:245], v155 offset:7168
	global_load_lds_dwordx4 v148, s[40:41]
	s_add_i32 m0, s12, 0xe000
	s_nop 0
	global_load_lds_dwordx4 v150, s[40:41]
	s_waitcnt vmcnt(8)
	s_waitcnt lgkmcnt(0)
	s_barrier
	v_mfma_f32_16x16x32_bf16 v[124:127], v[182:185], v[214:217], v[124:127]
	v_mfma_f32_16x16x32_bf16 v[120:123], v[190:193], v[214:217], v[120:123]
	v_mfma_f32_16x16x32_bf16 v[116:119], v[182:185], v[222:225], v[116:119]
	v_mfma_f32_16x16x32_bf16 v[112:115], v[190:193], v[222:225], v[112:115]
	v_mfma_f32_16x16x32_bf16 v[100:103], v[182:185], v[230:233], v[100:103]
	v_mfma_f32_16x16x32_bf16 v[96:99], v[190:193], v[230:233], v[96:99]
	v_mfma_f32_16x16x32_bf16 v[84:87], v[182:185], v[238:241], v[84:87]
	v_mfma_f32_16x16x32_bf16 v[80:83], v[190:193], v[238:241], v[80:83]
	v_mfma_f32_16x16x32_bf16 v[124:127], v[186:189], v[218:221], v[124:127]
	v_mfma_f32_16x16x32_bf16 v[120:123], v[194:197], v[218:221], v[120:123]
	v_mfma_f32_16x16x32_bf16 v[116:119], v[186:189], v[226:229], v[116:119]
	v_mfma_f32_16x16x32_bf16 v[112:115], v[194:197], v[226:229], v[112:115]
	v_mfma_f32_16x16x32_bf16 v[100:103], v[186:189], v[234:237], v[100:103]
	v_mfma_f32_16x16x32_bf16 v[96:99], v[194:197], v[234:237], v[96:99]
	v_mfma_f32_16x16x32_bf16 v[84:87], v[186:189], v[242:245], v[84:87]
	v_mfma_f32_16x16x32_bf16 v[80:83], v[194:197], v[242:245], v[80:83]
	v_mfma_f32_16x16x32_bf16 v[108:111], v[198:201], v[214:217], v[108:111]
	v_mfma_f32_16x16x32_bf16 v[104:107], v[206:209], v[214:217], v[104:107]
	v_mfma_f32_16x16x32_bf16 v[92:95], v[198:201], v[222:225], v[92:95]
	v_mfma_f32_16x16x32_bf16 v[88:91], v[206:209], v[222:225], v[88:91]
	v_mfma_f32_16x16x32_bf16 v[76:79], v[198:201], v[230:233], v[76:79]
	v_mfma_f32_16x16x32_bf16 v[72:75], v[206:209], v[230:233], v[72:75]
	v_mfma_f32_16x16x32_bf16 v[68:71], v[198:201], v[238:241], v[68:71]
	v_mfma_f32_16x16x32_bf16 v[64:67], v[206:209], v[238:241], v[64:67]
	v_mfma_f32_16x16x32_bf16 v[108:111], v[202:205], v[218:221], v[108:111]
	v_mfma_f32_16x16x32_bf16 v[104:107], v[210:213], v[218:221], v[104:107]
	v_mfma_f32_16x16x32_bf16 v[92:95], v[202:205], v[226:229], v[92:95]
	v_mfma_f32_16x16x32_bf16 v[88:91], v[210:213], v[226:229], v[88:91]
	v_mfma_f32_16x16x32_bf16 v[76:79], v[202:205], v[234:237], v[76:79]
	v_mfma_f32_16x16x32_bf16 v[72:75], v[210:213], v[234:237], v[72:75]
	v_mfma_f32_16x16x32_bf16 v[68:71], v[202:205], v[242:245], v[68:71]
	v_mfma_f32_16x16x32_bf16 v[64:67], v[210:213], v[242:245], v[64:67]
	s_barrier
	s_add_u32 s60, s44, 0x80
	s_addc_u32 s61, s45, 0
	s_add_u32 s62, s46, 0x80
	s_addc_u32 s63, s47, 0
	s_add_i32 s21, s22, s3
	s_mov_b32 m0, s21
	ds_read_b128 v[214:217], v155 offset:16384
	ds_read_b128 v[218:221], v155 offset:17408
	ds_read_b128 v[222:225], v155 offset:18432
	ds_read_b128 v[226:229], v155 offset:19456
	ds_read_b128 v[230:233], v155 offset:20480
	ds_read_b128 v[234:237], v155 offset:21504
	ds_read_b128 v[238:241], v155 offset:22528
	ds_read_b128 v[242:245], v155 offset:23552
	global_load_lds_dwordx4 v130, s[44:45]
	s_add_i32 m0, s21, 0x2000
	s_add_u32 s40, s44, 0x40000
	s_addc_u32 s41, s45, 0
	s_add_i32 s21, s23, s3
	global_load_lds_dwordx4 v146, s[44:45]
	s_mov_b32 m0, s21
	s_nop 0
	global_load_lds_dwordx4 v130, s[40:41]
	s_add_i32 m0, s21, 0x2000
	s_nop 0
	global_load_lds_dwordx4 v146, s[40:41]
	s_mov_b32 m0, s12
	s_nop 0
	global_load_lds_dwordx4 v142, s[46:47]
	s_mov_b32 m0, s13
	s_nop 0
	global_load_lds_dwordx4 v144, s[46:47]
	s_waitcnt vmcnt(8)
	s_waitcnt lgkmcnt(0)
	s_barrier
	v_mfma_f32_16x16x32_bf16 v[60:63], v[182:185], v[214:217], v[60:63]
	v_mfma_f32_16x16x32_bf16 v[56:59], v[190:193], v[214:217], v[56:59]
	v_mfma_f32_16x16x32_bf16 v[52:55], v[182:185], v[222:225], v[52:55]
	v_mfma_f32_16x16x32_bf16 v[48:51], v[190:193], v[222:225], v[48:51]
	v_mfma_f32_16x16x32_bf16 v[36:39], v[182:185], v[230:233], v[36:39]
	v_mfma_f32_16x16x32_bf16 v[32:35], v[190:193], v[230:233], v[32:35]
	v_mfma_f32_16x16x32_bf16 v[20:23], v[182:185], v[238:241], v[20:23]
	v_mfma_f32_16x16x32_bf16 v[16:19], v[190:193], v[238:241], v[16:19]
	v_mfma_f32_16x16x32_bf16 v[60:63], v[186:189], v[218:221], v[60:63]
	v_mfma_f32_16x16x32_bf16 v[56:59], v[194:197], v[218:221], v[56:59]
	v_mfma_f32_16x16x32_bf16 v[52:55], v[186:189], v[226:229], v[52:55]
	v_mfma_f32_16x16x32_bf16 v[48:51], v[194:197], v[226:229], v[48:51]
	v_mfma_f32_16x16x32_bf16 v[36:39], v[186:189], v[234:237], v[36:39]
	v_mfma_f32_16x16x32_bf16 v[32:35], v[194:197], v[234:237], v[32:35]
	v_mfma_f32_16x16x32_bf16 v[20:23], v[186:189], v[242:245], v[20:23]
	v_mfma_f32_16x16x32_bf16 v[16:19], v[194:197], v[242:245], v[16:19]
	v_mfma_f32_16x16x32_bf16 v[44:47], v[198:201], v[214:217], v[44:47]
	v_mfma_f32_16x16x32_bf16 v[40:43], v[206:209], v[214:217], v[40:43]
	v_mfma_f32_16x16x32_bf16 v[28:31], v[198:201], v[222:225], v[28:31]
	v_mfma_f32_16x16x32_bf16 v[24:27], v[206:209], v[222:225], v[24:27]
	v_mfma_f32_16x16x32_bf16 v[12:15], v[198:201], v[230:233], v[12:15]
	v_mfma_f32_16x16x32_bf16 v[8:11], v[206:209], v[230:233], v[8:11]
	v_mfma_f32_16x16x32_bf16 v[4:7], v[198:201], v[238:241], v[4:7]
	v_mfma_f32_16x16x32_bf16 v[0:3], v[206:209], v[238:241], v[0:3]
	v_mfma_f32_16x16x32_bf16 v[44:47], v[202:205], v[218:221], v[44:47]
	v_mfma_f32_16x16x32_bf16 v[40:43], v[210:213], v[218:221], v[40:43]
	v_mfma_f32_16x16x32_bf16 v[28:31], v[202:205], v[226:229], v[28:31]
	v_mfma_f32_16x16x32_bf16 v[24:27], v[210:213], v[226:229], v[24:27]
	v_mfma_f32_16x16x32_bf16 v[12:15], v[202:205], v[234:237], v[12:15]
	v_mfma_f32_16x16x32_bf16 v[8:11], v[210:213], v[234:237], v[8:11]
	v_mfma_f32_16x16x32_bf16 v[4:7], v[202:205], v[242:245], v[4:7]
	v_mfma_f32_16x16x32_bf16 v[0:3], v[210:213], v[242:245], v[0:3]
	s_barrier
	v_add_u32_e32 v181, s34, v153
	ds_read_b128 v[182:185], v181
	ds_read_b128 v[186:189], v181 offset:1024
	ds_read_b128 v[190:193], v181 offset:2048
	ds_read_b128 v[194:197], v181 offset:3072
	v_add_u32_e32 v181, s35, v153
	ds_read_b128 v[198:201], v181
	ds_read_b128 v[202:205], v181 offset:1024
	ds_read_b128 v[206:209], v181 offset:2048
	ds_read_b128 v[210:213], v181 offset:3072
	s_add_u32 s40, s46, 0xb0000
	s_addc_u32 s41, s47, 0
	s_mov_b32 m0, s18
	ds_read_b128 v[214:217], v155 offset:32768
	ds_read_b128 v[218:221], v155 offset:33792
	ds_read_b128 v[222:225], v155 offset:34816
	ds_read_b128 v[226:229], v155 offset:35840
	ds_read_b128 v[230:233], v155 offset:36864
	ds_read_b128 v[234:237], v155 offset:37888
	ds_read_b128 v[238:241], v155 offset:38912
	ds_read_b128 v[242:245], v155 offset:39936
	global_load_lds_dwordx4 v142, s[40:41]
	s_mov_b32 m0, s19
	s_nop 0
	global_load_lds_dwordx4 v144, s[40:41]
	s_waitcnt vmcnt(8)
	s_waitcnt lgkmcnt(0)
	s_barrier
	v_mfma_f32_16x16x32_bf16 v[124:127], v[182:185], v[214:217], v[124:127]
	v_mfma_f32_16x16x32_bf16 v[120:123], v[190:193], v[214:217], v[120:123]
	v_mfma_f32_16x16x32_bf16 v[116:119], v[182:185], v[222:225], v[116:119]
	v_mfma_f32_16x16x32_bf16 v[112:115], v[190:193], v[222:225], v[112:115]
	v_mfma_f32_16x16x32_bf16 v[100:103], v[182:185], v[230:233], v[100:103]
	v_mfma_f32_16x16x32_bf16 v[96:99], v[190:193], v[230:233], v[96:99]
	v_mfma_f32_16x16x32_bf16 v[84:87], v[182:185], v[238:241], v[84:87]
	v_mfma_f32_16x16x32_bf16 v[80:83], v[190:193], v[238:241], v[80:83]
	v_mfma_f32_16x16x32_bf16 v[124:127], v[186:189], v[218:221], v[124:127]
	v_mfma_f32_16x16x32_bf16 v[120:123], v[194:197], v[218:221], v[120:123]
	v_mfma_f32_16x16x32_bf16 v[116:119], v[186:189], v[226:229], v[116:119]
	v_mfma_f32_16x16x32_bf16 v[112:115], v[194:197], v[226:229], v[112:115]
	v_mfma_f32_16x16x32_bf16 v[100:103], v[186:189], v[234:237], v[100:103]
	v_mfma_f32_16x16x32_bf16 v[96:99], v[194:197], v[234:237], v[96:99]
	v_mfma_f32_16x16x32_bf16 v[84:87], v[186:189], v[242:245], v[84:87]
	v_mfma_f32_16x16x32_bf16 v[80:83], v[194:197], v[242:245], v[80:83]
	v_mfma_f32_16x16x32_bf16 v[108:111], v[198:201], v[214:217], v[108:111]
	v_mfma_f32_16x16x32_bf16 v[104:107], v[206:209], v[214:217], v[104:107]
	v_mfma_f32_16x16x32_bf16 v[92:95], v[198:201], v[222:225], v[92:95]
	v_mfma_f32_16x16x32_bf16 v[88:91], v[206:209], v[222:225], v[88:91]
	v_mfma_f32_16x16x32_bf16 v[76:79], v[198:201], v[230:233], v[76:79]
	v_mfma_f32_16x16x32_bf16 v[72:75], v[206:209], v[230:233], v[72:75]
	v_mfma_f32_16x16x32_bf16 v[68:71], v[198:201], v[238:241], v[68:71]
	v_mfma_f32_16x16x32_bf16 v[64:67], v[206:209], v[238:241], v[64:67]
	v_mfma_f32_16x16x32_bf16 v[108:111], v[202:205], v[218:221], v[108:111]
	v_mfma_f32_16x16x32_bf16 v[104:107], v[210:213], v[218:221], v[104:107]
	v_mfma_f32_16x16x32_bf16 v[92:95], v[202:205], v[226:229], v[92:95]
	v_mfma_f32_16x16x32_bf16 v[88:91], v[210:213], v[226:229], v[88:91]
	v_mfma_f32_16x16x32_bf16 v[76:79], v[202:205], v[234:237], v[76:79]
	v_mfma_f32_16x16x32_bf16 v[72:75], v[210:213], v[234:237], v[72:75]
	v_mfma_f32_16x16x32_bf16 v[68:71], v[202:205], v[242:245], v[68:71]
	v_mfma_f32_16x16x32_bf16 v[64:67], v[210:213], v[242:245], v[64:67]
	s_barrier
	s_add_i32 s21, s34, s3
	s_mov_b32 m0, s21
	ds_read_b128 v[214:217], v155 offset:49152
	ds_read_b128 v[218:221], v155 offset:50176
	ds_read_b128 v[222:225], v155 offset:51200
	ds_read_b128 v[226:229], v155 offset:52224
	ds_read_b128 v[230:233], v155 offset:53248
	ds_read_b128 v[234:237], v155 offset:54272
	ds_read_b128 v[238:241], v155 offset:55296
	ds_read_b128 v[242:245], v155 offset:56320
	global_load_lds_dwordx4 v130, s[60:61]
	s_add_i32 m0, s21, 0x2000
	s_add_u32 s40, s44, 0x40080
	s_addc_u32 s41, s45, 0
	s_add_i32 s21, s35, s3
	global_load_lds_dwordx4 v146, s[60:61]
	s_mov_b32 m0, s21
	s_nop 0
	global_load_lds_dwordx4 v130, s[40:41]
	s_add_i32 m0, s21, 0x2000
	s_nop 0
	global_load_lds_dwordx4 v146, s[40:41]
	s_mov_b32 m0, s20
	s_nop 0
	global_load_lds_dwordx4 v142, s[62:63]
	s_mov_b32 m0, s26
	s_nop 0
	global_load_lds_dwordx4 v144, s[62:63]
	s_waitcnt vmcnt(8)
	s_waitcnt lgkmcnt(0)
	s_barrier
	v_mfma_f32_16x16x32_bf16 v[60:63], v[182:185], v[214:217], v[60:63]
	v_mfma_f32_16x16x32_bf16 v[56:59], v[190:193], v[214:217], v[56:59]
	v_mfma_f32_16x16x32_bf16 v[52:55], v[182:185], v[222:225], v[52:55]
	v_mfma_f32_16x16x32_bf16 v[48:51], v[190:193], v[222:225], v[48:51]
	v_mfma_f32_16x16x32_bf16 v[36:39], v[182:185], v[230:233], v[36:39]
	v_mfma_f32_16x16x32_bf16 v[32:35], v[190:193], v[230:233], v[32:35]
	v_mfma_f32_16x16x32_bf16 v[20:23], v[182:185], v[238:241], v[20:23]
	v_mfma_f32_16x16x32_bf16 v[16:19], v[190:193], v[238:241], v[16:19]
	v_mfma_f32_16x16x32_bf16 v[60:63], v[186:189], v[218:221], v[60:63]
	v_mfma_f32_16x16x32_bf16 v[56:59], v[194:197], v[218:221], v[56:59]
	v_mfma_f32_16x16x32_bf16 v[52:55], v[186:189], v[226:229], v[52:55]
	v_mfma_f32_16x16x32_bf16 v[48:51], v[194:197], v[226:229], v[48:51]
	v_mfma_f32_16x16x32_bf16 v[36:39], v[186:189], v[234:237], v[36:39]
	v_mfma_f32_16x16x32_bf16 v[32:35], v[194:197], v[234:237], v[32:35]
	v_mfma_f32_16x16x32_bf16 v[20:23], v[186:189], v[242:245], v[20:23]
	v_mfma_f32_16x16x32_bf16 v[16:19], v[194:197], v[242:245], v[16:19]
	v_mfma_f32_16x16x32_bf16 v[44:47], v[198:201], v[214:217], v[44:47]
	v_mfma_f32_16x16x32_bf16 v[40:43], v[206:209], v[214:217], v[40:43]
	v_mfma_f32_16x16x32_bf16 v[28:31], v[198:201], v[222:225], v[28:31]
	v_mfma_f32_16x16x32_bf16 v[24:27], v[206:209], v[222:225], v[24:27]
	v_mfma_f32_16x16x32_bf16 v[12:15], v[198:201], v[230:233], v[12:15]
	v_mfma_f32_16x16x32_bf16 v[8:11], v[206:209], v[230:233], v[8:11]
	v_mfma_f32_16x16x32_bf16 v[4:7], v[198:201], v[238:241], v[4:7]
	v_mfma_f32_16x16x32_bf16 v[0:3], v[206:209], v[238:241], v[0:3]
	v_mfma_f32_16x16x32_bf16 v[44:47], v[202:205], v[218:221], v[44:47]
	v_mfma_f32_16x16x32_bf16 v[40:43], v[210:213], v[218:221], v[40:43]
	v_mfma_f32_16x16x32_bf16 v[28:31], v[202:205], v[226:229], v[28:31]
	v_mfma_f32_16x16x32_bf16 v[24:27], v[210:213], v[226:229], v[24:27]
	v_mfma_f32_16x16x32_bf16 v[12:15], v[202:205], v[234:237], v[12:15]
	v_mfma_f32_16x16x32_bf16 v[8:11], v[210:213], v[234:237], v[8:11]
	v_mfma_f32_16x16x32_bf16 v[4:7], v[202:205], v[242:245], v[4:7]
	v_mfma_f32_16x16x32_bf16 v[0:3], v[210:213], v[242:245], v[0:3]
	s_barrier
	s_add_u32 s29, s29, 0x100
	s_addc_u32 s49, s49, 0
	s_cmp_ge_i32 s50, s48
	s_mov_b64 s[40:41], s[42:43]
	s_mov_b32 s44, s50
	s_cbranch_scc0 .LBB0_1272

.LBB0_1437:
	s_ashr_i32 s11, s10, 31
	s_lshl_b64 s[12:13], s[10:11], 19
	v_readlane_b32 s14, v252, 27
	v_readlane_b32 s15, v252, 28
	s_add_u32 s28, s14, s12
	s_addc_u32 s29, s15, s13
	s_and_b64 s[12:13], s[40:41], exec
	s_cselect_b32 s3, s29, s17
	s_cselect_b32 s11, s28, s16
	s_ashr_i32 s9, s8, 31
	s_lshl_b64 s[12:13], s[8:9], 19
	s_add_u32 s36, s26, s12
	s_addc_u32 s37, s46, s13
	s_and_b64 s[12:13], s[40:41], exec
	s_cselect_b32 s9, s37, s43
	s_cselect_b32 s12, s36, s42
	s_add_u32 s16, s16, 0x40080
	s_addc_u32 s17, s17, 0
	s_add_u32 s13, s42, 0x100
	s_addc_u32 s14, s43, 0
	s_mov_b32 s15, -2
	v_add_u32_e32 v152, s22, v155
	ds_read_b128 v[182:185], v152
	ds_read_b128 v[186:189], v152 offset:1024
	ds_read_b128 v[190:193], v152 offset:2048
	ds_read_b128 v[194:197], v152 offset:3072
	v_add_u32_e32 v152, s23, v155
	ds_read_b128 v[198:201], v152
	ds_read_b128 v[202:205], v152 offset:1024
	ds_read_b128 v[206:209], v152 offset:2048
	ds_read_b128 v[210:213], v152 offset:3072
	s_add_u32 s18, s16, 0xfffc0080
	s_addc_u32 s19, s17, -1
	s_cmp_eq_u32 s15, 12
	s_cselect_b32 s45, s3, s19
	s_cselect_b32 s44, s11, s18
	s_cselect_b32 s43, s9, s14
	s_cselect_b32 s42, s12, s13
	s_add_i32 m0, s48, 0xc000
	ds_read_b128 v[214:217], v157
	ds_read_b128 v[218:221], v157 offset:1024
	ds_read_b128 v[222:225], v157 offset:2048
	ds_read_b128 v[226:229], v157 offset:3072
	ds_read_b128 v[230:233], v157 offset:4096
	ds_read_b128 v[234:237], v157 offset:5120
	ds_read_b128 v[238:241], v157 offset:6144
	ds_read_b128 v[242:245], v157 offset:7168
	global_load_lds_dwordx4 v148, s[16:17]
	s_add_i32 m0, s48, 0xe000
	s_nop 0
	global_load_lds_dwordx4 v150, s[16:17]
	s_waitcnt vmcnt(8)
	s_waitcnt lgkmcnt(0)
	s_barrier
	v_mfma_f32_16x16x32_bf16 v[124:127], v[182:185], v[214:217], 0
	v_mfma_f32_16x16x32_bf16 v[120:123], v[190:193], v[214:217], 0
	v_mfma_f32_16x16x32_bf16 v[108:111], v[182:185], v[222:225], 0
	v_mfma_f32_16x16x32_bf16 v[104:107], v[190:193], v[222:225], 0
	v_mfma_f32_16x16x32_bf16 v[92:95], v[182:185], v[230:233], 0
	v_mfma_f32_16x16x32_bf16 v[88:91], v[190:193], v[230:233], 0
	v_mfma_f32_16x16x32_bf16 v[76:79], v[182:185], v[238:241], 0
	v_mfma_f32_16x16x32_bf16 v[72:75], v[190:193], v[238:241], 0
	v_mfma_f32_16x16x32_bf16 v[124:127], v[186:189], v[218:221], v[124:127]
	v_mfma_f32_16x16x32_bf16 v[120:123], v[194:197], v[218:221], v[120:123]
	v_mfma_f32_16x16x32_bf16 v[108:111], v[186:189], v[226:229], v[108:111]
	v_mfma_f32_16x16x32_bf16 v[104:107], v[194:197], v[226:229], v[104:107]
	v_mfma_f32_16x16x32_bf16 v[92:95], v[186:189], v[234:237], v[92:95]
	v_mfma_f32_16x16x32_bf16 v[88:91], v[194:197], v[234:237], v[88:91]
	v_mfma_f32_16x16x32_bf16 v[76:79], v[186:189], v[242:245], v[76:79]
	v_mfma_f32_16x16x32_bf16 v[72:75], v[194:197], v[242:245], v[72:75]
	v_mfma_f32_16x16x32_bf16 v[116:119], v[198:201], v[214:217], 0
	v_mfma_f32_16x16x32_bf16 v[112:115], v[206:209], v[214:217], 0
	v_mfma_f32_16x16x32_bf16 v[100:103], v[198:201], v[222:225], 0
	v_mfma_f32_16x16x32_bf16 v[96:99], v[206:209], v[222:225], 0
	v_mfma_f32_16x16x32_bf16 v[84:87], v[198:201], v[230:233], 0
	v_mfma_f32_16x16x32_bf16 v[80:83], v[206:209], v[230:233], 0
	v_mfma_f32_16x16x32_bf16 v[68:71], v[198:201], v[238:241], 0
	v_mfma_f32_16x16x32_bf16 v[64:67], v[206:209], v[238:241], 0
	v_mfma_f32_16x16x32_bf16 v[116:119], v[202:205], v[218:221], v[116:119]
	v_mfma_f32_16x16x32_bf16 v[112:115], v[210:213], v[218:221], v[112:115]
	v_mfma_f32_16x16x32_bf16 v[100:103], v[202:205], v[226:229], v[100:103]
	v_mfma_f32_16x16x32_bf16 v[96:99], v[210:213], v[226:229], v[96:99]
	v_mfma_f32_16x16x32_bf16 v[84:87], v[202:205], v[234:237], v[84:87]
	v_mfma_f32_16x16x32_bf16 v[80:83], v[210:213], v[234:237], v[80:83]
	v_mfma_f32_16x16x32_bf16 v[68:71], v[202:205], v[242:245], v[68:71]
	v_mfma_f32_16x16x32_bf16 v[64:67], v[210:213], v[242:245], v[64:67]
	s_barrier
	s_add_u32 s60, s42, 0x80
	s_addc_u32 s61, s43, 0
	s_add_u32 s62, s44, 0x80
	s_addc_u32 s63, s45, 0
	s_add_i32 s18, s22, s47
	s_mov_b32 m0, s18
	ds_read_b128 v[214:217], v157 offset:16384
	ds_read_b128 v[218:221], v157 offset:17408
	ds_read_b128 v[222:225], v157 offset:18432
	ds_read_b128 v[226:229], v157 offset:19456
	ds_read_b128 v[230:233], v157 offset:20480
	ds_read_b128 v[234:237], v157 offset:21504
	ds_read_b128 v[238:241], v157 offset:22528
	ds_read_b128 v[242:245], v157 offset:23552
	global_load_lds_dwordx4 v130, s[42:43]
	s_add_i32 m0, s18, 0x2000
	s_add_u32 s18, s42, 0x40000
	s_addc_u32 s19, s43, 0
	s_add_i32 s21, s23, s47
	global_load_lds_dwordx4 v142, s[42:43]
	s_mov_b32 m0, s21
	s_nop 0
	global_load_lds_dwordx4 v130, s[18:19]
	s_add_i32 m0, s21, 0x2000
	s_nop 0
	global_load_lds_dwordx4 v142, s[18:19]
	s_mov_b32 m0, s48
	s_nop 0
	global_load_lds_dwordx4 v146, s[44:45]
	s_mov_b32 m0, s49
	s_nop 0
	global_load_lds_dwordx4 v144, s[44:45]
	s_waitcnt vmcnt(8)
	s_waitcnt lgkmcnt(0)
	s_barrier
	v_mfma_f32_16x16x32_bf16 v[60:63], v[182:185], v[214:217], 0
	v_mfma_f32_16x16x32_bf16 v[56:59], v[190:193], v[214:217], 0
	v_mfma_f32_16x16x32_bf16 v[44:47], v[182:185], v[222:225], 0
	v_mfma_f32_16x16x32_bf16 v[40:43], v[190:193], v[222:225], 0
	v_mfma_f32_16x16x32_bf16 v[28:31], v[182:185], v[230:233], 0
	v_mfma_f32_16x16x32_bf16 v[24:27], v[190:193], v[230:233], 0
	v_mfma_f32_16x16x32_bf16 v[12:15], v[182:185], v[238:241], 0
	v_mfma_f32_16x16x32_bf16 v[8:11], v[190:193], v[238:241], 0
	v_mfma_f32_16x16x32_bf16 v[60:63], v[186:189], v[218:221], v[60:63]
	v_mfma_f32_16x16x32_bf16 v[56:59], v[194:197], v[218:221], v[56:59]
	v_mfma_f32_16x16x32_bf16 v[44:47], v[186:189], v[226:229], v[44:47]
	v_mfma_f32_16x16x32_bf16 v[40:43], v[194:197], v[226:229], v[40:43]
	v_mfma_f32_16x16x32_bf16 v[28:31], v[186:189], v[234:237], v[28:31]
	v_mfma_f32_16x16x32_bf16 v[24:27], v[194:197], v[234:237], v[24:27]
	v_mfma_f32_16x16x32_bf16 v[12:15], v[186:189], v[242:245], v[12:15]
	v_mfma_f32_16x16x32_bf16 v[8:11], v[194:197], v[242:245], v[8:11]
	v_mfma_f32_16x16x32_bf16 v[52:55], v[198:201], v[214:217], 0
	v_mfma_f32_16x16x32_bf16 v[48:51], v[206:209], v[214:217], 0
	v_mfma_f32_16x16x32_bf16 v[36:39], v[198:201], v[222:225], 0
	v_mfma_f32_16x16x32_bf16 v[32:35], v[206:209], v[222:225], 0
	v_mfma_f32_16x16x32_bf16 v[20:23], v[198:201], v[230:233], 0
	v_mfma_f32_16x16x32_bf16 v[16:19], v[206:209], v[230:233], 0
	v_mfma_f32_16x16x32_bf16 v[4:7], v[198:201], v[238:241], 0
	v_mfma_f32_16x16x32_bf16 v[0:3], v[206:209], v[238:241], 0
	v_mfma_f32_16x16x32_bf16 v[52:55], v[202:205], v[218:221], v[52:55]
	v_mfma_f32_16x16x32_bf16 v[48:51], v[210:213], v[218:221], v[48:51]
	v_mfma_f32_16x16x32_bf16 v[36:39], v[202:205], v[226:229], v[36:39]
	v_mfma_f32_16x16x32_bf16 v[32:35], v[210:213], v[226:229], v[32:35]
	v_mfma_f32_16x16x32_bf16 v[20:23], v[202:205], v[234:237], v[20:23]
	v_mfma_f32_16x16x32_bf16 v[16:19], v[210:213], v[234:237], v[16:19]
	v_mfma_f32_16x16x32_bf16 v[4:7], v[202:205], v[242:245], v[4:7]
	v_mfma_f32_16x16x32_bf16 v[0:3], v[210:213], v[242:245], v[0:3]
	s_barrier
	v_add_u32_e32 v181, s34, v155
	ds_read_b128 v[182:185], v181
	ds_read_b128 v[186:189], v181 offset:1024
	ds_read_b128 v[190:193], v181 offset:2048
	ds_read_b128 v[194:197], v181 offset:3072
	v_add_u32_e32 v181, s35, v155
	ds_read_b128 v[198:201], v181
	ds_read_b128 v[202:205], v181 offset:1024
	ds_read_b128 v[206:209], v181 offset:2048
	ds_read_b128 v[210:213], v181 offset:3072
	s_add_u32 s18, s44, 0x40000
	s_addc_u32 s19, s45, 0
	s_mov_b32 m0, s50
	ds_read_b128 v[214:217], v157 offset:32768
	ds_read_b128 v[218:221], v157 offset:33792
	ds_read_b128 v[222:225], v157 offset:34816
	ds_read_b128 v[226:229], v157 offset:35840
	ds_read_b128 v[230:233], v157 offset:36864
	ds_read_b128 v[234:237], v157 offset:37888
	ds_read_b128 v[238:241], v157 offset:38912
	ds_read_b128 v[242:245], v157 offset:39936
	global_load_lds_dwordx4 v146, s[18:19]
	s_mov_b32 m0, s51
	s_nop 0
	global_load_lds_dwordx4 v144, s[18:19]
	s_waitcnt vmcnt(8)
	s_waitcnt lgkmcnt(0)
	s_barrier
	v_mfma_f32_16x16x32_bf16 v[124:127], v[182:185], v[214:217], v[124:127]
	v_mfma_f32_16x16x32_bf16 v[120:123], v[190:193], v[214:217], v[120:123]
	v_mfma_f32_16x16x32_bf16 v[108:111], v[182:185], v[222:225], v[108:111]
	v_mfma_f32_16x16x32_bf16 v[104:107], v[190:193], v[222:225], v[104:107]
	v_mfma_f32_16x16x32_bf16 v[92:95], v[182:185], v[230:233], v[92:95]
	v_mfma_f32_16x16x32_bf16 v[88:91], v[190:193], v[230:233], v[88:91]
	v_mfma_f32_16x16x32_bf16 v[76:79], v[182:185], v[238:241], v[76:79]
	v_mfma_f32_16x16x32_bf16 v[72:75], v[190:193], v[238:241], v[72:75]
	v_mfma_f32_16x16x32_bf16 v[124:127], v[186:189], v[218:221], v[124:127]
	v_mfma_f32_16x16x32_bf16 v[120:123], v[194:197], v[218:221], v[120:123]
	v_mfma_f32_16x16x32_bf16 v[108:111], v[186:189], v[226:229], v[108:111]
	v_mfma_f32_16x16x32_bf16 v[104:107], v[194:197], v[226:229], v[104:107]
	v_mfma_f32_16x16x32_bf16 v[92:95], v[186:189], v[234:237], v[92:95]
	v_mfma_f32_16x16x32_bf16 v[88:91], v[194:197], v[234:237], v[88:91]
	v_mfma_f32_16x16x32_bf16 v[76:79], v[186:189], v[242:245], v[76:79]
	v_mfma_f32_16x16x32_bf16 v[72:75], v[194:197], v[242:245], v[72:75]
	v_mfma_f32_16x16x32_bf16 v[116:119], v[198:201], v[214:217], v[116:119]
	v_mfma_f32_16x16x32_bf16 v[112:115], v[206:209], v[214:217], v[112:115]
	v_mfma_f32_16x16x32_bf16 v[100:103], v[198:201], v[222:225], v[100:103]
	v_mfma_f32_16x16x32_bf16 v[96:99], v[206:209], v[222:225], v[96:99]
	v_mfma_f32_16x16x32_bf16 v[84:87], v[198:201], v[230:233], v[84:87]
	v_mfma_f32_16x16x32_bf16 v[80:83], v[206:209], v[230:233], v[80:83]
	v_mfma_f32_16x16x32_bf16 v[68:71], v[198:201], v[238:241], v[68:71]
	v_mfma_f32_16x16x32_bf16 v[64:67], v[206:209], v[238:241], v[64:67]
	v_mfma_f32_16x16x32_bf16 v[116:119], v[202:205], v[218:221], v[116:119]
	v_mfma_f32_16x16x32_bf16 v[112:115], v[210:213], v[218:221], v[112:115]
	v_mfma_f32_16x16x32_bf16 v[100:103], v[202:205], v[226:229], v[100:103]
	v_mfma_f32_16x16x32_bf16 v[96:99], v[210:213], v[226:229], v[96:99]
	v_mfma_f32_16x16x32_bf16 v[84:87], v[202:205], v[234:237], v[84:87]
	v_mfma_f32_16x16x32_bf16 v[80:83], v[210:213], v[234:237], v[80:83]
	v_mfma_f32_16x16x32_bf16 v[68:71], v[202:205], v[242:245], v[68:71]
	v_mfma_f32_16x16x32_bf16 v[64:67], v[210:213], v[242:245], v[64:67]
	s_barrier
	s_add_i32 s18, s34, s47
	s_mov_b32 m0, s18
	ds_read_b128 v[214:217], v157 offset:49152
	ds_read_b128 v[218:221], v157 offset:50176
	ds_read_b128 v[222:225], v157 offset:51200
	ds_read_b128 v[226:229], v157 offset:52224
	ds_read_b128 v[230:233], v157 offset:53248
	ds_read_b128 v[234:237], v157 offset:54272
	ds_read_b128 v[238:241], v157 offset:55296
	ds_read_b128 v[242:245], v157 offset:56320
	global_load_lds_dwordx4 v130, s[60:61]
	s_add_i32 m0, s18, 0x2000
	s_add_u32 s18, s42, 0x40080
	s_addc_u32 s19, s43, 0
	s_add_i32 s21, s35, s47
	global_load_lds_dwordx4 v142, s[60:61]
	s_mov_b32 m0, s21
	s_nop 0
	global_load_lds_dwordx4 v130, s[18:19]
	s_add_i32 m0, s21, 0x2000
	s_nop 0
	global_load_lds_dwordx4 v142, s[18:19]
	s_mov_b32 m0, s52
	s_nop 0
	global_load_lds_dwordx4 v146, s[62:63]
	s_mov_b32 m0, s53
	s_nop 0
	global_load_lds_dwordx4 v144, s[62:63]
	s_waitcnt vmcnt(8)
	s_waitcnt lgkmcnt(0)
	s_barrier
	v_mfma_f32_16x16x32_bf16 v[60:63], v[182:185], v[214:217], v[60:63]
	v_mfma_f32_16x16x32_bf16 v[56:59], v[190:193], v[214:217], v[56:59]
	v_mfma_f32_16x16x32_bf16 v[44:47], v[182:185], v[222:225], v[44:47]
	v_mfma_f32_16x16x32_bf16 v[40:43], v[190:193], v[222:225], v[40:43]
	v_mfma_f32_16x16x32_bf16 v[28:31], v[182:185], v[230:233], v[28:31]
	v_mfma_f32_16x16x32_bf16 v[24:27], v[190:193], v[230:233], v[24:27]
	v_mfma_f32_16x16x32_bf16 v[12:15], v[182:185], v[238:241], v[12:15]
	v_mfma_f32_16x16x32_bf16 v[8:11], v[190:193], v[238:241], v[8:11]
	v_mfma_f32_16x16x32_bf16 v[60:63], v[186:189], v[218:221], v[60:63]
	v_mfma_f32_16x16x32_bf16 v[56:59], v[194:197], v[218:221], v[56:59]
	v_mfma_f32_16x16x32_bf16 v[44:47], v[186:189], v[226:229], v[44:47]
	v_mfma_f32_16x16x32_bf16 v[40:43], v[194:197], v[226:229], v[40:43]
	v_mfma_f32_16x16x32_bf16 v[28:31], v[186:189], v[234:237], v[28:31]
	v_mfma_f32_16x16x32_bf16 v[24:27], v[194:197], v[234:237], v[24:27]
	v_mfma_f32_16x16x32_bf16 v[12:15], v[186:189], v[242:245], v[12:15]
	v_mfma_f32_16x16x32_bf16 v[8:11], v[194:197], v[242:245], v[8:11]
	v_mfma_f32_16x16x32_bf16 v[52:55], v[198:201], v[214:217], v[52:55]
	v_mfma_f32_16x16x32_bf16 v[48:51], v[206:209], v[214:217], v[48:51]
	v_mfma_f32_16x16x32_bf16 v[36:39], v[198:201], v[222:225], v[36:39]
	v_mfma_f32_16x16x32_bf16 v[32:35], v[206:209], v[222:225], v[32:35]
	v_mfma_f32_16x16x32_bf16 v[20:23], v[198:201], v[230:233], v[20:23]
	v_mfma_f32_16x16x32_bf16 v[16:19], v[206:209], v[230:233], v[16:19]
	v_mfma_f32_16x16x32_bf16 v[4:7], v[198:201], v[238:241], v[4:7]
	v_mfma_f32_16x16x32_bf16 v[0:3], v[206:209], v[238:241], v[0:3]
	v_mfma_f32_16x16x32_bf16 v[52:55], v[202:205], v[218:221], v[52:55]
	v_mfma_f32_16x16x32_bf16 v[48:51], v[210:213], v[218:221], v[48:51]
	v_mfma_f32_16x16x32_bf16 v[36:39], v[202:205], v[226:229], v[36:39]
	v_mfma_f32_16x16x32_bf16 v[32:35], v[210:213], v[226:229], v[32:35]
	v_mfma_f32_16x16x32_bf16 v[20:23], v[202:205], v[234:237], v[20:23]
	v_mfma_f32_16x16x32_bf16 v[16:19], v[210:213], v[234:237], v[16:19]
	v_mfma_f32_16x16x32_bf16 v[4:7], v[202:205], v[242:245], v[4:7]
	v_mfma_f32_16x16x32_bf16 v[0:3], v[210:213], v[242:245], v[0:3]
	s_barrier
	s_add_i32 s15, s15, 2
	s_add_u32 s16, s16, 0x100
	s_addc_u32 s17, s17, 0
	s_add_u32 s13, s13, 0x100
	s_addc_u32 s14, s14, 0
	s_cmp_gt_u32 s15, 13
	s_cbranch_scc1 .Lpeel_done_1438
.LBB0_1438:
	v_add_u32_e32 v152, s22, v155
	ds_read_b128 v[182:185], v152
	ds_read_b128 v[186:189], v152 offset:1024
	ds_read_b128 v[190:193], v152 offset:2048
	ds_read_b128 v[194:197], v152 offset:3072
	v_add_u32_e32 v152, s23, v155
	ds_read_b128 v[198:201], v152
	ds_read_b128 v[202:205], v152 offset:1024
	ds_read_b128 v[206:209], v152 offset:2048
	ds_read_b128 v[210:213], v152 offset:3072
	s_add_u32 s18, s16, 0xfffc0080
	s_addc_u32 s19, s17, -1
	s_cmp_eq_u32 s15, 12
	s_cselect_b32 s45, s3, s19
	s_cselect_b32 s44, s11, s18
	s_cselect_b32 s43, s9, s14
	s_cselect_b32 s42, s12, s13
	s_add_i32 m0, s48, 0xc000
	ds_read_b128 v[214:217], v157
	ds_read_b128 v[218:221], v157 offset:1024
	ds_read_b128 v[222:225], v157 offset:2048
	ds_read_b128 v[226:229], v157 offset:3072
	ds_read_b128 v[230:233], v157 offset:4096
	ds_read_b128 v[234:237], v157 offset:5120
	ds_read_b128 v[238:241], v157 offset:6144
	ds_read_b128 v[242:245], v157 offset:7168
	global_load_lds_dwordx4 v148, s[16:17]
	s_add_i32 m0, s48, 0xe000
	s_nop 0
	global_load_lds_dwordx4 v150, s[16:17]
	s_waitcnt vmcnt(8)
	s_waitcnt lgkmcnt(0)
	s_barrier
	v_mfma_f32_16x16x32_bf16 v[124:127], v[182:185], v[214:217], v[124:127]
	v_mfma_f32_16x16x32_bf16 v[120:123], v[190:193], v[214:217], v[120:123]
	v_mfma_f32_16x16x32_bf16 v[108:111], v[182:185], v[222:225], v[108:111]
	v_mfma_f32_16x16x32_bf16 v[104:107], v[190:193], v[222:225], v[104:107]
	v_mfma_f32_16x16x32_bf16 v[92:95], v[182:185], v[230:233], v[92:95]
	v_mfma_f32_16x16x32_bf16 v[88:91], v[190:193], v[230:233], v[88:91]
	v_mfma_f32_16x16x32_bf16 v[76:79], v[182:185], v[238:241], v[76:79]
	v_mfma_f32_16x16x32_bf16 v[72:75], v[190:193], v[238:241], v[72:75]
	v_mfma_f32_16x16x32_bf16 v[124:127], v[186:189], v[218:221], v[124:127]
	v_mfma_f32_16x16x32_bf16 v[120:123], v[194:197], v[218:221], v[120:123]
	v_mfma_f32_16x16x32_bf16 v[108:111], v[186:189], v[226:229], v[108:111]
	v_mfma_f32_16x16x32_bf16 v[104:107], v[194:197], v[226:229], v[104:107]
	v_mfma_f32_16x16x32_bf16 v[92:95], v[186:189], v[234:237], v[92:95]
	v_mfma_f32_16x16x32_bf16 v[88:91], v[194:197], v[234:237], v[88:91]
	v_mfma_f32_16x16x32_bf16 v[76:79], v[186:189], v[242:245], v[76:79]
	v_mfma_f32_16x16x32_bf16 v[72:75], v[194:197], v[242:245], v[72:75]
	v_mfma_f32_16x16x32_bf16 v[116:119], v[198:201], v[214:217], v[116:119]
	v_mfma_f32_16x16x32_bf16 v[112:115], v[206:209], v[214:217], v[112:115]
	v_mfma_f32_16x16x32_bf16 v[100:103], v[198:201], v[222:225], v[100:103]
	v_mfma_f32_16x16x32_bf16 v[96:99], v[206:209], v[222:225], v[96:99]
	v_mfma_f32_16x16x32_bf16 v[84:87], v[198:201], v[230:233], v[84:87]
	v_mfma_f32_16x16x32_bf16 v[80:83], v[206:209], v[230:233], v[80:83]
	v_mfma_f32_16x16x32_bf16 v[68:71], v[198:201], v[238:241], v[68:71]
	v_mfma_f32_16x16x32_bf16 v[64:67], v[206:209], v[238:241], v[64:67]
	v_mfma_f32_16x16x32_bf16 v[116:119], v[202:205], v[218:221], v[116:119]
	v_mfma_f32_16x16x32_bf16 v[112:115], v[210:213], v[218:221], v[112:115]
	v_mfma_f32_16x16x32_bf16 v[100:103], v[202:205], v[226:229], v[100:103]
	v_mfma_f32_16x16x32_bf16 v[96:99], v[210:213], v[226:229], v[96:99]
	v_mfma_f32_16x16x32_bf16 v[84:87], v[202:205], v[234:237], v[84:87]
	v_mfma_f32_16x16x32_bf16 v[80:83], v[210:213], v[234:237], v[80:83]
	v_mfma_f32_16x16x32_bf16 v[68:71], v[202:205], v[242:245], v[68:71]
	v_mfma_f32_16x16x32_bf16 v[64:67], v[210:213], v[242:245], v[64:67]
	s_barrier
	s_add_u32 s60, s42, 0x80
	s_addc_u32 s61, s43, 0
	s_add_u32 s62, s44, 0x80
	s_addc_u32 s63, s45, 0
	s_add_i32 s18, s22, s47
	s_mov_b32 m0, s18
	ds_read_b128 v[214:217], v157 offset:16384
	ds_read_b128 v[218:221], v157 offset:17408
	ds_read_b128 v[222:225], v157 offset:18432
	ds_read_b128 v[226:229], v157 offset:19456
	ds_read_b128 v[230:233], v157 offset:20480
	ds_read_b128 v[234:237], v157 offset:21504
	ds_read_b128 v[238:241], v157 offset:22528
	ds_read_b128 v[242:245], v157 offset:23552
	global_load_lds_dwordx4 v130, s[42:43]
	s_add_i32 m0, s18, 0x2000
	s_add_u32 s18, s42, 0x40000
	s_addc_u32 s19, s43, 0
	s_add_i32 s21, s23, s47
	global_load_lds_dwordx4 v142, s[42:43]
	s_mov_b32 m0, s21
	s_nop 0
	global_load_lds_dwordx4 v130, s[18:19]
	s_add_i32 m0, s21, 0x2000
	s_nop 0
	global_load_lds_dwordx4 v142, s[18:19]
	s_mov_b32 m0, s48
	s_nop 0
	global_load_lds_dwordx4 v146, s[44:45]
	s_mov_b32 m0, s49
	s_nop 0
	global_load_lds_dwordx4 v144, s[44:45]
	s_waitcnt vmcnt(8)
	s_waitcnt lgkmcnt(0)
	s_barrier
	v_mfma_f32_16x16x32_bf16 v[60:63], v[182:185], v[214:217], v[60:63]
	v_mfma_f32_16x16x32_bf16 v[56:59], v[190:193], v[214:217], v[56:59]
	v_mfma_f32_16x16x32_bf16 v[44:47], v[182:185], v[222:225], v[44:47]
	v_mfma_f32_16x16x32_bf16 v[40:43], v[190:193], v[222:225], v[40:43]
	v_mfma_f32_16x16x32_bf16 v[28:31], v[182:185], v[230:233], v[28:31]
	v_mfma_f32_16x16x32_bf16 v[24:27], v[190:193], v[230:233], v[24:27]
	v_mfma_f32_16x16x32_bf16 v[12:15], v[182:185], v[238:241], v[12:15]
	v_mfma_f32_16x16x32_bf16 v[8:11], v[190:193], v[238:241], v[8:11]
	v_mfma_f32_16x16x32_bf16 v[60:63], v[186:189], v[218:221], v[60:63]
	v_mfma_f32_16x16x32_bf16 v[56:59], v[194:197], v[218:221], v[56:59]
	v_mfma_f32_16x16x32_bf16 v[44:47], v[186:189], v[226:229], v[44:47]
	v_mfma_f32_16x16x32_bf16 v[40:43], v[194:197], v[226:229], v[40:43]
	v_mfma_f32_16x16x32_bf16 v[28:31], v[186:189], v[234:237], v[28:31]
	v_mfma_f32_16x16x32_bf16 v[24:27], v[194:197], v[234:237], v[24:27]
	v_mfma_f32_16x16x32_bf16 v[12:15], v[186:189], v[242:245], v[12:15]
	v_mfma_f32_16x16x32_bf16 v[8:11], v[194:197], v[242:245], v[8:11]
	v_mfma_f32_16x16x32_bf16 v[52:55], v[198:201], v[214:217], v[52:55]
	v_mfma_f32_16x16x32_bf16 v[48:51], v[206:209], v[214:217], v[48:51]
	v_mfma_f32_16x16x32_bf16 v[36:39], v[198:201], v[222:225], v[36:39]
	v_mfma_f32_16x16x32_bf16 v[32:35], v[206:209], v[222:225], v[32:35]
	v_mfma_f32_16x16x32_bf16 v[20:23], v[198:201], v[230:233], v[20:23]
	v_mfma_f32_16x16x32_bf16 v[16:19], v[206:209], v[230:233], v[16:19]
	v_mfma_f32_16x16x32_bf16 v[4:7], v[198:201], v[238:241], v[4:7]
	v_mfma_f32_16x16x32_bf16 v[0:3], v[206:209], v[238:241], v[0:3]
	v_mfma_f32_16x16x32_bf16 v[52:55], v[202:205], v[218:221], v[52:55]
	v_mfma_f32_16x16x32_bf16 v[48:51], v[210:213], v[218:221], v[48:51]
	v_mfma_f32_16x16x32_bf16 v[36:39], v[202:205], v[226:229], v[36:39]
	v_mfma_f32_16x16x32_bf16 v[32:35], v[210:213], v[226:229], v[32:35]
	v_mfma_f32_16x16x32_bf16 v[20:23], v[202:205], v[234:237], v[20:23]
	v_mfma_f32_16x16x32_bf16 v[16:19], v[210:213], v[234:237], v[16:19]
	v_mfma_f32_16x16x32_bf16 v[4:7], v[202:205], v[242:245], v[4:7]
	v_mfma_f32_16x16x32_bf16 v[0:3], v[210:213], v[242:245], v[0:3]
	s_barrier
	v_add_u32_e32 v181, s34, v155
	ds_read_b128 v[182:185], v181
	ds_read_b128 v[186:189], v181 offset:1024
	ds_read_b128 v[190:193], v181 offset:2048
	ds_read_b128 v[194:197], v181 offset:3072
	v_add_u32_e32 v181, s35, v155
	ds_read_b128 v[198:201], v181
	ds_read_b128 v[202:205], v181 offset:1024
	ds_read_b128 v[206:209], v181 offset:2048
	ds_read_b128 v[210:213], v181 offset:3072
	s_add_u32 s18, s44, 0x40000
	s_addc_u32 s19, s45, 0
	s_mov_b32 m0, s50
	ds_read_b128 v[214:217], v157 offset:32768
	ds_read_b128 v[218:221], v157 offset:33792
	ds_read_b128 v[222:225], v157 offset:34816
	ds_read_b128 v[226:229], v157 offset:35840
	ds_read_b128 v[230:233], v157 offset:36864
	ds_read_b128 v[234:237], v157 offset:37888
	ds_read_b128 v[238:241], v157 offset:38912
	ds_read_b128 v[242:245], v157 offset:39936
	global_load_lds_dwordx4 v146, s[18:19]
	s_mov_b32 m0, s51
	s_nop 0
	global_load_lds_dwordx4 v144, s[18:19]
	s_waitcnt vmcnt(8)
	s_waitcnt lgkmcnt(0)
	s_barrier
	v_mfma_f32_16x16x32_bf16 v[124:127], v[182:185], v[214:217], v[124:127]
	v_mfma_f32_16x16x32_bf16 v[120:123], v[190:193], v[214:217], v[120:123]
	v_mfma_f32_16x16x32_bf16 v[108:111], v[182:185], v[222:225], v[108:111]
	v_mfma_f32_16x16x32_bf16 v[104:107], v[190:193], v[222:225], v[104:107]
	v_mfma_f32_16x16x32_bf16 v[92:95], v[182:185], v[230:233], v[92:95]
	v_mfma_f32_16x16x32_bf16 v[88:91], v[190:193], v[230:233], v[88:91]
	v_mfma_f32_16x16x32_bf16 v[76:79], v[182:185], v[238:241], v[76:79]
	v_mfma_f32_16x16x32_bf16 v[72:75], v[190:193], v[238:241], v[72:75]
	v_mfma_f32_16x16x32_bf16 v[124:127], v[186:189], v[218:221], v[124:127]
	v_mfma_f32_16x16x32_bf16 v[120:123], v[194:197], v[218:221], v[120:123]
	v_mfma_f32_16x16x32_bf16 v[108:111], v[186:189], v[226:229], v[108:111]
	v_mfma_f32_16x16x32_bf16 v[104:107], v[194:197], v[226:229], v[104:107]
	v_mfma_f32_16x16x32_bf16 v[92:95], v[186:189], v[234:237], v[92:95]
	v_mfma_f32_16x16x32_bf16 v[88:91], v[194:197], v[234:237], v[88:91]
	v_mfma_f32_16x16x32_bf16 v[76:79], v[186:189], v[242:245], v[76:79]
	v_mfma_f32_16x16x32_bf16 v[72:75], v[194:197], v[242:245], v[72:75]
	v_mfma_f32_16x16x32_bf16 v[116:119], v[198:201], v[214:217], v[116:119]
	v_mfma_f32_16x16x32_bf16 v[112:115], v[206:209], v[214:217], v[112:115]
	v_mfma_f32_16x16x32_bf16 v[100:103], v[198:201], v[222:225], v[100:103]
	v_mfma_f32_16x16x32_bf16 v[96:99], v[206:209], v[222:225], v[96:99]
	v_mfma_f32_16x16x32_bf16 v[84:87], v[198:201], v[230:233], v[84:87]
	v_mfma_f32_16x16x32_bf16 v[80:83], v[206:209], v[230:233], v[80:83]
	v_mfma_f32_16x16x32_bf16 v[68:71], v[198:201], v[238:241], v[68:71]
	v_mfma_f32_16x16x32_bf16 v[64:67], v[206:209], v[238:241], v[64:67]
	v_mfma_f32_16x16x32_bf16 v[116:119], v[202:205], v[218:221], v[116:119]
	v_mfma_f32_16x16x32_bf16 v[112:115], v[210:213], v[218:221], v[112:115]
	v_mfma_f32_16x16x32_bf16 v[100:103], v[202:205], v[226:229], v[100:103]
	v_mfma_f32_16x16x32_bf16 v[96:99], v[210:213], v[226:229], v[96:99]
	v_mfma_f32_16x16x32_bf16 v[84:87], v[202:205], v[234:237], v[84:87]
	v_mfma_f32_16x16x32_bf16 v[80:83], v[210:213], v[234:237], v[80:83]
	v_mfma_f32_16x16x32_bf16 v[68:71], v[202:205], v[242:245], v[68:71]
	v_mfma_f32_16x16x32_bf16 v[64:67], v[210:213], v[242:245], v[64:67]
	s_barrier
	s_add_i32 s18, s34, s47
	s_mov_b32 m0, s18
	ds_read_b128 v[214:217], v157 offset:49152
	ds_read_b128 v[218:221], v157 offset:50176
	ds_read_b128 v[222:225], v157 offset:51200
	ds_read_b128 v[226:229], v157 offset:52224
	ds_read_b128 v[230:233], v157 offset:53248
	ds_read_b128 v[234:237], v157 offset:54272
	ds_read_b128 v[238:241], v157 offset:55296
	ds_read_b128 v[242:245], v157 offset:56320
	global_load_lds_dwordx4 v130, s[60:61]
	s_add_i32 m0, s18, 0x2000
	s_add_u32 s18, s42, 0x40080
	s_addc_u32 s19, s43, 0
	s_add_i32 s21, s35, s47
	global_load_lds_dwordx4 v142, s[60:61]
	s_mov_b32 m0, s21
	s_nop 0
	global_load_lds_dwordx4 v130, s[18:19]
	s_add_i32 m0, s21, 0x2000
	s_nop 0
	global_load_lds_dwordx4 v142, s[18:19]
	s_mov_b32 m0, s52
	s_nop 0
	global_load_lds_dwordx4 v146, s[62:63]
	s_mov_b32 m0, s53
	s_nop 0
	global_load_lds_dwordx4 v144, s[62:63]
	s_waitcnt vmcnt(8)
	s_waitcnt lgkmcnt(0)
	s_barrier
	v_mfma_f32_16x16x32_bf16 v[60:63], v[182:185], v[214:217], v[60:63]
	v_mfma_f32_16x16x32_bf16 v[56:59], v[190:193], v[214:217], v[56:59]
	v_mfma_f32_16x16x32_bf16 v[44:47], v[182:185], v[222:225], v[44:47]
	v_mfma_f32_16x16x32_bf16 v[40:43], v[190:193], v[222:225], v[40:43]
	v_mfma_f32_16x16x32_bf16 v[28:31], v[182:185], v[230:233], v[28:31]
	v_mfma_f32_16x16x32_bf16 v[24:27], v[190:193], v[230:233], v[24:27]
	v_mfma_f32_16x16x32_bf16 v[12:15], v[182:185], v[238:241], v[12:15]
	v_mfma_f32_16x16x32_bf16 v[8:11], v[190:193], v[238:241], v[8:11]
	v_mfma_f32_16x16x32_bf16 v[60:63], v[186:189], v[218:221], v[60:63]
	v_mfma_f32_16x16x32_bf16 v[56:59], v[194:197], v[218:221], v[56:59]
	v_mfma_f32_16x16x32_bf16 v[44:47], v[186:189], v[226:229], v[44:47]
	v_mfma_f32_16x16x32_bf16 v[40:43], v[194:197], v[226:229], v[40:43]
	v_mfma_f32_16x16x32_bf16 v[28:31], v[186:189], v[234:237], v[28:31]
	v_mfma_f32_16x16x32_bf16 v[24:27], v[194:197], v[234:237], v[24:27]
	v_mfma_f32_16x16x32_bf16 v[12:15], v[186:189], v[242:245], v[12:15]
	v_mfma_f32_16x16x32_bf16 v[8:11], v[194:197], v[242:245], v[8:11]
	v_mfma_f32_16x16x32_bf16 v[52:55], v[198:201], v[214:217], v[52:55]
	v_mfma_f32_16x16x32_bf16 v[48:51], v[206:209], v[214:217], v[48:51]
	v_mfma_f32_16x16x32_bf16 v[36:39], v[198:201], v[222:225], v[36:39]
	v_mfma_f32_16x16x32_bf16 v[32:35], v[206:209], v[222:225], v[32:35]
	v_mfma_f32_16x16x32_bf16 v[20:23], v[198:201], v[230:233], v[20:23]
	v_mfma_f32_16x16x32_bf16 v[16:19], v[206:209], v[230:233], v[16:19]
	v_mfma_f32_16x16x32_bf16 v[4:7], v[198:201], v[238:241], v[4:7]
	v_mfma_f32_16x16x32_bf16 v[0:3], v[206:209], v[238:241], v[0:3]
	v_mfma_f32_16x16x32_bf16 v[52:55], v[202:205], v[218:221], v[52:55]
	v_mfma_f32_16x16x32_bf16 v[48:51], v[210:213], v[218:221], v[48:51]
	v_mfma_f32_16x16x32_bf16 v[36:39], v[202:205], v[226:229], v[36:39]
	v_mfma_f32_16x16x32_bf16 v[32:35], v[210:213], v[226:229], v[32:35]
	v_mfma_f32_16x16x32_bf16 v[20:23], v[202:205], v[234:237], v[20:23]
	v_mfma_f32_16x16x32_bf16 v[16:19], v[210:213], v[234:237], v[16:19]
	v_mfma_f32_16x16x32_bf16 v[4:7], v[202:205], v[242:245], v[4:7]
	v_mfma_f32_16x16x32_bf16 v[0:3], v[210:213], v[242:245], v[0:3]
	s_barrier
	s_add_i32 s15, s15, 2
	s_add_u32 s16, s16, 0x100
	s_addc_u32 s17, s17, 0
	s_add_u32 s13, s13, 0x100
	s_addc_u32 s14, s14, 0
	s_cmp_gt_u32 s15, 13
	s_cbranch_scc0 .LBB0_1438

.LBB0_1510:
	s_add_i32 s11, s49, -2
	s_add_u32 s50, s40, 0x100
	s_addc_u32 s51, s41, 0
	s_mov_b32 s42, 0
	v_add_u32_e32 v156, s22, v153
	ds_read_b128 v[182:185], v156
	ds_read_b128 v[186:189], v156 offset:1024
	ds_read_b128 v[190:193], v156 offset:2048
	ds_read_b128 v[194:197], v156 offset:3072
	v_add_u32_e32 v156, s23, v153
	ds_read_b128 v[198:201], v156
	ds_read_b128 v[202:205], v156 offset:1024
	ds_read_b128 v[206:209], v156 offset:2048
	ds_read_b128 v[210:213], v156 offset:3072
	s_add_i32 s52, s42, 2
	s_add_u32 s40, s36, 0x100
	s_addc_u32 s41, s37, 0
	s_cmp_eq_u32 s11, s42
	s_cselect_b32 s42, s28, s50
	s_cselect_b32 s45, s17, s41
	s_cselect_b32 s44, s16, s40
	s_cselect_b32 s43, s29, s51
	s_add_i32 m0, s13, 0xc000
	ds_read_b128 v[214:217], v155
	ds_read_b128 v[218:221], v155 offset:1024
	ds_read_b128 v[222:225], v155 offset:2048
	ds_read_b128 v[226:229], v155 offset:3072
	ds_read_b128 v[230:233], v155 offset:4096
	ds_read_b128 v[234:237], v155 offset:5120
	ds_read_b128 v[238:241], v155 offset:6144
	ds_read_b128 v[242:245], v155 offset:7168
	global_load_lds_dwordx4 v148, s[36:37]
	s_add_i32 m0, s13, 0xe000
	s_nop 0
	global_load_lds_dwordx4 v150, s[36:37]
	s_waitcnt vmcnt(8)
	s_waitcnt lgkmcnt(0)
	s_barrier
	v_mfma_f32_16x16x32_bf16 v[124:127], v[182:185], v[214:217], 0
	v_mfma_f32_16x16x32_bf16 v[120:123], v[190:193], v[214:217], 0
	v_mfma_f32_16x16x32_bf16 v[116:119], v[182:185], v[222:225], 0
	v_mfma_f32_16x16x32_bf16 v[112:115], v[190:193], v[222:225], 0
	v_mfma_f32_16x16x32_bf16 v[100:103], v[182:185], v[230:233], 0
	v_mfma_f32_16x16x32_bf16 v[96:99], v[190:193], v[230:233], 0
	v_mfma_f32_16x16x32_bf16 v[84:87], v[182:185], v[238:241], 0
	v_mfma_f32_16x16x32_bf16 v[80:83], v[190:193], v[238:241], 0
	v_mfma_f32_16x16x32_bf16 v[124:127], v[186:189], v[218:221], v[124:127]
	v_mfma_f32_16x16x32_bf16 v[120:123], v[194:197], v[218:221], v[120:123]
	v_mfma_f32_16x16x32_bf16 v[116:119], v[186:189], v[226:229], v[116:119]
	v_mfma_f32_16x16x32_bf16 v[112:115], v[194:197], v[226:229], v[112:115]
	v_mfma_f32_16x16x32_bf16 v[100:103], v[186:189], v[234:237], v[100:103]
	v_mfma_f32_16x16x32_bf16 v[96:99], v[194:197], v[234:237], v[96:99]
	v_mfma_f32_16x16x32_bf16 v[84:87], v[186:189], v[242:245], v[84:87]
	v_mfma_f32_16x16x32_bf16 v[80:83], v[194:197], v[242:245], v[80:83]
	v_mfma_f32_16x16x32_bf16 v[108:111], v[198:201], v[214:217], 0
	v_mfma_f32_16x16x32_bf16 v[104:107], v[206:209], v[214:217], 0
	v_mfma_f32_16x16x32_bf16 v[92:95], v[198:201], v[222:225], 0
	v_mfma_f32_16x16x32_bf16 v[88:91], v[206:209], v[222:225], 0
	v_mfma_f32_16x16x32_bf16 v[76:79], v[198:201], v[230:233], 0
	v_mfma_f32_16x16x32_bf16 v[72:75], v[206:209], v[230:233], 0
	v_mfma_f32_16x16x32_bf16 v[68:71], v[198:201], v[238:241], 0
	v_mfma_f32_16x16x32_bf16 v[64:67], v[206:209], v[238:241], 0
	v_mfma_f32_16x16x32_bf16 v[108:111], v[202:205], v[218:221], v[108:111]
	v_mfma_f32_16x16x32_bf16 v[104:107], v[210:213], v[218:221], v[104:107]
	v_mfma_f32_16x16x32_bf16 v[92:95], v[202:205], v[226:229], v[92:95]
	v_mfma_f32_16x16x32_bf16 v[88:91], v[210:213], v[226:229], v[88:91]
	v_mfma_f32_16x16x32_bf16 v[76:79], v[202:205], v[234:237], v[76:79]
	v_mfma_f32_16x16x32_bf16 v[72:75], v[210:213], v[234:237], v[72:75]
	v_mfma_f32_16x16x32_bf16 v[68:71], v[202:205], v[242:245], v[68:71]
	v_mfma_f32_16x16x32_bf16 v[64:67], v[210:213], v[242:245], v[64:67]
	s_barrier
	s_add_u32 s60, s42, 0x80
	s_addc_u32 s61, s43, 0
	s_add_u32 s62, s44, 0x80
	s_addc_u32 s63, s45, 0
	s_add_i32 s21, s22, s12
	s_mov_b32 m0, s21
	ds_read_b128 v[214:217], v155 offset:16384
	ds_read_b128 v[218:221], v155 offset:17408
	ds_read_b128 v[222:225], v155 offset:18432
	ds_read_b128 v[226:229], v155 offset:19456
	ds_read_b128 v[230:233], v155 offset:20480
	ds_read_b128 v[234:237], v155 offset:21504
	ds_read_b128 v[238:241], v155 offset:22528
	ds_read_b128 v[242:245], v155 offset:23552
	global_load_lds_dwordx4 v130, s[42:43]
	s_add_i32 m0, s21, 0x2000
	s_add_u32 s24, s42, 0xb0000
	s_addc_u32 s25, s43, 0
	s_add_i32 s21, s23, s12
	global_load_lds_dwordx4 v146, s[42:43]
	s_mov_b32 m0, s21
	s_nop 0
	global_load_lds_dwordx4 v130, s[24:25]
	s_add_i32 m0, s21, 0x2000
	s_nop 0
	global_load_lds_dwordx4 v146, s[24:25]
	s_mov_b32 m0, s13
	s_nop 0
	global_load_lds_dwordx4 v142, s[44:45]
	s_mov_b32 m0, s19
	s_nop 0
	global_load_lds_dwordx4 v144, s[44:45]
	s_waitcnt vmcnt(8)
	s_waitcnt lgkmcnt(0)
	s_barrier
	v_mfma_f32_16x16x32_bf16 v[60:63], v[182:185], v[214:217], 0
	v_mfma_f32_16x16x32_bf16 v[56:59], v[190:193], v[214:217], 0
	v_mfma_f32_16x16x32_bf16 v[52:55], v[182:185], v[222:225], 0
	v_mfma_f32_16x16x32_bf16 v[48:51], v[190:193], v[222:225], 0
	v_mfma_f32_16x16x32_bf16 v[36:39], v[182:185], v[230:233], 0
	v_mfma_f32_16x16x32_bf16 v[32:35], v[190:193], v[230:233], 0
	v_mfma_f32_16x16x32_bf16 v[20:23], v[182:185], v[238:241], 0
	v_mfma_f32_16x16x32_bf16 v[16:19], v[190:193], v[238:241], 0
	v_mfma_f32_16x16x32_bf16 v[60:63], v[186:189], v[218:221], v[60:63]
	v_mfma_f32_16x16x32_bf16 v[56:59], v[194:197], v[218:221], v[56:59]
	v_mfma_f32_16x16x32_bf16 v[52:55], v[186:189], v[226:229], v[52:55]
	v_mfma_f32_16x16x32_bf16 v[48:51], v[194:197], v[226:229], v[48:51]
	v_mfma_f32_16x16x32_bf16 v[36:39], v[186:189], v[234:237], v[36:39]
	v_mfma_f32_16x16x32_bf16 v[32:35], v[194:197], v[234:237], v[32:35]
	v_mfma_f32_16x16x32_bf16 v[20:23], v[186:189], v[242:245], v[20:23]
	v_mfma_f32_16x16x32_bf16 v[16:19], v[194:197], v[242:245], v[16:19]
	v_mfma_f32_16x16x32_bf16 v[44:47], v[198:201], v[214:217], 0
	v_mfma_f32_16x16x32_bf16 v[40:43], v[206:209], v[214:217], 0
	v_mfma_f32_16x16x32_bf16 v[28:31], v[198:201], v[222:225], 0
	v_mfma_f32_16x16x32_bf16 v[24:27], v[206:209], v[222:225], 0
	v_mfma_f32_16x16x32_bf16 v[12:15], v[198:201], v[230:233], 0
	v_mfma_f32_16x16x32_bf16 v[8:11], v[206:209], v[230:233], 0
	v_mfma_f32_16x16x32_bf16 v[4:7], v[198:201], v[238:241], 0
	v_mfma_f32_16x16x32_bf16 v[0:3], v[206:209], v[238:241], 0
	v_mfma_f32_16x16x32_bf16 v[44:47], v[202:205], v[218:221], v[44:47]
	v_mfma_f32_16x16x32_bf16 v[40:43], v[210:213], v[218:221], v[40:43]
	v_mfma_f32_16x16x32_bf16 v[28:31], v[202:205], v[226:229], v[28:31]
	v_mfma_f32_16x16x32_bf16 v[24:27], v[210:213], v[226:229], v[24:27]
	v_mfma_f32_16x16x32_bf16 v[12:15], v[202:205], v[234:237], v[12:15]
	v_mfma_f32_16x16x32_bf16 v[8:11], v[210:213], v[234:237], v[8:11]
	v_mfma_f32_16x16x32_bf16 v[4:7], v[202:205], v[242:245], v[4:7]
	v_mfma_f32_16x16x32_bf16 v[0:3], v[210:213], v[242:245], v[0:3]
	s_barrier
	v_add_u32_e32 v181, s34, v153
	ds_read_b128 v[182:185], v181
	ds_read_b128 v[186:189], v181 offset:1024
	ds_read_b128 v[190:193], v181 offset:2048
	ds_read_b128 v[194:197], v181 offset:3072
	v_add_u32_e32 v181, s35, v153
	ds_read_b128 v[198:201], v181
	ds_read_b128 v[202:205], v181 offset:1024
	ds_read_b128 v[206:209], v181 offset:2048
	ds_read_b128 v[210:213], v181 offset:3072
	s_add_u32 s24, s44, 0xb0000
	s_addc_u32 s25, s45, 0
	s_mov_b32 m0, s20
	ds_read_b128 v[214:217], v155 offset:32768
	ds_read_b128 v[218:221], v155 offset:33792
	ds_read_b128 v[222:225], v155 offset:34816
	ds_read_b128 v[226:229], v155 offset:35840
	ds_read_b128 v[230:233], v155 offset:36864
	ds_read_b128 v[234:237], v155 offset:37888
	ds_read_b128 v[238:241], v155 offset:38912
	ds_read_b128 v[242:245], v155 offset:39936
	global_load_lds_dwordx4 v142, s[24:25]
	s_mov_b32 m0, s26
	s_nop 0
	global_load_lds_dwordx4 v144, s[24:25]
	s_waitcnt vmcnt(8)
	s_waitcnt lgkmcnt(0)
	s_barrier
	v_mfma_f32_16x16x32_bf16 v[124:127], v[182:185], v[214:217], v[124:127]
	v_mfma_f32_16x16x32_bf16 v[120:123], v[190:193], v[214:217], v[120:123]
	v_mfma_f32_16x16x32_bf16 v[116:119], v[182:185], v[222:225], v[116:119]
	v_mfma_f32_16x16x32_bf16 v[112:115], v[190:193], v[222:225], v[112:115]
	v_mfma_f32_16x16x32_bf16 v[100:103], v[182:185], v[230:233], v[100:103]
	v_mfma_f32_16x16x32_bf16 v[96:99], v[190:193], v[230:233], v[96:99]
	v_mfma_f32_16x16x32_bf16 v[84:87], v[182:185], v[238:241], v[84:87]
	v_mfma_f32_16x16x32_bf16 v[80:83], v[190:193], v[238:241], v[80:83]
	v_mfma_f32_16x16x32_bf16 v[124:127], v[186:189], v[218:221], v[124:127]
	v_mfma_f32_16x16x32_bf16 v[120:123], v[194:197], v[218:221], v[120:123]
	v_mfma_f32_16x16x32_bf16 v[116:119], v[186:189], v[226:229], v[116:119]
	v_mfma_f32_16x16x32_bf16 v[112:115], v[194:197], v[226:229], v[112:115]
	v_mfma_f32_16x16x32_bf16 v[100:103], v[186:189], v[234:237], v[100:103]
	v_mfma_f32_16x16x32_bf16 v[96:99], v[194:197], v[234:237], v[96:99]
	v_mfma_f32_16x16x32_bf16 v[84:87], v[186:189], v[242:245], v[84:87]
	v_mfma_f32_16x16x32_bf16 v[80:83], v[194:197], v[242:245], v[80:83]
	v_mfma_f32_16x16x32_bf16 v[108:111], v[198:201], v[214:217], v[108:111]
	v_mfma_f32_16x16x32_bf16 v[104:107], v[206:209], v[214:217], v[104:107]
	v_mfma_f32_16x16x32_bf16 v[92:95], v[198:201], v[222:225], v[92:95]
	v_mfma_f32_16x16x32_bf16 v[88:91], v[206:209], v[222:225], v[88:91]
	v_mfma_f32_16x16x32_bf16 v[76:79], v[198:201], v[230:233], v[76:79]
	v_mfma_f32_16x16x32_bf16 v[72:75], v[206:209], v[230:233], v[72:75]
	v_mfma_f32_16x16x32_bf16 v[68:71], v[198:201], v[238:241], v[68:71]
	v_mfma_f32_16x16x32_bf16 v[64:67], v[206:209], v[238:241], v[64:67]
	v_mfma_f32_16x16x32_bf16 v[108:111], v[202:205], v[218:221], v[108:111]
	v_mfma_f32_16x16x32_bf16 v[104:107], v[210:213], v[218:221], v[104:107]
	v_mfma_f32_16x16x32_bf16 v[92:95], v[202:205], v[226:229], v[92:95]
	v_mfma_f32_16x16x32_bf16 v[88:91], v[210:213], v[226:229], v[88:91]
	v_mfma_f32_16x16x32_bf16 v[76:79], v[202:205], v[234:237], v[76:79]
	v_mfma_f32_16x16x32_bf16 v[72:75], v[210:213], v[234:237], v[72:75]
	v_mfma_f32_16x16x32_bf16 v[68:71], v[202:205], v[242:245], v[68:71]
	v_mfma_f32_16x16x32_bf16 v[64:67], v[210:213], v[242:245], v[64:67]
	s_barrier
	s_add_i32 s21, s34, s12
	s_mov_b32 m0, s21
	ds_read_b128 v[214:217], v155 offset:49152
	ds_read_b128 v[218:221], v155 offset:50176
	ds_read_b128 v[222:225], v155 offset:51200
	ds_read_b128 v[226:229], v155 offset:52224
	ds_read_b128 v[230:233], v155 offset:53248
	ds_read_b128 v[234:237], v155 offset:54272
	ds_read_b128 v[238:241], v155 offset:55296
	ds_read_b128 v[242:245], v155 offset:56320
	global_load_lds_dwordx4 v130, s[60:61]
	s_add_i32 m0, s21, 0x2000
	s_add_u32 s24, s42, 0xb0080
	s_addc_u32 s25, s43, 0
	s_add_i32 s21, s35, s12
	global_load_lds_dwordx4 v146, s[60:61]
	s_mov_b32 m0, s21
	s_nop 0
	global_load_lds_dwordx4 v130, s[24:25]
	s_add_i32 m0, s21, 0x2000
	s_nop 0
	global_load_lds_dwordx4 v146, s[24:25]
	s_mov_b32 m0, s33
	s_nop 0
	global_load_lds_dwordx4 v142, s[62:63]
	s_mov_b32 m0, s38
	s_nop 0
	global_load_lds_dwordx4 v144, s[62:63]
	s_waitcnt vmcnt(8)
	s_waitcnt lgkmcnt(0)
	s_barrier
	v_mfma_f32_16x16x32_bf16 v[60:63], v[182:185], v[214:217], v[60:63]
	v_mfma_f32_16x16x32_bf16 v[56:59], v[190:193], v[214:217], v[56:59]
	v_mfma_f32_16x16x32_bf16 v[52:55], v[182:185], v[222:225], v[52:55]
	v_mfma_f32_16x16x32_bf16 v[48:51], v[190:193], v[222:225], v[48:51]
	v_mfma_f32_16x16x32_bf16 v[36:39], v[182:185], v[230:233], v[36:39]
	v_mfma_f32_16x16x32_bf16 v[32:35], v[190:193], v[230:233], v[32:35]
	v_mfma_f32_16x16x32_bf16 v[20:23], v[182:185], v[238:241], v[20:23]
	v_mfma_f32_16x16x32_bf16 v[16:19], v[190:193], v[238:241], v[16:19]
	v_mfma_f32_16x16x32_bf16 v[60:63], v[186:189], v[218:221], v[60:63]
	v_mfma_f32_16x16x32_bf16 v[56:59], v[194:197], v[218:221], v[56:59]
	v_mfma_f32_16x16x32_bf16 v[52:55], v[186:189], v[226:229], v[52:55]
	v_mfma_f32_16x16x32_bf16 v[48:51], v[194:197], v[226:229], v[48:51]
	v_mfma_f32_16x16x32_bf16 v[36:39], v[186:189], v[234:237], v[36:39]
	v_mfma_f32_16x16x32_bf16 v[32:35], v[194:197], v[234:237], v[32:35]
	v_mfma_f32_16x16x32_bf16 v[20:23], v[186:189], v[242:245], v[20:23]
	v_mfma_f32_16x16x32_bf16 v[16:19], v[194:197], v[242:245], v[16:19]
	v_mfma_f32_16x16x32_bf16 v[44:47], v[198:201], v[214:217], v[44:47]
	v_mfma_f32_16x16x32_bf16 v[40:43], v[206:209], v[214:217], v[40:43]
	v_mfma_f32_16x16x32_bf16 v[28:31], v[198:201], v[222:225], v[28:31]
	v_mfma_f32_16x16x32_bf16 v[24:27], v[206:209], v[222:225], v[24:27]
	v_mfma_f32_16x16x32_bf16 v[12:15], v[198:201], v[230:233], v[12:15]
	v_mfma_f32_16x16x32_bf16 v[8:11], v[206:209], v[230:233], v[8:11]
	v_mfma_f32_16x16x32_bf16 v[4:7], v[198:201], v[238:241], v[4:7]
	v_mfma_f32_16x16x32_bf16 v[0:3], v[206:209], v[238:241], v[0:3]
	v_mfma_f32_16x16x32_bf16 v[44:47], v[202:205], v[218:221], v[44:47]
	v_mfma_f32_16x16x32_bf16 v[40:43], v[210:213], v[218:221], v[40:43]
	v_mfma_f32_16x16x32_bf16 v[28:31], v[202:205], v[226:229], v[28:31]
	v_mfma_f32_16x16x32_bf16 v[24:27], v[210:213], v[226:229], v[24:27]
	v_mfma_f32_16x16x32_bf16 v[12:15], v[202:205], v[234:237], v[12:15]
	v_mfma_f32_16x16x32_bf16 v[8:11], v[210:213], v[234:237], v[8:11]
	v_mfma_f32_16x16x32_bf16 v[4:7], v[202:205], v[242:245], v[4:7]
	v_mfma_f32_16x16x32_bf16 v[0:3], v[210:213], v[242:245], v[0:3]
	s_barrier
	s_add_u32 s50, s50, 0x100
	s_addc_u32 s51, s51, 0
	s_cmp_ge_i32 s52, s49
	s_mov_b64 s[36:37], s[40:41]
	s_mov_b32 s42, s52
	s_cbranch_scc1 .Lpeel_done_1511
.LBB0_1511:
	v_add_u32_e32 v156, s22, v153
	ds_read_b128 v[182:185], v156
	ds_read_b128 v[186:189], v156 offset:1024
	ds_read_b128 v[190:193], v156 offset:2048
	ds_read_b128 v[194:197], v156 offset:3072
	v_add_u32_e32 v156, s23, v153
	ds_read_b128 v[198:201], v156
	ds_read_b128 v[202:205], v156 offset:1024
	ds_read_b128 v[206:209], v156 offset:2048
	ds_read_b128 v[210:213], v156 offset:3072
	s_add_i32 s52, s42, 2
	s_add_u32 s40, s36, 0x100
	s_addc_u32 s41, s37, 0
	s_cmp_eq_u32 s11, s42
	s_cselect_b32 s42, s28, s50
	s_cselect_b32 s45, s17, s41
	s_cselect_b32 s44, s16, s40
	s_cselect_b32 s43, s29, s51
	s_add_i32 m0, s13, 0xc000
	ds_read_b128 v[214:217], v155
	ds_read_b128 v[218:221], v155 offset:1024
	ds_read_b128 v[222:225], v155 offset:2048
	ds_read_b128 v[226:229], v155 offset:3072
	ds_read_b128 v[230:233], v155 offset:4096
	ds_read_b128 v[234:237], v155 offset:5120
	ds_read_b128 v[238:241], v155 offset:6144
	ds_read_b128 v[242:245], v155 offset:7168
	global_load_lds_dwordx4 v148, s[36:37]
	s_add_i32 m0, s13, 0xe000
	s_nop 0
	global_load_lds_dwordx4 v150, s[36:37]
	s_waitcnt vmcnt(8)
	s_waitcnt lgkmcnt(0)
	s_barrier
	v_mfma_f32_16x16x32_bf16 v[124:127], v[182:185], v[214:217], v[124:127]
	v_mfma_f32_16x16x32_bf16 v[120:123], v[190:193], v[214:217], v[120:123]
	v_mfma_f32_16x16x32_bf16 v[116:119], v[182:185], v[222:225], v[116:119]
	v_mfma_f32_16x16x32_bf16 v[112:115], v[190:193], v[222:225], v[112:115]
	v_mfma_f32_16x16x32_bf16 v[100:103], v[182:185], v[230:233], v[100:103]
	v_mfma_f32_16x16x32_bf16 v[96:99], v[190:193], v[230:233], v[96:99]
	v_mfma_f32_16x16x32_bf16 v[84:87], v[182:185], v[238:241], v[84:87]
	v_mfma_f32_16x16x32_bf16 v[80:83], v[190:193], v[238:241], v[80:83]
	v_mfma_f32_16x16x32_bf16 v[124:127], v[186:189], v[218:221], v[124:127]
	v_mfma_f32_16x16x32_bf16 v[120:123], v[194:197], v[218:221], v[120:123]
	v_mfma_f32_16x16x32_bf16 v[116:119], v[186:189], v[226:229], v[116:119]
	v_mfma_f32_16x16x32_bf16 v[112:115], v[194:197], v[226:229], v[112:115]
	v_mfma_f32_16x16x32_bf16 v[100:103], v[186:189], v[234:237], v[100:103]
	v_mfma_f32_16x16x32_bf16 v[96:99], v[194:197], v[234:237], v[96:99]
	v_mfma_f32_16x16x32_bf16 v[84:87], v[186:189], v[242:245], v[84:87]
	v_mfma_f32_16x16x32_bf16 v[80:83], v[194:197], v[242:245], v[80:83]
	v_mfma_f32_16x16x32_bf16 v[108:111], v[198:201], v[214:217], v[108:111]
	v_mfma_f32_16x16x32_bf16 v[104:107], v[206:209], v[214:217], v[104:107]
	v_mfma_f32_16x16x32_bf16 v[92:95], v[198:201], v[222:225], v[92:95]
	v_mfma_f32_16x16x32_bf16 v[88:91], v[206:209], v[222:225], v[88:91]
	v_mfma_f32_16x16x32_bf16 v[76:79], v[198:201], v[230:233], v[76:79]
	v_mfma_f32_16x16x32_bf16 v[72:75], v[206:209], v[230:233], v[72:75]
	v_mfma_f32_16x16x32_bf16 v[68:71], v[198:201], v[238:241], v[68:71]
	v_mfma_f32_16x16x32_bf16 v[64:67], v[206:209], v[238:241], v[64:67]
	v_mfma_f32_16x16x32_bf16 v[108:111], v[202:205], v[218:221], v[108:111]
	v_mfma_f32_16x16x32_bf16 v[104:107], v[210:213], v[218:221], v[104:107]
	v_mfma_f32_16x16x32_bf16 v[92:95], v[202:205], v[226:229], v[92:95]
	v_mfma_f32_16x16x32_bf16 v[88:91], v[210:213], v[226:229], v[88:91]
	v_mfma_f32_16x16x32_bf16 v[76:79], v[202:205], v[234:237], v[76:79]
	v_mfma_f32_16x16x32_bf16 v[72:75], v[210:213], v[234:237], v[72:75]
	v_mfma_f32_16x16x32_bf16 v[68:71], v[202:205], v[242:245], v[68:71]
	v_mfma_f32_16x16x32_bf16 v[64:67], v[210:213], v[242:245], v[64:67]
	s_barrier
	s_add_u32 s60, s42, 0x80
	s_addc_u32 s61, s43, 0
	s_add_u32 s62, s44, 0x80
	s_addc_u32 s63, s45, 0
	s_add_i32 s21, s22, s12
	s_mov_b32 m0, s21
	ds_read_b128 v[214:217], v155 offset:16384
	ds_read_b128 v[218:221], v155 offset:17408
	ds_read_b128 v[222:225], v155 offset:18432
	ds_read_b128 v[226:229], v155 offset:19456
	ds_read_b128 v[230:233], v155 offset:20480
	ds_read_b128 v[234:237], v155 offset:21504
	ds_read_b128 v[238:241], v155 offset:22528
	ds_read_b128 v[242:245], v155 offset:23552
	global_load_lds_dwordx4 v130, s[42:43]
	s_add_i32 m0, s21, 0x2000
	s_add_u32 s24, s42, 0xb0000
	s_addc_u32 s25, s43, 0
	s_add_i32 s21, s23, s12
	global_load_lds_dwordx4 v146, s[42:43]
	s_mov_b32 m0, s21
	s_nop 0
	global_load_lds_dwordx4 v130, s[24:25]
	s_add_i32 m0, s21, 0x2000
	s_nop 0
	global_load_lds_dwordx4 v146, s[24:25]
	s_mov_b32 m0, s13
	s_nop 0
	global_load_lds_dwordx4 v142, s[44:45]
	s_mov_b32 m0, s19
	s_nop 0
	global_load_lds_dwordx4 v144, s[44:45]
	s_waitcnt vmcnt(8)
	s_waitcnt lgkmcnt(0)
	s_barrier
	v_mfma_f32_16x16x32_bf16 v[60:63], v[182:185], v[214:217], v[60:63]
	v_mfma_f32_16x16x32_bf16 v[56:59], v[190:193], v[214:217], v[56:59]
	v_mfma_f32_16x16x32_bf16 v[52:55], v[182:185], v[222:225], v[52:55]
	v_mfma_f32_16x16x32_bf16 v[48:51], v[190:193], v[222:225], v[48:51]
	v_mfma_f32_16x16x32_bf16 v[36:39], v[182:185], v[230:233], v[36:39]
	v_mfma_f32_16x16x32_bf16 v[32:35], v[190:193], v[230:233], v[32:35]
	v_mfma_f32_16x16x32_bf16 v[20:23], v[182:185], v[238:241], v[20:23]
	v_mfma_f32_16x16x32_bf16 v[16:19], v[190:193], v[238:241], v[16:19]
	v_mfma_f32_16x16x32_bf16 v[60:63], v[186:189], v[218:221], v[60:63]
	v_mfma_f32_16x16x32_bf16 v[56:59], v[194:197], v[218:221], v[56:59]
	v_mfma_f32_16x16x32_bf16 v[52:55], v[186:189], v[226:229], v[52:55]
	v_mfma_f32_16x16x32_bf16 v[48:51], v[194:197], v[226:229], v[48:51]
	v_mfma_f32_16x16x32_bf16 v[36:39], v[186:189], v[234:237], v[36:39]
	v_mfma_f32_16x16x32_bf16 v[32:35], v[194:197], v[234:237], v[32:35]
	v_mfma_f32_16x16x32_bf16 v[20:23], v[186:189], v[242:245], v[20:23]
	v_mfma_f32_16x16x32_bf16 v[16:19], v[194:197], v[242:245], v[16:19]
	v_mfma_f32_16x16x32_bf16 v[44:47], v[198:201], v[214:217], v[44:47]
	v_mfma_f32_16x16x32_bf16 v[40:43], v[206:209], v[214:217], v[40:43]
	v_mfma_f32_16x16x32_bf16 v[28:31], v[198:201], v[222:225], v[28:31]
	v_mfma_f32_16x16x32_bf16 v[24:27], v[206:209], v[222:225], v[24:27]
	v_mfma_f32_16x16x32_bf16 v[12:15], v[198:201], v[230:233], v[12:15]
	v_mfma_f32_16x16x32_bf16 v[8:11], v[206:209], v[230:233], v[8:11]
	v_mfma_f32_16x16x32_bf16 v[4:7], v[198:201], v[238:241], v[4:7]
	v_mfma_f32_16x16x32_bf16 v[0:3], v[206:209], v[238:241], v[0:3]
	v_mfma_f32_16x16x32_bf16 v[44:47], v[202:205], v[218:221], v[44:47]
	v_mfma_f32_16x16x32_bf16 v[40:43], v[210:213], v[218:221], v[40:43]
	v_mfma_f32_16x16x32_bf16 v[28:31], v[202:205], v[226:229], v[28:31]
	v_mfma_f32_16x16x32_bf16 v[24:27], v[210:213], v[226:229], v[24:27]
	v_mfma_f32_16x16x32_bf16 v[12:15], v[202:205], v[234:237], v[12:15]
	v_mfma_f32_16x16x32_bf16 v[8:11], v[210:213], v[234:237], v[8:11]
	v_mfma_f32_16x16x32_bf16 v[4:7], v[202:205], v[242:245], v[4:7]
	v_mfma_f32_16x16x32_bf16 v[0:3], v[210:213], v[242:245], v[0:3]
	s_barrier
	v_add_u32_e32 v181, s34, v153
	ds_read_b128 v[182:185], v181
	ds_read_b128 v[186:189], v181 offset:1024
	ds_read_b128 v[190:193], v181 offset:2048
	ds_read_b128 v[194:197], v181 offset:3072
	v_add_u32_e32 v181, s35, v153
	ds_read_b128 v[198:201], v181
	ds_read_b128 v[202:205], v181 offset:1024
	ds_read_b128 v[206:209], v181 offset:2048
	ds_read_b128 v[210:213], v181 offset:3072
	s_add_u32 s24, s44, 0xb0000
	s_addc_u32 s25, s45, 0
	s_mov_b32 m0, s20
	ds_read_b128 v[214:217], v155 offset:32768
	ds_read_b128 v[218:221], v155 offset:33792
	ds_read_b128 v[222:225], v155 offset:34816
	ds_read_b128 v[226:229], v155 offset:35840
	ds_read_b128 v[230:233], v155 offset:36864
	ds_read_b128 v[234:237], v155 offset:37888
	ds_read_b128 v[238:241], v155 offset:38912
	ds_read_b128 v[242:245], v155 offset:39936
	global_load_lds_dwordx4 v142, s[24:25]
	s_mov_b32 m0, s26
	s_nop 0
	global_load_lds_dwordx4 v144, s[24:25]
	s_waitcnt vmcnt(8)
	s_waitcnt lgkmcnt(0)
	s_barrier
	v_mfma_f32_16x16x32_bf16 v[124:127], v[182:185], v[214:217], v[124:127]
	v_mfma_f32_16x16x32_bf16 v[120:123], v[190:193], v[214:217], v[120:123]
	v_mfma_f32_16x16x32_bf16 v[116:119], v[182:185], v[222:225], v[116:119]
	v_mfma_f32_16x16x32_bf16 v[112:115], v[190:193], v[222:225], v[112:115]
	v_mfma_f32_16x16x32_bf16 v[100:103], v[182:185], v[230:233], v[100:103]
	v_mfma_f32_16x16x32_bf16 v[96:99], v[190:193], v[230:233], v[96:99]
	v_mfma_f32_16x16x32_bf16 v[84:87], v[182:185], v[238:241], v[84:87]
	v_mfma_f32_16x16x32_bf16 v[80:83], v[190:193], v[238:241], v[80:83]
	v_mfma_f32_16x16x32_bf16 v[124:127], v[186:189], v[218:221], v[124:127]
	v_mfma_f32_16x16x32_bf16 v[120:123], v[194:197], v[218:221], v[120:123]
	v_mfma_f32_16x16x32_bf16 v[116:119], v[186:189], v[226:229], v[116:119]
	v_mfma_f32_16x16x32_bf16 v[112:115], v[194:197], v[226:229], v[112:115]
	v_mfma_f32_16x16x32_bf16 v[100:103], v[186:189], v[234:237], v[100:103]
	v_mfma_f32_16x16x32_bf16 v[96:99], v[194:197], v[234:237], v[96:99]
	v_mfma_f32_16x16x32_bf16 v[84:87], v[186:189], v[242:245], v[84:87]
	v_mfma_f32_16x16x32_bf16 v[80:83], v[194:197], v[242:245], v[80:83]
	v_mfma_f32_16x16x32_bf16 v[108:111], v[198:201], v[214:217], v[108:111]
	v_mfma_f32_16x16x32_bf16 v[104:107], v[206:209], v[214:217], v[104:107]
	v_mfma_f32_16x16x32_bf16 v[92:95], v[198:201], v[222:225], v[92:95]
	v_mfma_f32_16x16x32_bf16 v[88:91], v[206:209], v[222:225], v[88:91]
	v_mfma_f32_16x16x32_bf16 v[76:79], v[198:201], v[230:233], v[76:79]
	v_mfma_f32_16x16x32_bf16 v[72:75], v[206:209], v[230:233], v[72:75]
	v_mfma_f32_16x16x32_bf16 v[68:71], v[198:201], v[238:241], v[68:71]
	v_mfma_f32_16x16x32_bf16 v[64:67], v[206:209], v[238:241], v[64:67]
	v_mfma_f32_16x16x32_bf16 v[108:111], v[202:205], v[218:221], v[108:111]
	v_mfma_f32_16x16x32_bf16 v[104:107], v[210:213], v[218:221], v[104:107]
	v_mfma_f32_16x16x32_bf16 v[92:95], v[202:205], v[226:229], v[92:95]
	v_mfma_f32_16x16x32_bf16 v[88:91], v[210:213], v[226:229], v[88:91]
	v_mfma_f32_16x16x32_bf16 v[76:79], v[202:205], v[234:237], v[76:79]
	v_mfma_f32_16x16x32_bf16 v[72:75], v[210:213], v[234:237], v[72:75]
	v_mfma_f32_16x16x32_bf16 v[68:71], v[202:205], v[242:245], v[68:71]
	v_mfma_f32_16x16x32_bf16 v[64:67], v[210:213], v[242:245], v[64:67]
	s_barrier
	s_add_i32 s21, s34, s12
	s_mov_b32 m0, s21
	ds_read_b128 v[214:217], v155 offset:49152
	ds_read_b128 v[218:221], v155 offset:50176
	ds_read_b128 v[222:225], v155 offset:51200
	ds_read_b128 v[226:229], v155 offset:52224
	ds_read_b128 v[230:233], v155 offset:53248
	ds_read_b128 v[234:237], v155 offset:54272
	ds_read_b128 v[238:241], v155 offset:55296
	ds_read_b128 v[242:245], v155 offset:56320
	global_load_lds_dwordx4 v130, s[60:61]
	s_add_i32 m0, s21, 0x2000
	s_add_u32 s24, s42, 0xb0080
	s_addc_u32 s25, s43, 0
	s_add_i32 s21, s35, s12
	global_load_lds_dwordx4 v146, s[60:61]
	s_mov_b32 m0, s21
	s_nop 0
	global_load_lds_dwordx4 v130, s[24:25]
	s_add_i32 m0, s21, 0x2000
	s_nop 0
	global_load_lds_dwordx4 v146, s[24:25]
	s_mov_b32 m0, s33
	s_nop 0
	global_load_lds_dwordx4 v142, s[62:63]
	s_mov_b32 m0, s38
	s_nop 0
	global_load_lds_dwordx4 v144, s[62:63]
	s_waitcnt vmcnt(8)
	s_waitcnt lgkmcnt(0)
	s_barrier
	v_mfma_f32_16x16x32_bf16 v[60:63], v[182:185], v[214:217], v[60:63]
	v_mfma_f32_16x16x32_bf16 v[56:59], v[190:193], v[214:217], v[56:59]
	v_mfma_f32_16x16x32_bf16 v[52:55], v[182:185], v[222:225], v[52:55]
	v_mfma_f32_16x16x32_bf16 v[48:51], v[190:193], v[222:225], v[48:51]
	v_mfma_f32_16x16x32_bf16 v[36:39], v[182:185], v[230:233], v[36:39]
	v_mfma_f32_16x16x32_bf16 v[32:35], v[190:193], v[230:233], v[32:35]
	v_mfma_f32_16x16x32_bf16 v[20:23], v[182:185], v[238:241], v[20:23]
	v_mfma_f32_16x16x32_bf16 v[16:19], v[190:193], v[238:241], v[16:19]
	v_mfma_f32_16x16x32_bf16 v[60:63], v[186:189], v[218:221], v[60:63]
	v_mfma_f32_16x16x32_bf16 v[56:59], v[194:197], v[218:221], v[56:59]
	v_mfma_f32_16x16x32_bf16 v[52:55], v[186:189], v[226:229], v[52:55]
	v_mfma_f32_16x16x32_bf16 v[48:51], v[194:197], v[226:229], v[48:51]
	v_mfma_f32_16x16x32_bf16 v[36:39], v[186:189], v[234:237], v[36:39]
	v_mfma_f32_16x16x32_bf16 v[32:35], v[194:197], v[234:237], v[32:35]
	v_mfma_f32_16x16x32_bf16 v[20:23], v[186:189], v[242:245], v[20:23]
	v_mfma_f32_16x16x32_bf16 v[16:19], v[194:197], v[242:245], v[16:19]
	v_mfma_f32_16x16x32_bf16 v[44:47], v[198:201], v[214:217], v[44:47]
	v_mfma_f32_16x16x32_bf16 v[40:43], v[206:209], v[214:217], v[40:43]
	v_mfma_f32_16x16x32_bf16 v[28:31], v[198:201], v[222:225], v[28:31]
	v_mfma_f32_16x16x32_bf16 v[24:27], v[206:209], v[222:225], v[24:27]
	v_mfma_f32_16x16x32_bf16 v[12:15], v[198:201], v[230:233], v[12:15]
	v_mfma_f32_16x16x32_bf16 v[8:11], v[206:209], v[230:233], v[8:11]
	v_mfma_f32_16x16x32_bf16 v[4:7], v[198:201], v[238:241], v[4:7]
	v_mfma_f32_16x16x32_bf16 v[0:3], v[206:209], v[238:241], v[0:3]
	v_mfma_f32_16x16x32_bf16 v[44:47], v[202:205], v[218:221], v[44:47]
	v_mfma_f32_16x16x32_bf16 v[40:43], v[210:213], v[218:221], v[40:43]
	v_mfma_f32_16x16x32_bf16 v[28:31], v[202:205], v[226:229], v[28:31]
	v_mfma_f32_16x16x32_bf16 v[24:27], v[210:213], v[226:229], v[24:27]
	v_mfma_f32_16x16x32_bf16 v[12:15], v[202:205], v[234:237], v[12:15]
	v_mfma_f32_16x16x32_bf16 v[8:11], v[210:213], v[234:237], v[8:11]
	v_mfma_f32_16x16x32_bf16 v[4:7], v[202:205], v[242:245], v[4:7]
	v_mfma_f32_16x16x32_bf16 v[0:3], v[210:213], v[242:245], v[0:3]
	s_barrier
	s_add_u32 s50, s50, 0x100
	s_addc_u32 s51, s51, 0
	s_cmp_ge_i32 s52, s49
	s_mov_b64 s[36:37], s[40:41]
	s_mov_b32 s42, s52
	s_cbranch_scc0 .LBB0_1511
